# u4 with more aggressive lgkmcnt wait merging and an LDS read-to-use distance rule in the step scheduler
# speedup vs baseline: 1.0132x; 1.0008x over previous
; DI float row16_sum(float v) { v += dppf(v, 0); v += dppf(v, 1); v += dppf(v, 2); v += dppf(v, 3); return v; }
; DI void mamba_scan(CP p, const Ptrs& w, int l, int item, float* sm) {
;     ...
;   auto load = [&](int c, MPre& P) {
; #pragma unroll
;     for (int i = 0; i < 2; ++i) {
;       int idx = tid + 256 * i, j = idx >> 5, q = idx & 31;
;       int ii = pos2i(c * 16 + j, dir);
;       P.pbq[i] = *(const uint4*)(mbc + ((size_t)b * TPB + ii) * 512 + (q < 16 ? 0 : 256) + gp * 128 + (q & 15) * 8);
;     }
;     {
;       int pos = c * 16 + xj, ii = pos2i(pos, dir);
;       size_t tok = (size_t)b * TPB + ii;
;       const bf16_t* prw = w.pC + tok * SPC;
;       bool hp = (ii != 0) && (ii != CTXL), hn = (ii != CTXL - 1) && (ii != TPB - 1);
;       P.px[0] = prw[chX + (hp ? -SPC : 0)]; P.px[1] = prw[chX]; P.px[2] = prw[chX + (hn ? SPC : 0)];
;       P.pxm[0] = hp ? 1.f : 0.f; P.pxm[1] = hn ? 1.f : 0.f;
;       float2 dd = *(const float2*)(w.mdt + (tok * 16 + dir * 8 + hd) * 2);
;       P.pdt[0] = dd.x; P.pdt[1] = dd.y; P.pdt[2] = w.mcb[tok * 2 + gp];
;     }
;   };
;     ...
;   auto run_chunk = [&](int c, const float* bf, float* sy) {
;     flush(max(c - 1, 0));
;     MStep cur = lds_step(bf, 0);
; #pragma unroll
;     for (int j = 0; j < 16; ++j) {
;       MStep nxt = cur;
;       if (j + 1 < 16) nxt = lds_step(bf, j + 1);
;       f2v ya = M0 * cur.C0.xy + M1 * cur.C0.zw, yb = M2 * cur.C1.xy + M3 * cur.C1.zw;
;       ya += yb;
;       float yp = row16_sum(ya.x + ya.y);
;       float y = cur.sc.x * yp + cur.xq * cur.sc.y + cur.ds;
;       const float dA = cur.sc.x, xq = cur.xq;
;       M0 = M0 * dA + xq * cur.B0.xy; M1 = M1 * dA + xq * cur.B0.zw;
;       M2 = M2 * dA + xq * cur.B1.xy; M3 = M3 * dA + xq * cur.B1.zw;
;       sy[(ng == 0 ? j * 16 : 0) + ysel] = y;
;       cur = nxt;
;     }
.LBB0_544:
	s_min_u32 s4, s52, 1
	s_lshl_b32 s5, s4, 8
	s_lshl_b32 s54, s4, 4
	s_add_i32 s4, s7, 4
	s_min_u32 s4, s4, 0x20f
	s_lshl_b32 s42, s4, 4
	v_add_u32_e32 v8, s42, v55
	s_sub_i32 s53, s57, s5
	v_cmp_lt_i32_e64 s[4:5], s37, v8
	v_mov_b64_e32 v[38:39], s[48:49]
	v_mov_b32_e32 v41, v157
	v_cndmask_b32_e64 v12, v231, v232, s[4:5]
	v_sub_u32_e32 v12, v12, v8
	v_cndmask_b32_e64 v12, v12, v8, s[40:41]
	v_add_u32_e32 v8, s42, v56
	v_cmp_lt_i32_e64 s[4:5], s37, v8
	v_ashrrev_i32_e32 v13, 31, v12
	v_lshl_add_u64 v[12:13], v[12:13], 0, s[90:91]
	v_cndmask_b32_e64 v14, v231, v232, s[4:5]
	v_sub_u32_e32 v14, v14, v8
	v_cndmask_b32_e64 v14, v14, v8, s[40:41]
	v_add_u32_e32 v8, s42, v54
	v_cmp_lt_i32_e64 s[4:5], s37, v8
	v_ashrrev_i32_e32 v15, 31, v14
	v_lshl_add_u64 v[14:15], v[14:15], 0, s[90:91]
	v_cndmask_b32_e64 v16, v231, v232, s[4:5]
	v_sub_u32_e32 v16, v16, v8
	v_cndmask_b32_e64 v16, v16, v8, s[40:41]
	v_and_b32_e32 v8, 0xfffffeff, v16
	v_ashrrev_i32_e32 v17, 31, v16
	v_cmp_eq_u32_e64 s[42:43], 0, v8
	v_lshl_add_u64 v[36:37], v[16:17], 0, s[90:91]
	v_mad_u64_u32 v[38:39], s[4:5], v36, s92, v[38:39]
	v_cndmask_b32_e64 v8, v233, 0, s[42:43]
	v_and_b32_e32 v40, 0xffffdfff, v16
	v_add_u32_e32 v16, v8, v48
	v_lshlrev_b64 v[12:13], 10, v[12:13]
	v_lshlrev_b64 v[14:15], 10, v[14:15]
	v_mad_i32_i24 v39, v37, s92, v39
	v_ashrrev_i32_e32 v17, 31, v16
	v_cmp_eq_u32_e64 s[44:45], s37, v40
	v_lshlrev_b64 v[42:43], 7, v[36:37]
	v_lshl_add_u64 v[12:13], v[30:31], 0, v[12:13]
	v_lshl_add_u64 v[14:15], v[30:31], 0, v[14:15]
	v_lshl_add_u64 v[16:17], v[16:17], 1, v[38:39]
	v_lshl_add_u64 v[38:39], v[38:39], 0, v[156:157]
	v_cndmask_b32_e64 v40, v234, 0, s[44:45]
	v_lshl_or_b32 v42, s6, 3, v42
	global_load_dwordx4 v[18:21], v[12:13], off
	s_nop 0
	global_load_dwordx4 v[12:15], v[14:15], off
	v_lshl_add_u64 v[40:41], v[38:39], 0, v[40:41]
	v_lshl_add_u64 v[42:43], s[46:47], 0, v[42:43]
	v_lshl_add_u64 v[44:45], v[36:37], 3, s[50:51]
	global_load_ushort v84, v[16:17], off
	global_load_ushort v85, v[38:39], off
	global_load_ushort v83, v[40:41], off
	global_load_dwordx2 v[36:37], v[42:43], off
	s_nop 0
	global_load_dword v17, v[44:45], off
	v_subrev_u32_e32 v8, s54, v82
	s_and_b32 s4, s53, 0x100
	v_lshl_add_u32 v16, s4, 2, v57
	v_cmp_lt_i32_e64 s[4:5], s37, v8
	ds_read_b32 v16, v16 offset:37376
	s_nop 0
	v_cndmask_b32_e64 v38, v231, v232, s[4:5]
	v_add3_u32 v38, v38, v81, s54
	v_cndmask_b32_e64 v38, v38, v8, s[40:41]
	v_ashrrev_i32_e32 v39, 31, v38
	v_lshl_add_u64 v[38:39], v[38:39], 0, s[90:91]
	v_lshlrev_b64 v[38:39], 10, v[38:39]
	s_waitcnt lgkmcnt(0)
	v_cvt_pk_bf16_f32 v8, v16, s0
	v_lshl_add_u64 v[38:39], v[34:35], 0, v[38:39]
	global_store_short v[38:39], v8, off
	s_waitcnt lgkmcnt(0)
	ds_read_b128 v[38:41], v59
	ds_read_b128 v[42:45], v59 offset:16
	ds_read_b128 v[88:91], v59 offset:8192
	ds_read_b128 v[92:95], v59 offset:8208
	v_add_u32_e32 v8, 0x4000, v60
	s_movk_i32 s4, 0x4800
	ds_read2_b32 v[46:47], v8 offset1:16
	v_add_u32_e32 v8, 0x4400, v60
	ds_read2_b32 v[116:117], v8 offset1:16
	v_add_u32_e64 v8, s4, 0
	ds_read2_b64 v[96:99], v8 offset1:2
	ds_read_b128 v[100:103], v59 offset:512
	ds_read_b128 v[104:107], v59 offset:528
	ds_read_b128 v[108:111], v59 offset:8704
	ds_read_b128 v[112:115], v59 offset:8720
	s_waitcnt lgkmcnt(7)
	v_pk_mul_f32 v[90:91], v[28:29], v[90:91]
	v_pk_fma_f32 v[88:89], v[26:27], v[88:89], v[90:91]
	v_pk_mul_f32 v[90:91], v[24:25], v[94:95]
	v_pk_fma_f32 v[90:91], v[22:23], v[92:93], v[90:91]
	v_pk_add_f32 v[88:89], v[88:89], v[90:91]
	v_add_f32_e32 v8, v88, v89
	s_waitcnt lgkmcnt(4)
	v_pk_mul_f32 v[22:23], v[22:23], v[96:97] op_sel_hi:[1,0]
	v_pk_mul_f32 v[26:27], v[26:27], v[96:97] op_sel_hi:[1,0]
	v_add_f32_dpp v8, v8, v8 quad_perm:[1,0,3,2] row_mask:0xf bank_mask:0xf bound_ctrl:1
	v_pk_fma_f32 v[92:93], v[42:43], v[46:47], v[22:23] op_sel_hi:[1,0,1]
	v_pk_mul_f32 v[22:23], v[24:25], v[96:97] op_sel_hi:[1,0]
	v_add_f32_dpp v8, v8, v8 quad_perm:[2,3,0,1] row_mask:0xf bank_mask:0xf bound_ctrl:1
	v_pk_fma_f32 v[88:89], v[38:39], v[46:47], v[26:27] op_sel_hi:[1,0,1]
	v_pk_mul_f32 v[26:27], v[28:29], v[96:97] op_sel_hi:[1,0]
	v_add_f32_dpp v8, v8, v8 row_half_mirror row_mask:0xf bank_mask:0xf bound_ctrl:1
	v_pk_fma_f32 v[94:95], v[44:45], v[46:47], v[22:23] op_sel_hi:[1,0,1]
	v_pk_fma_f32 v[90:91], v[40:41], v[46:47], v[26:27] op_sel_hi:[1,0,1]
	v_add_f32_dpp v8, v8, v8 row_mirror row_mask:0xf bank_mask:0xf bound_ctrl:1
	v_mul_f32_e32 v8, v96, v8
	v_fmac_f32_e32 v8, v46, v97
	v_add_f32_e32 v8, v116, v8
	ds_write_b32 v61, v8 offset:37376
	ds_read_b128 v[22:25], v59 offset:1024
	ds_read_b128 v[26:29], v59 offset:1040
	ds_read_b128 v[38:41], v59 offset:9216
	s_waitcnt lgkmcnt(4)
	v_pk_mul_f32 v[96:97], v[90:91], v[110:111]
	ds_read_b128 v[42:45], v59 offset:9232
	v_pk_fma_f32 v[96:97], v[88:89], v[108:109], v[96:97]
	v_pk_mul_f32 v[108:109], v[94:95], v[114:115]
	ds_read_b32 v8, v60 offset:16512
	v_pk_fma_f32 v[108:109], v[92:93], v[112:113], v[108:109]
	ds_read_b32 v116, v60 offset:17536
	v_pk_add_f32 v[96:97], v[96:97], v[108:109]
	ds_read_b64 v[118:119], v157 offset:18464
	v_add_f32_e32 v16, v96, v97
	v_pk_mul_f32 v[88:89], v[88:89], v[98:99] op_sel_hi:[1,0]
	s_nop 0
	v_add_f32_dpp v16, v16, v16 quad_perm:[1,0,3,2] row_mask:0xf bank_mask:0xf bound_ctrl:1
	s_nop 1
	v_add_f32_dpp v16, v16, v16 quad_perm:[2,3,0,1] row_mask:0xf bank_mask:0xf bound_ctrl:1
	s_nop 1
	v_add_f32_dpp v16, v16, v16 row_half_mirror row_mask:0xf bank_mask:0xf bound_ctrl:1
	s_nop 1
	v_add_f32_dpp v16, v16, v16 row_mirror row_mask:0xf bank_mask:0xf bound_ctrl:1
	v_mul_f32_e32 v16, v98, v16
	v_fmac_f32_e32 v16, v47, v99
	v_add_f32_e32 v96, v117, v16
	v_mov_b32_e32 v16, v47
	ds_write_b32 v62, v96 offset:37376
	v_pk_fma_f32 v[46:47], v[100:101], v[16:17], v[88:89] op_sel_hi:[1,0,1]
	v_pk_mul_f32 v[88:89], v[90:91], v[98:99] op_sel_hi:[1,0]
	v_pk_fma_f32 v[108:109], v[102:103], v[16:17], v[88:89] op_sel_hi:[1,0,1]
	v_pk_mul_f32 v[88:89], v[92:93], v[98:99] op_sel_hi:[1,0]
	v_pk_fma_f32 v[104:105], v[104:105], v[16:17], v[88:89] op_sel_hi:[1,0,1]
	v_pk_mul_f32 v[88:89], v[94:95], v[98:99] op_sel_hi:[1,0]
	v_pk_fma_f32 v[106:107], v[106:107], v[16:17], v[88:89] op_sel_hi:[1,0,1]
	ds_read_b128 v[88:91], v59 offset:1536
	ds_read_b128 v[92:95], v59 offset:1552
	ds_read_b128 v[96:99], v59 offset:9728
	ds_read_b128 v[100:103], v59 offset:9744
	ds_read_b32 v16, v60 offset:16576
	ds_read_b32 v114, v60 offset:17600
	s_waitcnt lgkmcnt(6)
; DI float row16_sum(float v) { v += dppf(v, 0); v += dppf(v, 1); v += dppf(v, 2); v += dppf(v, 3); return v; }
; DI void mamba_scan(CP p, const Ptrs& w, int l, int item, float* sm) {
;     ...
; #pragma unroll
;     for (int j = 0; j < 16; ++j) {
;       MStep nxt = cur;
;       if (j + 1 < 16) nxt = lds_step(bf, j + 1);
;       f2v ya = M0 * cur.C0.xy + M1 * cur.C0.zw, yb = M2 * cur.C1.xy + M3 * cur.C1.zw;
;       ya += yb;
;       float yp = row16_sum(ya.x + ya.y);
;       float y = cur.sc.x * yp + cur.xq * cur.sc.y + cur.ds;
;       const float dA = cur.sc.x, xq = cur.xq;
;       M0 = M0 * dA + xq * cur.B0.xy; M1 = M1 * dA + xq * cur.B0.zw;
;       M2 = M2 * dA + xq * cur.B1.xy; M3 = M3 * dA + xq * cur.B1.zw;
;       sy[(ng == 0 ? j * 16 : 0) + ysel] = y;
;       cur = nxt;
;     }
	v_pk_mul_f32 v[40:41], v[108:109], v[40:41]
	ds_read_b64 v[110:111], v157 offset:18480
	v_pk_fma_f32 v[38:39], v[46:47], v[38:39], v[40:41]
	v_pk_mul_f32 v[40:41], v[106:107], v[44:45]
	v_pk_fma_f32 v[40:41], v[104:105], v[42:43], v[40:41]
	v_pk_add_f32 v[38:39], v[38:39], v[40:41]
	v_add_f32_e32 v38, v38, v39
	s_nop 1
	v_add_f32_dpp v38, v38, v38 quad_perm:[1,0,3,2] row_mask:0xf bank_mask:0xf bound_ctrl:1
	s_nop 1
	v_add_f32_dpp v38, v38, v38 quad_perm:[2,3,0,1] row_mask:0xf bank_mask:0xf bound_ctrl:1
	s_nop 1
	v_add_f32_dpp v38, v38, v38 row_half_mirror row_mask:0xf bank_mask:0xf bound_ctrl:1
	s_nop 1
	v_add_f32_dpp v38, v38, v38 row_mirror row_mask:0xf bank_mask:0xf bound_ctrl:1
	v_mul_f32_e32 v38, v118, v38
	v_fmac_f32_e32 v38, v8, v119
	v_add_f32_e32 v40, v116, v38
	v_pk_mul_f32 v[38:39], v[46:47], v[118:119] op_sel_hi:[1,0]
	ds_write_b32 v63, v40 offset:37376
	v_pk_fma_f32 v[46:47], v[22:23], v[8:9], v[38:39] op_sel_hi:[1,0,1]
	v_pk_mul_f32 v[22:23], v[108:109], v[118:119] op_sel_hi:[1,0]
	v_pk_fma_f32 v[108:109], v[24:25], v[8:9], v[22:23] op_sel_hi:[1,0,1]
	v_pk_mul_f32 v[22:23], v[104:105], v[118:119] op_sel_hi:[1,0]
	v_pk_fma_f32 v[104:105], v[26:27], v[8:9], v[22:23] op_sel_hi:[1,0,1]
	v_pk_mul_f32 v[22:23], v[106:107], v[118:119] op_sel_hi:[1,0]
	v_pk_fma_f32 v[106:107], v[28:29], v[8:9], v[22:23] op_sel_hi:[1,0,1]
	ds_read_b128 v[22:25], v59 offset:2048
	ds_read_b128 v[26:29], v59 offset:2064
	ds_read_b128 v[38:41], v59 offset:10240
	ds_read_b128 v[42:45], v59 offset:10256
	ds_read_b32 v8, v60 offset:16640
	ds_read_b32 v115, v60 offset:17664
	ds_read_b64 v[112:113], v157 offset:18496
	s_waitcnt lgkmcnt(7)
	v_pk_mul_f32 v[98:99], v[108:109], v[98:99]
	v_pk_fma_f32 v[96:97], v[46:47], v[96:97], v[98:99]
	v_pk_mul_f32 v[46:47], v[46:47], v[110:111] op_sel_hi:[1,0]
	v_pk_mul_f32 v[98:99], v[106:107], v[102:103]
	v_pk_fma_f32 v[46:47], v[88:89], v[16:17], v[46:47] op_sel_hi:[1,0,1]
	v_pk_mul_f32 v[88:89], v[108:109], v[110:111] op_sel_hi:[1,0]
	v_pk_fma_f32 v[98:99], v[104:105], v[100:101], v[98:99]
	v_pk_fma_f32 v[108:109], v[90:91], v[16:17], v[88:89] op_sel_hi:[1,0,1]
	v_pk_mul_f32 v[88:89], v[104:105], v[110:111] op_sel_hi:[1,0]
	v_pk_add_f32 v[96:97], v[96:97], v[98:99]
	v_pk_fma_f32 v[104:105], v[92:93], v[16:17], v[88:89] op_sel_hi:[1,0,1]
	v_pk_mul_f32 v[88:89], v[106:107], v[110:111] op_sel_hi:[1,0]
	v_add_f32_e32 v96, v96, v97
	v_pk_fma_f32 v[106:107], v[94:95], v[16:17], v[88:89] op_sel_hi:[1,0,1]
	s_waitcnt lgkmcnt(0)
	v_pk_mul_f32 v[40:41], v[108:109], v[40:41]
	v_add_f32_dpp v96, v96, v96 quad_perm:[1,0,3,2] row_mask:0xf bank_mask:0xf bound_ctrl:1
	v_pk_fma_f32 v[38:39], v[46:47], v[38:39], v[40:41]
	v_pk_mul_f32 v[40:41], v[106:107], v[44:45]
	v_add_f32_dpp v96, v96, v96 quad_perm:[2,3,0,1] row_mask:0xf bank_mask:0xf bound_ctrl:1
	v_pk_fma_f32 v[40:41], v[104:105], v[42:43], v[40:41]
	v_pk_add_f32 v[38:39], v[38:39], v[40:41]
	v_add_f32_dpp v96, v96, v96 row_half_mirror row_mask:0xf bank_mask:0xf bound_ctrl:1
	v_add_f32_e32 v38, v38, v39
	s_nop 0
	v_add_f32_dpp v96, v96, v96 row_mirror row_mask:0xf bank_mask:0xf bound_ctrl:1
	v_add_f32_dpp v38, v38, v38 quad_perm:[1,0,3,2] row_mask:0xf bank_mask:0xf bound_ctrl:1
	v_mul_f32_e32 v96, v110, v96
	v_fmac_f32_e32 v96, v16, v111
	v_add_f32_dpp v38, v38, v38 quad_perm:[2,3,0,1] row_mask:0xf bank_mask:0xf bound_ctrl:1
	v_add_f32_e32 v96, v114, v96
	ds_write_b32 v65, v96 offset:37376
	v_add_f32_dpp v38, v38, v38 row_half_mirror row_mask:0xf bank_mask:0xf bound_ctrl:1
	ds_read_b128 v[88:91], v59 offset:2560
	ds_read_b128 v[92:95], v59 offset:2576
	v_add_f32_dpp v38, v38, v38 row_mirror row_mask:0xf bank_mask:0xf bound_ctrl:1
	ds_read_b128 v[96:99], v59 offset:10752
	v_mul_f32_e32 v38, v112, v38
	ds_read_b128 v[100:103], v59 offset:10768
	v_fmac_f32_e32 v38, v8, v113
	ds_read_b32 v16, v60 offset:16704
	v_add_f32_e32 v40, v115, v38
	v_pk_mul_f32 v[38:39], v[46:47], v[112:113] op_sel_hi:[1,0]
	ds_read_b32 v114, v60 offset:17728
	v_pk_fma_f32 v[46:47], v[22:23], v[8:9], v[38:39] op_sel_hi:[1,0,1]
	v_pk_mul_f32 v[22:23], v[108:109], v[112:113] op_sel_hi:[1,0]
	ds_read_b64 v[110:111], v157 offset:18512
	v_pk_fma_f32 v[108:109], v[24:25], v[8:9], v[22:23] op_sel_hi:[1,0,1]
	v_pk_mul_f32 v[22:23], v[104:105], v[112:113] op_sel_hi:[1,0]
	ds_write_b32 v66, v40 offset:37376
	v_pk_fma_f32 v[104:105], v[26:27], v[8:9], v[22:23] op_sel_hi:[1,0,1]
	v_pk_mul_f32 v[22:23], v[106:107], v[112:113] op_sel_hi:[1,0]
	v_pk_fma_f32 v[106:107], v[28:29], v[8:9], v[22:23] op_sel_hi:[1,0,1]
	ds_read_b128 v[22:25], v59 offset:3072
	ds_read_b128 v[26:29], v59 offset:3088
	ds_read_b128 v[38:41], v59 offset:11264
	ds_read_b128 v[42:45], v59 offset:11280
	ds_read_b32 v8, v60 offset:16768
	ds_read_b32 v115, v60 offset:17792
	s_waitcnt lgkmcnt(14)
	ds_read_b64 v[112:113], v157 offset:18528
	s_waitcnt lgkmcnt(8)
	v_pk_mul_f32 v[98:99], v[108:109], v[98:99]
	v_pk_fma_f32 v[96:97], v[46:47], v[96:97], v[98:99]
	v_pk_mul_f32 v[98:99], v[106:107], v[102:103]
	v_pk_fma_f32 v[98:99], v[104:105], v[100:101], v[98:99]
	v_pk_add_f32 v[96:97], v[96:97], v[98:99]
	v_add_f32_e32 v96, v96, v97
	v_pk_mul_f32 v[46:47], v[46:47], v[110:111] op_sel_hi:[1,0]
	v_pk_fma_f32 v[46:47], v[88:89], v[16:17], v[46:47] op_sel_hi:[1,0,1]
	v_add_f32_dpp v96, v96, v96 quad_perm:[1,0,3,2] row_mask:0xf bank_mask:0xf bound_ctrl:1
	v_pk_mul_f32 v[88:89], v[108:109], v[110:111] op_sel_hi:[1,0]
	v_pk_fma_f32 v[108:109], v[90:91], v[16:17], v[88:89] op_sel_hi:[1,0,1]
	v_pk_mul_f32 v[88:89], v[104:105], v[110:111] op_sel_hi:[1,0]
	v_add_f32_dpp v96, v96, v96 quad_perm:[2,3,0,1] row_mask:0xf bank_mask:0xf bound_ctrl:1
	v_pk_fma_f32 v[104:105], v[92:93], v[16:17], v[88:89] op_sel_hi:[1,0,1]
	v_pk_mul_f32 v[88:89], v[106:107], v[110:111] op_sel_hi:[1,0]
	v_add_f32_dpp v96, v96, v96 row_half_mirror row_mask:0xf bank_mask:0xf bound_ctrl:1
	v_pk_fma_f32 v[106:107], v[94:95], v[16:17], v[88:89] op_sel_hi:[1,0,1]
	s_waitcnt lgkmcnt(0)
; DI float row16_sum(float v) { v += dppf(v, 0); v += dppf(v, 1); v += dppf(v, 2); v += dppf(v, 3); return v; }
; DI void mamba_scan(CP p, const Ptrs& w, int l, int item, float* sm) {
;     ...
; #pragma unroll
;     for (int j = 0; j < 16; ++j) {
;       MStep nxt = cur;
;       if (j + 1 < 16) nxt = lds_step(bf, j + 1);
;       f2v ya = M0 * cur.C0.xy + M1 * cur.C0.zw, yb = M2 * cur.C1.xy + M3 * cur.C1.zw;
;       ya += yb;
;       float yp = row16_sum(ya.x + ya.y);
;       float y = cur.sc.x * yp + cur.xq * cur.sc.y + cur.ds;
;       const float dA = cur.sc.x, xq = cur.xq;
;       M0 = M0 * dA + xq * cur.B0.xy; M1 = M1 * dA + xq * cur.B0.zw;
;       M2 = M2 * dA + xq * cur.B1.xy; M3 = M3 * dA + xq * cur.B1.zw;
;       sy[(ng == 0 ? j * 16 : 0) + ysel] = y;
;       cur = nxt;
;     }
	v_pk_mul_f32 v[40:41], v[108:109], v[40:41]
	v_add_f32_dpp v96, v96, v96 row_mirror row_mask:0xf bank_mask:0xf bound_ctrl:1
	v_pk_fma_f32 v[38:39], v[46:47], v[38:39], v[40:41]
	v_pk_mul_f32 v[40:41], v[106:107], v[44:45]
	v_mul_f32_e32 v96, v110, v96
	v_pk_fma_f32 v[40:41], v[104:105], v[42:43], v[40:41]
	v_fmac_f32_e32 v96, v16, v111
	v_pk_add_f32 v[38:39], v[38:39], v[40:41]
	v_add_f32_e32 v96, v114, v96
	v_add_f32_e32 v38, v38, v39
	ds_write_b32 v67, v96 offset:37376
	ds_read_b128 v[88:91], v59 offset:3584
	v_add_f32_dpp v38, v38, v38 quad_perm:[1,0,3,2] row_mask:0xf bank_mask:0xf bound_ctrl:1
	ds_read_b128 v[92:95], v59 offset:3600
	ds_read_b128 v[96:99], v59 offset:11776
	v_add_f32_dpp v38, v38, v38 quad_perm:[2,3,0,1] row_mask:0xf bank_mask:0xf bound_ctrl:1
	ds_read_b128 v[100:103], v59 offset:11792
	ds_read_b32 v16, v60 offset:16832
	v_add_f32_dpp v38, v38, v38 row_half_mirror row_mask:0xf bank_mask:0xf bound_ctrl:1
	ds_read_b32 v114, v60 offset:17856
	ds_read_b64 v[110:111], v157 offset:18544
	v_add_f32_dpp v38, v38, v38 row_mirror row_mask:0xf bank_mask:0xf bound_ctrl:1
	v_mul_f32_e32 v38, v112, v38
	v_fmac_f32_e32 v38, v8, v113
	v_add_f32_e32 v40, v115, v38
	v_pk_mul_f32 v[38:39], v[46:47], v[112:113] op_sel_hi:[1,0]
	ds_write_b32 v68, v40 offset:37376
	v_pk_fma_f32 v[46:47], v[22:23], v[8:9], v[38:39] op_sel_hi:[1,0,1]
	v_pk_mul_f32 v[22:23], v[108:109], v[112:113] op_sel_hi:[1,0]
	v_pk_fma_f32 v[108:109], v[24:25], v[8:9], v[22:23] op_sel_hi:[1,0,1]
	v_pk_mul_f32 v[22:23], v[104:105], v[112:113] op_sel_hi:[1,0]
	v_pk_fma_f32 v[104:105], v[26:27], v[8:9], v[22:23] op_sel_hi:[1,0,1]
	v_pk_mul_f32 v[22:23], v[106:107], v[112:113] op_sel_hi:[1,0]
	v_pk_fma_f32 v[106:107], v[28:29], v[8:9], v[22:23] op_sel_hi:[1,0,1]
	ds_read_b128 v[22:25], v59 offset:4096
	ds_read_b128 v[26:29], v59 offset:4112
	ds_read_b128 v[38:41], v59 offset:12288
	ds_read_b128 v[42:45], v59 offset:12304
	ds_read_b32 v8, v60 offset:16896
	ds_read_b32 v115, v60 offset:17920
	s_waitcnt lgkmcnt(14)
	ds_read_b64 v[112:113], v157 offset:18560
	s_waitcnt lgkmcnt(7)
	v_pk_mul_f32 v[98:99], v[108:109], v[98:99]
	v_pk_fma_f32 v[96:97], v[46:47], v[96:97], v[98:99]
	v_pk_mul_f32 v[98:99], v[106:107], v[102:103]
	v_pk_fma_f32 v[98:99], v[104:105], v[100:101], v[98:99]
	v_pk_add_f32 v[96:97], v[96:97], v[98:99]
	v_pk_mul_f32 v[46:47], v[46:47], v[110:111] op_sel_hi:[1,0]
	v_add_f32_e32 v96, v96, v97
	v_pk_fma_f32 v[46:47], v[88:89], v[16:17], v[46:47] op_sel_hi:[1,0,1]
	v_pk_mul_f32 v[88:89], v[108:109], v[110:111] op_sel_hi:[1,0]
	v_add_f32_dpp v96, v96, v96 quad_perm:[1,0,3,2] row_mask:0xf bank_mask:0xf bound_ctrl:1
	v_pk_fma_f32 v[108:109], v[90:91], v[16:17], v[88:89] op_sel_hi:[1,0,1]
	v_pk_mul_f32 v[88:89], v[104:105], v[110:111] op_sel_hi:[1,0]
	v_add_f32_dpp v96, v96, v96 quad_perm:[2,3,0,1] row_mask:0xf bank_mask:0xf bound_ctrl:1
	v_pk_fma_f32 v[104:105], v[92:93], v[16:17], v[88:89] op_sel_hi:[1,0,1]
	v_pk_mul_f32 v[88:89], v[106:107], v[110:111] op_sel_hi:[1,0]
	v_add_f32_dpp v96, v96, v96 row_half_mirror row_mask:0xf bank_mask:0xf bound_ctrl:1
	v_pk_fma_f32 v[106:107], v[94:95], v[16:17], v[88:89] op_sel_hi:[1,0,1]
	s_waitcnt lgkmcnt(0)
	v_pk_mul_f32 v[40:41], v[108:109], v[40:41]
	v_add_f32_dpp v96, v96, v96 row_mirror row_mask:0xf bank_mask:0xf bound_ctrl:1
	v_pk_fma_f32 v[38:39], v[46:47], v[38:39], v[40:41]
	v_pk_mul_f32 v[40:41], v[106:107], v[44:45]
	v_mul_f32_e32 v96, v110, v96
	v_pk_fma_f32 v[40:41], v[104:105], v[42:43], v[40:41]
	v_fmac_f32_e32 v96, v16, v111
	v_pk_add_f32 v[38:39], v[38:39], v[40:41]
	v_add_f32_e32 v96, v114, v96
	v_add_f32_e32 v38, v38, v39
	ds_write_b32 v70, v96 offset:37376
	ds_read_b128 v[88:91], v59 offset:4608
	v_add_f32_dpp v38, v38, v38 quad_perm:[1,0,3,2] row_mask:0xf bank_mask:0xf bound_ctrl:1
	ds_read_b128 v[92:95], v59 offset:4624
	ds_read_b128 v[96:99], v59 offset:12800
	v_add_f32_dpp v38, v38, v38 quad_perm:[2,3,0,1] row_mask:0xf bank_mask:0xf bound_ctrl:1
	ds_read_b128 v[100:103], v59 offset:12816
	ds_read_b32 v16, v60 offset:16960
	v_add_f32_dpp v38, v38, v38 row_half_mirror row_mask:0xf bank_mask:0xf bound_ctrl:1
	ds_read_b32 v114, v60 offset:17984
	ds_read_b64 v[110:111], v157 offset:18576
	v_add_f32_dpp v38, v38, v38 row_mirror row_mask:0xf bank_mask:0xf bound_ctrl:1
	v_mul_f32_e32 v38, v112, v38
	v_fmac_f32_e32 v38, v8, v113
	v_add_f32_e32 v40, v115, v38
	v_pk_mul_f32 v[38:39], v[46:47], v[112:113] op_sel_hi:[1,0]
	ds_write_b32 v71, v40 offset:37376
	v_pk_fma_f32 v[46:47], v[22:23], v[8:9], v[38:39] op_sel_hi:[1,0,1]
	v_pk_mul_f32 v[22:23], v[108:109], v[112:113] op_sel_hi:[1,0]
	v_pk_fma_f32 v[108:109], v[24:25], v[8:9], v[22:23] op_sel_hi:[1,0,1]
	v_pk_mul_f32 v[22:23], v[104:105], v[112:113] op_sel_hi:[1,0]
	v_pk_fma_f32 v[104:105], v[26:27], v[8:9], v[22:23] op_sel_hi:[1,0,1]
	v_pk_mul_f32 v[22:23], v[106:107], v[112:113] op_sel_hi:[1,0]
	v_pk_fma_f32 v[106:107], v[28:29], v[8:9], v[22:23] op_sel_hi:[1,0,1]
	ds_read_b128 v[22:25], v59 offset:5120
	ds_read_b128 v[26:29], v59 offset:5136
	ds_read_b128 v[38:41], v59 offset:13312
	ds_read_b128 v[42:45], v59 offset:13328
	ds_read_b32 v8, v60 offset:17024
	ds_read_b32 v115, v60 offset:18048
	s_waitcnt lgkmcnt(14)
	ds_read_b64 v[112:113], v157 offset:18592
	s_waitcnt lgkmcnt(7)
; DI float row16_sum(float v) { v += dppf(v, 0); v += dppf(v, 1); v += dppf(v, 2); v += dppf(v, 3); return v; }
; DI void mamba_scan(CP p, const Ptrs& w, int l, int item, float* sm) {
;     ...
; #pragma unroll
;     for (int j = 0; j < 16; ++j) {
;       MStep nxt = cur;
;       if (j + 1 < 16) nxt = lds_step(bf, j + 1);
;       f2v ya = M0 * cur.C0.xy + M1 * cur.C0.zw, yb = M2 * cur.C1.xy + M3 * cur.C1.zw;
;       ya += yb;
;       float yp = row16_sum(ya.x + ya.y);
;       float y = cur.sc.x * yp + cur.xq * cur.sc.y + cur.ds;
;       const float dA = cur.sc.x, xq = cur.xq;
;       M0 = M0 * dA + xq * cur.B0.xy; M1 = M1 * dA + xq * cur.B0.zw;
;       M2 = M2 * dA + xq * cur.B1.xy; M3 = M3 * dA + xq * cur.B1.zw;
;       sy[(ng == 0 ? j * 16 : 0) + ysel] = y;
;       cur = nxt;
;     }
	v_pk_mul_f32 v[98:99], v[108:109], v[98:99]
	v_pk_fma_f32 v[96:97], v[46:47], v[96:97], v[98:99]
	v_pk_mul_f32 v[98:99], v[106:107], v[102:103]
	v_pk_fma_f32 v[98:99], v[104:105], v[100:101], v[98:99]
	v_pk_add_f32 v[96:97], v[96:97], v[98:99]
	v_pk_mul_f32 v[46:47], v[46:47], v[110:111] op_sel_hi:[1,0]
	v_add_f32_e32 v96, v96, v97
	v_pk_fma_f32 v[46:47], v[88:89], v[16:17], v[46:47] op_sel_hi:[1,0,1]
	v_pk_mul_f32 v[88:89], v[108:109], v[110:111] op_sel_hi:[1,0]
	v_add_f32_dpp v96, v96, v96 quad_perm:[1,0,3,2] row_mask:0xf bank_mask:0xf bound_ctrl:1
	v_pk_fma_f32 v[108:109], v[90:91], v[16:17], v[88:89] op_sel_hi:[1,0,1]
	v_pk_mul_f32 v[88:89], v[104:105], v[110:111] op_sel_hi:[1,0]
	v_add_f32_dpp v96, v96, v96 quad_perm:[2,3,0,1] row_mask:0xf bank_mask:0xf bound_ctrl:1
	v_pk_fma_f32 v[104:105], v[92:93], v[16:17], v[88:89] op_sel_hi:[1,0,1]
	v_pk_mul_f32 v[88:89], v[106:107], v[110:111] op_sel_hi:[1,0]
	v_add_f32_dpp v96, v96, v96 row_half_mirror row_mask:0xf bank_mask:0xf bound_ctrl:1
	v_pk_fma_f32 v[106:107], v[94:95], v[16:17], v[88:89] op_sel_hi:[1,0,1]
	s_waitcnt lgkmcnt(0)
	v_pk_mul_f32 v[40:41], v[108:109], v[40:41]
	v_add_f32_dpp v96, v96, v96 row_mirror row_mask:0xf bank_mask:0xf bound_ctrl:1
	v_pk_fma_f32 v[38:39], v[46:47], v[38:39], v[40:41]
	v_mul_f32_e32 v96, v110, v96
	v_pk_mul_f32 v[40:41], v[106:107], v[44:45]
	v_fmac_f32_e32 v96, v16, v111
	v_pk_fma_f32 v[40:41], v[104:105], v[42:43], v[40:41]
	v_add_f32_e32 v96, v114, v96
	v_pk_add_f32 v[38:39], v[38:39], v[40:41]
	ds_write_b32 v73, v96 offset:37376
	ds_read_b128 v[88:91], v59 offset:5632
	ds_read_b128 v[92:95], v59 offset:5648
	v_add_f32_e32 v38, v38, v39
	ds_read_b128 v[96:99], v59 offset:13824
	ds_read_b128 v[100:103], v59 offset:13840
	v_add_f32_dpp v38, v38, v38 quad_perm:[1,0,3,2] row_mask:0xf bank_mask:0xf bound_ctrl:1
	ds_read_b32 v16, v60 offset:17088
	ds_read_b32 v114, v60 offset:18112
	v_add_f32_dpp v38, v38, v38 quad_perm:[2,3,0,1] row_mask:0xf bank_mask:0xf bound_ctrl:1
	ds_read_b64 v[110:111], v157 offset:18608
	s_nop 0
	v_add_f32_dpp v38, v38, v38 row_half_mirror row_mask:0xf bank_mask:0xf bound_ctrl:1
	s_nop 1
	v_add_f32_dpp v38, v38, v38 row_mirror row_mask:0xf bank_mask:0xf bound_ctrl:1
	v_mul_f32_e32 v38, v112, v38
	v_fmac_f32_e32 v38, v8, v113
	v_add_f32_e32 v40, v115, v38
	v_pk_mul_f32 v[38:39], v[46:47], v[112:113] op_sel_hi:[1,0]
	ds_write_b32 v74, v40 offset:37376
	v_pk_fma_f32 v[46:47], v[22:23], v[8:9], v[38:39] op_sel_hi:[1,0,1]
	v_pk_mul_f32 v[22:23], v[108:109], v[112:113] op_sel_hi:[1,0]
	v_pk_fma_f32 v[108:109], v[24:25], v[8:9], v[22:23] op_sel_hi:[1,0,1]
	v_pk_mul_f32 v[22:23], v[104:105], v[112:113] op_sel_hi:[1,0]
	v_pk_fma_f32 v[104:105], v[26:27], v[8:9], v[22:23] op_sel_hi:[1,0,1]
	v_pk_mul_f32 v[22:23], v[106:107], v[112:113] op_sel_hi:[1,0]
	v_pk_fma_f32 v[106:107], v[28:29], v[8:9], v[22:23] op_sel_hi:[1,0,1]
	ds_read_b128 v[22:25], v59 offset:6144
	ds_read_b128 v[26:29], v59 offset:6160
	ds_read_b128 v[38:41], v59 offset:14336
	ds_read_b128 v[42:45], v59 offset:14352
	ds_read_b32 v8, v60 offset:17152
	ds_read_b32 v115, v60 offset:18176
	s_waitcnt lgkmcnt(14)
	ds_read_b64 v[112:113], v157 offset:18624
	s_waitcnt lgkmcnt(7)
	v_pk_mul_f32 v[98:99], v[108:109], v[98:99]
	v_pk_fma_f32 v[96:97], v[46:47], v[96:97], v[98:99]
	v_pk_mul_f32 v[98:99], v[106:107], v[102:103]
	v_pk_fma_f32 v[98:99], v[104:105], v[100:101], v[98:99]
	v_pk_add_f32 v[96:97], v[96:97], v[98:99]
	v_pk_mul_f32 v[46:47], v[46:47], v[110:111] op_sel_hi:[1,0]
	v_add_f32_e32 v96, v96, v97
	v_pk_fma_f32 v[46:47], v[88:89], v[16:17], v[46:47] op_sel_hi:[1,0,1]
	v_pk_mul_f32 v[88:89], v[108:109], v[110:111] op_sel_hi:[1,0]
	v_add_f32_dpp v96, v96, v96 quad_perm:[1,0,3,2] row_mask:0xf bank_mask:0xf bound_ctrl:1
	v_pk_fma_f32 v[108:109], v[90:91], v[16:17], v[88:89] op_sel_hi:[1,0,1]
	v_pk_mul_f32 v[88:89], v[104:105], v[110:111] op_sel_hi:[1,0]
	v_add_f32_dpp v96, v96, v96 quad_perm:[2,3,0,1] row_mask:0xf bank_mask:0xf bound_ctrl:1
	v_pk_fma_f32 v[104:105], v[92:93], v[16:17], v[88:89] op_sel_hi:[1,0,1]
	v_pk_mul_f32 v[88:89], v[106:107], v[110:111] op_sel_hi:[1,0]
	v_add_f32_dpp v96, v96, v96 row_half_mirror row_mask:0xf bank_mask:0xf bound_ctrl:1
	v_pk_fma_f32 v[106:107], v[94:95], v[16:17], v[88:89] op_sel_hi:[1,0,1]
	s_waitcnt lgkmcnt(0)
	v_pk_mul_f32 v[40:41], v[108:109], v[40:41]
	v_add_f32_dpp v96, v96, v96 row_mirror row_mask:0xf bank_mask:0xf bound_ctrl:1
	v_pk_fma_f32 v[38:39], v[46:47], v[38:39], v[40:41]
	v_mul_f32_e32 v96, v110, v96
	v_pk_mul_f32 v[40:41], v[106:107], v[44:45]
	v_fmac_f32_e32 v96, v16, v111
	v_pk_fma_f32 v[40:41], v[104:105], v[42:43], v[40:41]
	v_add_f32_e32 v96, v114, v96
	v_pk_add_f32 v[38:39], v[38:39], v[40:41]
	ds_write_b32 v75, v96 offset:37376
	ds_read_b128 v[88:91], v59 offset:6656
	ds_read_b128 v[92:95], v59 offset:6672
	ds_read_b128 v[96:99], v59 offset:14848
	ds_read_b128 v[100:103], v59 offset:14864
	v_add_f32_e32 v38, v38, v39
	ds_read_b32 v16, v60 offset:17216
	ds_read_b32 v118, v60 offset:18240
	v_add_f32_dpp v38, v38, v38 quad_perm:[1,0,3,2] row_mask:0xf bank_mask:0xf bound_ctrl:1
	ds_read_b64 v[116:117], v157 offset:18640
	s_nop 0
	v_add_f32_dpp v38, v38, v38 quad_perm:[2,3,0,1] row_mask:0xf bank_mask:0xf bound_ctrl:1
	s_nop 1
	v_add_f32_dpp v38, v38, v38 row_half_mirror row_mask:0xf bank_mask:0xf bound_ctrl:1
	s_nop 1
	v_add_f32_dpp v38, v38, v38 row_mirror row_mask:0xf bank_mask:0xf bound_ctrl:1
	v_mul_f32_e32 v38, v112, v38
	v_fmac_f32_e32 v38, v8, v113
	v_add_f32_e32 v40, v115, v38
	v_pk_mul_f32 v[38:39], v[46:47], v[112:113] op_sel_hi:[1,0]
	ds_write_b32 v76, v40 offset:37376
	v_pk_fma_f32 v[22:23], v[22:23], v[8:9], v[38:39] op_sel_hi:[1,0,1]
	v_pk_mul_f32 v[38:39], v[108:109], v[112:113] op_sel_hi:[1,0]
	ds_read_b128 v[42:45], v59 offset:7168
	v_pk_fma_f32 v[24:25], v[24:25], v[8:9], v[38:39] op_sel_hi:[1,0,1]
	v_pk_mul_f32 v[38:39], v[104:105], v[112:113] op_sel_hi:[1,0]
	v_pk_fma_f32 v[26:27], v[26:27], v[8:9], v[38:39] op_sel_hi:[1,0,1]
	v_pk_mul_f32 v[38:39], v[106:107], v[112:113] op_sel_hi:[1,0]
	ds_read_b128 v[104:107], v59 offset:7184
	v_pk_fma_f32 v[28:29], v[28:29], v[8:9], v[38:39] op_sel_hi:[1,0,1]
	ds_read_b128 v[108:111], v59 offset:15360
	ds_read_b128 v[112:115], v59 offset:15376
	ds_read_b32 v8, v60 offset:17280
	ds_read_b32 v119, v60 offset:18304
	s_waitcnt lgkmcnt(14)
; DI float bf2f(bf16_t h) { return __uint_as_float(((unsigned)h) << 16); }
; DI float siluf(float x) { return x * sigmf(x); }
; DI float row16_sum(float v) { v += dppf(v, 0); v += dppf(v, 1); v += dppf(v, 2); v += dppf(v, 3); return v; }
; DI void mamba_scan(CP p, const Ptrs& w, int l, int item, float* sm) {
;     ...
;   auto stage = [&](const MPre& P, float* bufp) {
; #pragma unroll
;     for (int i = 0; i < 2; ++i) {
;       int idx = tid + 256 * i, j = idx >> 5, q = idx & 31;
;       float f[8];
;       unpack8(P.pbq[i], f);
;       float* d = bufp + (q < 16 ? 0 : 2048) + j * 128 + (q & 15) * 8;
;       *(float4*)d = make_float4(f[0], f[1], f[2], f[3]);
;       *(float4*)(d + 4) = make_float4(f[4], f[5], f[6], f[7]);
;     }
;     {
;       float xs = siluf(wX0 * P.pxm[0] * bf2f(P.px[0]) + wX1 * bf2f(P.px[1]) + wX2 * P.pxm[1] * bf2f(P.px[2]) + bX);
;       bufp[4096 + xj * 16 + xp] = xs * P.pdt[0];
;       bufp[4096 + 256 + xj * 16 + xp] = Dsk * xs;
;       if (xp == 0) *(float4*)(bufp + 4096 + 512 + xj * 4) = make_float4(P.pdt[1], P.pdt[2], 0.f, 0.f);
;     }
;     ...
; #pragma unroll
;     for (int j = 0; j < 16; ++j) {
;       MStep nxt = cur;
;       if (j + 1 < 16) nxt = lds_step(bf, j + 1);
;       f2v ya = M0 * cur.C0.xy + M1 * cur.C0.zw, yb = M2 * cur.C1.xy + M3 * cur.C1.zw;
;       ya += yb;
;       float yp = row16_sum(ya.x + ya.y);
;       float y = cur.sc.x * yp + cur.xq * cur.sc.y + cur.ds;
;       const float dA = cur.sc.x, xq = cur.xq;
;       M0 = M0 * dA + xq * cur.B0.xy; M1 = M1 * dA + xq * cur.B0.zw;
;       M2 = M2 * dA + xq * cur.B1.xy; M3 = M3 * dA + xq * cur.B1.zw;
;       sy[(ng == 0 ? j * 16 : 0) + ysel] = y;
;       cur = nxt;
;     }
	ds_read_b64 v[46:47], v157 offset:18656
	s_waitcnt lgkmcnt(6)
	v_pk_mul_f32 v[38:39], v[24:25], v[98:99]
	v_pk_mul_f32 v[40:41], v[28:29], v[102:103]
	v_pk_fma_f32 v[38:39], v[22:23], v[96:97], v[38:39]
	v_pk_fma_f32 v[40:41], v[26:27], v[100:101], v[40:41]
	v_pk_add_f32 v[38:39], v[38:39], v[40:41]
	v_add_f32_e32 v38, v38, v39
	v_pk_mul_f32 v[22:23], v[22:23], v[116:117] op_sel_hi:[1,0]
	v_pk_fma_f32 v[40:41], v[88:89], v[16:17], v[22:23] op_sel_hi:[1,0,1]
	v_add_f32_dpp v38, v38, v38 quad_perm:[1,0,3,2] row_mask:0xf bank_mask:0xf bound_ctrl:1
	v_pk_mul_f32 v[22:23], v[24:25], v[116:117] op_sel_hi:[1,0]
	v_pk_fma_f32 v[96:97], v[90:91], v[16:17], v[22:23] op_sel_hi:[1,0,1]
	v_add_f32_dpp v38, v38, v38 quad_perm:[2,3,0,1] row_mask:0xf bank_mask:0xf bound_ctrl:1
	v_pk_mul_f32 v[22:23], v[26:27], v[116:117] op_sel_hi:[1,0]
	v_pk_fma_f32 v[98:99], v[92:93], v[16:17], v[22:23] op_sel_hi:[1,0,1]
	v_add_f32_dpp v38, v38, v38 row_half_mirror row_mask:0xf bank_mask:0xf bound_ctrl:1
	v_pk_mul_f32 v[22:23], v[28:29], v[116:117] op_sel_hi:[1,0]
	v_pk_fma_f32 v[100:101], v[94:95], v[16:17], v[22:23] op_sel_hi:[1,0,1]
	v_add_f32_dpp v38, v38, v38 row_mirror row_mask:0xf bank_mask:0xf bound_ctrl:1
	v_mul_f32_e32 v38, v116, v38
	v_fmac_f32_e32 v38, v16, v117
	v_add_f32_e32 v38, v118, v38
	ds_write_b32 v77, v38 offset:37376
	ds_read_b128 v[26:29], v59 offset:7680
	ds_read_b128 v[22:25], v59 offset:7696
	ds_read_b128 v[88:91], v59 offset:15872
	ds_read_b128 v[92:95], v59 offset:15888
	s_waitcnt lgkmcnt(5)
	v_pk_mul_f32 v[102:103], v[96:97], v[110:111]
	ds_read_b32 v16, v60 offset:17344
	v_pk_fma_f32 v[102:103], v[40:41], v[108:109], v[102:103]
	v_pk_mul_f32 v[108:109], v[100:101], v[114:115]
	v_pk_mul_f32 v[40:41], v[40:41], v[46:47] op_sel_hi:[1,0]
	ds_read_b32 v116, v60 offset:18368
	v_pk_fma_f32 v[108:109], v[98:99], v[112:113], v[108:109]
	v_pk_fma_f32 v[42:43], v[42:43], v[8:9], v[40:41] op_sel_hi:[1,0,1]
	v_pk_mul_f32 v[40:41], v[96:97], v[46:47] op_sel_hi:[1,0]
	v_pk_add_f32 v[102:103], v[102:103], v[108:109]
	ds_read_b64 v[38:39], v157 offset:18672
	v_add_f32_e32 v102, v102, v103
	v_pk_fma_f32 v[44:45], v[44:45], v[8:9], v[40:41] op_sel_hi:[1,0,1]
	v_pk_mul_f32 v[40:41], v[98:99], v[46:47] op_sel_hi:[1,0]
	v_add_f32_dpp v102, v102, v102 quad_perm:[1,0,3,2] row_mask:0xf bank_mask:0xf bound_ctrl:1
	v_pk_fma_f32 v[40:41], v[104:105], v[8:9], v[40:41] op_sel_hi:[1,0,1]
	s_waitcnt lgkmcnt(2)
	v_pk_mul_f32 v[90:91], v[44:45], v[90:91]
	v_add_f32_dpp v102, v102, v102 quad_perm:[2,3,0,1] row_mask:0xf bank_mask:0xf bound_ctrl:1
	v_pk_fma_f32 v[88:89], v[42:43], v[88:89], v[90:91]
	s_nop 0
	v_add_f32_dpp v102, v102, v102 row_half_mirror row_mask:0xf bank_mask:0xf bound_ctrl:1
	s_nop 1
	v_add_f32_dpp v102, v102, v102 row_mirror row_mask:0xf bank_mask:0xf bound_ctrl:1
	v_mul_f32_e32 v102, v46, v102
	v_fmac_f32_e32 v102, v8, v47
	v_pk_mul_f32 v[46:47], v[100:101], v[46:47] op_sel_hi:[1,0]
	v_add_f32_e32 v102, v119, v102
	v_pk_fma_f32 v[46:47], v[106:107], v[8:9], v[46:47] op_sel_hi:[1,0,1]
	ds_write_b32 v78, v102 offset:37376
	v_pk_mul_f32 v[90:91], v[46:47], v[94:95]
	v_pk_fma_f32 v[90:91], v[40:41], v[92:93], v[90:91]
	v_pk_add_f32 v[88:89], v[88:89], v[90:91]
	s_waitcnt vmcnt(8)
	v_lshlrev_b32_e32 v90, 16, v5
	v_add_f32_e32 v8, v88, v89
	v_lshlrev_b32_e32 v88, 16, v4
	v_and_b32_e32 v89, 0xffff0000, v4
	v_add_f32_dpp v8, v8, v8 quad_perm:[1,0,3,2] row_mask:0xf bank_mask:0xf bound_ctrl:1
	v_and_b32_e32 v91, 0xffff0000, v5
	v_lshlrev_b32_e32 v4, 16, v6
	v_add_f32_dpp v8, v8, v8 quad_perm:[2,3,0,1] row_mask:0xf bank_mask:0xf bound_ctrl:1
	v_and_b32_e32 v5, 0xffff0000, v6
	v_lshlrev_b32_e32 v6, 16, v7
	v_add_f32_dpp v8, v8, v8 row_half_mirror row_mask:0xf bank_mask:0xf bound_ctrl:1
	v_and_b32_e32 v7, 0xffff0000, v7
	s_nop 0
	v_add_f32_dpp v8, v8, v8 row_mirror row_mask:0xf bank_mask:0xf bound_ctrl:1
	s_waitcnt lgkmcnt(1)
	v_mul_f32_e32 v8, v38, v8
	v_fmac_f32_e32 v8, v16, v39
	v_add_f32_e32 v8, v116, v8
	ds_write_b32 v80, v8 offset:37376
	ds_write_b128 v58, v[88:91] offset:18688
	ds_write_b128 v58, v[4:7] offset:18704
	v_lshlrev_b32_e32 v4, 16, v0
	v_and_b32_e32 v5, 0xffff0000, v0
	v_lshlrev_b32_e32 v6, 16, v1
	v_and_b32_e32 v7, 0xffff0000, v1
	v_mul_f32_e32 v0, v49, v87
	v_lshlrev_b32_e32 v1, 16, v64
	v_mul_f32_e32 v0, v0, v1
	v_lshlrev_b32_e32 v1, 16, v69
	v_fmac_f32_e32 v0, v50, v1
	v_mul_f32_e32 v1, v51, v86
	v_lshlrev_b32_e32 v8, 16, v79
	v_fmac_f32_e32 v0, v1, v8
	v_add_f32_e32 v8, v52, v0
	v_mul_f32_e32 v0, 0xbfb8aa3b, v8
	v_exp_f32_e32 v39, v0
	v_lshlrev_b32_e32 v0, 16, v2
	v_and_b32_e32 v1, 0xffff0000, v2
	v_lshlrev_b32_e32 v2, 16, v3
	v_add_f32_e32 v39, 1.0, v39
	v_rcp_f32_e32 v39, v39
	v_and_b32_e32 v3, 0xffff0000, v3
	ds_write_b128 v58, v[4:7] offset:22784
	ds_write_b128 v58, v[0:3] offset:22800
	v_mul_f32_e32 v0, v8, v39
	v_mul_f32_e32 v1, v10, v0
	v_mul_f32_e32 v0, v53, v0
	ds_write2st64_b32 v57, v1, v0 offset0:137 offset1:141
	s_and_saveexec_b64 s[4:5], vcc
	v_mov_b32_e32 v8, v11
	v_mov_b32_e32 v10, v157
	v_mov_b32_e32 v11, v157
	ds_write_b128 v72, v[8:11] offset:37120
	s_or_b64 exec, exec, s[4:5]
	s_add_i32 s7, s7, 2
	v_pk_mul_f32 v[0:1], v[42:43], v[38:39] op_sel_hi:[1,0]
	s_min_u32 s4, s7, 0x20c
	v_pk_fma_f32 v[108:109], v[26:27], v[16:17], v[0:1] op_sel_hi:[1,0,1]
	v_pk_mul_f32 v[0:1], v[44:45], v[38:39] op_sel_hi:[1,0]
	s_lshl_b32 s4, s4, 4
	v_pk_fma_f32 v[110:111], v[28:29], v[16:17], v[0:1] op_sel_hi:[1,0,1]
	v_pk_mul_f32 v[0:1], v[40:41], v[38:39] op_sel_hi:[1,0]
	v_cndmask_b32_e64 v87, 1.0, 0, s[42:43]
	v_pk_fma_f32 v[112:113], v[22:23], v[16:17], v[0:1] op_sel_hi:[1,0,1]
	v_pk_mul_f32 v[0:1], v[46:47], v[38:39] op_sel_hi:[1,0]
; DI float row16_sum(float v) { v += dppf(v, 0); v += dppf(v, 1); v += dppf(v, 2); v += dppf(v, 3); return v; }
; DI void mamba_scan(CP p, const Ptrs& w, int l, int item, float* sm) {
;     ...
;   auto load = [&](int c, MPre& P) {
; #pragma unroll
;     for (int i = 0; i < 2; ++i) {
;       int idx = tid + 256 * i, j = idx >> 5, q = idx & 31;
;       int ii = pos2i(c * 16 + j, dir);
;       P.pbq[i] = *(const uint4*)(mbc + ((size_t)b * TPB + ii) * 512 + (q < 16 ? 0 : 256) + gp * 128 + (q & 15) * 8);
;     }
;     {
;       int pos = c * 16 + xj, ii = pos2i(pos, dir);
;       size_t tok = (size_t)b * TPB + ii;
;       const bf16_t* prw = w.pC + tok * SPC;
;       bool hp = (ii != 0) && (ii != CTXL), hn = (ii != CTXL - 1) && (ii != TPB - 1);
;       P.px[0] = prw[chX + (hp ? -SPC : 0)]; P.px[1] = prw[chX]; P.px[2] = prw[chX + (hn ? SPC : 0)];
;       P.pxm[0] = hp ? 1.f : 0.f; P.pxm[1] = hn ? 1.f : 0.f;
;       float2 dd = *(const float2*)(w.mdt + (tok * 16 + dir * 8 + hd) * 2);
;       P.pdt[0] = dd.x; P.pdt[1] = dd.y; P.pdt[2] = w.mcb[tok * 2 + gp];
;     }
;   };
;     ...
; #pragma unroll
;     for (int j = 0; j < 16; ++j) {
;       MStep nxt = cur;
;       if (j + 1 < 16) nxt = lds_step(bf, j + 1);
;       f2v ya = M0 * cur.C0.xy + M1 * cur.C0.zw, yb = M2 * cur.C1.xy + M3 * cur.C1.zw;
;       ya += yb;
;       float yp = row16_sum(ya.x + ya.y);
;       float y = cur.sc.x * yp + cur.xq * cur.sc.y + cur.ds;
;       const float dA = cur.sc.x, xq = cur.xq;
;       M0 = M0 * dA + xq * cur.B0.xy; M1 = M1 * dA + xq * cur.B0.zw;
;       M2 = M2 * dA + xq * cur.B1.xy; M3 = M3 * dA + xq * cur.B1.zw;
;       sy[(ng == 0 ? j * 16 : 0) + ysel] = y;
;       cur = nxt;
;     }
	s_add_i32 s42, s4, 48
	v_pk_fma_f32 v[46:47], v[24:25], v[16:17], v[0:1] op_sel_hi:[1,0,1]
	v_add_u32_e32 v0, s42, v55
	v_cmp_lt_i32_e64 s[4:5], s37, v0
	v_add_u32_e32 v2, s42, v56
	v_add_u32_e32 v8, s42, v54
	v_cndmask_b32_e64 v1, v231, v232, s[4:5]
	v_cmp_lt_i32_e64 s[4:5], s37, v2
	v_sub_u32_e32 v1, v1, v0
	v_cndmask_b32_e64 v0, v1, v0, s[40:41]
	v_cndmask_b32_e64 v3, v231, v232, s[4:5]
	v_cmp_lt_i32_e64 s[4:5], s37, v8
	v_sub_u32_e32 v3, v3, v2
	v_cndmask_b32_e64 v2, v3, v2, s[40:41]
	v_cndmask_b32_e64 v9, v231, v232, s[4:5]
	v_sub_u32_e32 v9, v9, v8
	v_cndmask_b32_e64 v8, v9, v8, s[40:41]
	v_ashrrev_i32_e32 v9, 31, v8
	v_lshl_add_u64 v[10:11], v[8:9], 0, s[90:91]
	v_and_b32_e32 v9, 0xfffffeff, v8
	v_cmp_eq_u32_e64 s[42:43], 0, v9
	v_ashrrev_i32_e32 v1, 31, v0
	v_ashrrev_i32_e32 v3, 31, v2
	v_mov_b64_e32 v[22:23], s[48:49]
	v_and_b32_e32 v16, 0xffffdfff, v8
	v_cndmask_b32_e64 v8, v233, 0, s[42:43]
	v_lshl_add_u64 v[0:1], v[0:1], 0, s[90:91]
	v_lshl_add_u64 v[2:3], v[2:3], 0, s[90:91]
	v_mad_u64_u32 v[22:23], s[4:5], v10, s92, v[22:23]
	v_add_u32_e32 v8, v8, v48
	v_cndmask_b32_e64 v86, 1.0, 0, s[44:45]
	v_lshlrev_b64 v[0:1], 10, v[0:1]
	v_lshlrev_b64 v[2:3], 10, v[2:3]
	v_mad_i32_i24 v23, v11, s92, v23
	v_ashrrev_i32_e32 v9, 31, v8
	v_cmp_eq_u32_e64 s[44:45], s37, v16
	v_lshlrev_b64 v[26:27], 7, v[10:11]
	v_lshl_add_u64 v[0:1], v[30:31], 0, v[0:1]
	v_lshl_add_u64 v[2:3], v[30:31], 0, v[2:3]
	v_lshl_add_u64 v[8:9], v[8:9], 1, v[22:23]
	v_lshl_add_u64 v[22:23], v[22:23], 0, v[156:157]
	v_cndmask_b32_e64 v24, v234, 0, s[44:45]
	v_mov_b32_e32 v25, v157
	v_lshl_or_b32 v26, s6, 3, v26
	s_waitcnt lgkmcnt(0)
	s_barrier
	global_load_dwordx4 v[4:7], v[0:1], off
	s_nop 0
	global_load_dwordx4 v[0:3], v[2:3], off
	v_lshl_add_u64 v[24:25], v[22:23], 0, v[24:25]
	v_lshl_add_u64 v[26:27], s[46:47], 0, v[26:27]
	v_lshl_add_u64 v[28:29], v[10:11], 3, s[50:51]
	global_load_ushort v64, v[8:9], off
	global_load_ushort v69, v[22:23], off
	global_load_ushort v79, v[24:25], off
	global_load_dwordx2 v[10:11], v[26:27], off
	s_nop 0
	global_load_dword v9, v[28:29], off
	v_cmp_lt_i32_e64 s[4:5], s37, v82
	ds_read_b32 v8, v57 offset:37376
	ds_read_b128 v[22:25], v59 offset:18688
	v_cndmask_b32_e64 v16, v231, v232, s[4:5]
	v_add_u32_e32 v16, v16, v81
	v_cndmask_b32_e64 v26, v16, v82, s[40:41]
	v_ashrrev_i32_e32 v27, 31, v26
	v_lshl_add_u64 v[26:27], v[26:27], 0, s[90:91]
	v_lshlrev_b64 v[26:27], 10, v[26:27]
	s_waitcnt lgkmcnt(1)
	v_cvt_pk_bf16_f32 v8, v8, s0
	v_lshl_add_u64 v[26:27], v[34:35], 0, v[26:27]
	global_store_short v[26:27], v8, off
	s_waitcnt lgkmcnt(0)
	v_add_u32_e32 v8, 0x8800, v60
	s_mov_b32 s4, 0x9000
	ds_read2_b32 v[114:115], v8 offset0:64 offset1:80
	v_add_u32_e32 v8, 0x8c00, v60
	ds_read2_b32 v[116:117], v8 offset0:64 offset1:80
	v_add_u32_e64 v8, s4, 0
	ds_read2_b64 v[26:29], v8 offset0:32 offset1:34
	ds_read_b128 v[38:41], v59 offset:18704
	ds_read_b128 v[42:45], v59 offset:19200
	ds_read_b128 v[88:91], v59 offset:26880
	ds_read_b128 v[92:95], v59 offset:19216
	ds_read_b128 v[96:99], v59 offset:26896
	ds_read_b128 v[100:103], v59 offset:27392
	ds_read_b128 v[104:107], v59 offset:27408
	s_waitcnt lgkmcnt(4)
	v_pk_mul_f32 v[90:91], v[110:111], v[90:91]
	v_pk_fma_f32 v[88:89], v[108:109], v[88:89], v[90:91]
	s_waitcnt lgkmcnt(2)
	v_pk_mul_f32 v[90:91], v[46:47], v[98:99]
	v_pk_fma_f32 v[90:91], v[112:113], v[96:97], v[90:91]
	v_pk_add_f32 v[88:89], v[88:89], v[90:91]
	v_add_f32_e32 v8, v88, v89
	v_pk_mul_f32 v[88:89], v[108:109], v[26:27] op_sel_hi:[1,0]
	v_pk_fma_f32 v[108:109], v[22:23], v[114:115], v[88:89] op_sel_hi:[1,0,1]
	v_add_f32_dpp v8, v8, v8 quad_perm:[1,0,3,2] row_mask:0xf bank_mask:0xf bound_ctrl:1
	v_pk_mul_f32 v[22:23], v[110:111], v[26:27] op_sel_hi:[1,0]
	v_pk_fma_f32 v[110:111], v[24:25], v[114:115], v[22:23] op_sel_hi:[1,0,1]
	v_add_f32_dpp v8, v8, v8 quad_perm:[2,3,0,1] row_mask:0xf bank_mask:0xf bound_ctrl:1
	v_pk_mul_f32 v[22:23], v[112:113], v[26:27] op_sel_hi:[1,0]
	s_waitcnt lgkmcnt(0)
	v_pk_mul_f32 v[102:103], v[110:111], v[102:103]
	v_add_f32_dpp v8, v8, v8 row_half_mirror row_mask:0xf bank_mask:0xf bound_ctrl:1
	v_pk_fma_f32 v[112:113], v[38:39], v[114:115], v[22:23] op_sel_hi:[1,0,1]
	v_pk_mul_f32 v[22:23], v[46:47], v[26:27] op_sel_hi:[1,0]
	v_add_f32_dpp v8, v8, v8 row_mirror row_mask:0xf bank_mask:0xf bound_ctrl:1
	v_mul_f32_e32 v8, v26, v8
	v_fmac_f32_e32 v8, v114, v27
	v_pk_fma_f32 v[26:27], v[40:41], v[114:115], v[22:23] op_sel_hi:[1,0,1]
	v_add_f32_e32 v8, v116, v8
	v_pk_fma_f32 v[100:101], v[108:109], v[100:101], v[102:103]
	v_pk_mul_f32 v[102:103], v[26:27], v[106:107]
	ds_write_b32 v61, v8 offset:38400
	ds_read_b128 v[22:25], v59 offset:19712
	ds_read_b128 v[38:41], v59 offset:19728
	ds_read_b128 v[88:91], v59 offset:27904
	ds_read_b128 v[96:99], v59 offset:27920
	v_pk_fma_f32 v[102:103], v[112:113], v[104:105], v[102:103]
	ds_read_b32 v8, v60 offset:35200
	v_pk_add_f32 v[100:101], v[100:101], v[102:103]
	ds_read_b32 v114, v60 offset:36224
	v_add_f32_e32 v16, v100, v101
	ds_read_b64 v[46:47], v157 offset:37152
	v_pk_mul_f32 v[100:101], v[108:109], v[28:29] op_sel_hi:[1,0]
	v_add_f32_dpp v16, v16, v16 quad_perm:[1,0,3,2] row_mask:0xf bank_mask:0xf bound_ctrl:1
	v_pk_mul_f32 v[26:27], v[26:27], v[28:29] op_sel_hi:[1,0]
	s_nop 0
	v_add_f32_dpp v16, v16, v16 quad_perm:[2,3,0,1] row_mask:0xf bank_mask:0xf bound_ctrl:1
	s_nop 1
	v_add_f32_dpp v16, v16, v16 row_half_mirror row_mask:0xf bank_mask:0xf bound_ctrl:1
	s_nop 1
	v_add_f32_dpp v16, v16, v16 row_mirror row_mask:0xf bank_mask:0xf bound_ctrl:1
	v_mul_f32_e32 v16, v28, v16
	v_fmac_f32_e32 v16, v115, v29
	v_add_f32_e32 v102, v117, v16
	v_mov_b32_e32 v16, v115
	ds_write_b32 v62, v102 offset:38400
	v_pk_fma_f32 v[104:105], v[42:43], v[16:17], v[100:101] op_sel_hi:[1,0,1]
	v_pk_mul_f32 v[42:43], v[110:111], v[28:29] op_sel_hi:[1,0]
	v_pk_fma_f32 v[110:111], v[94:95], v[16:17], v[26:27] op_sel_hi:[1,0,1]
	v_pk_fma_f32 v[106:107], v[44:45], v[16:17], v[42:43] op_sel_hi:[1,0,1]
	v_pk_mul_f32 v[42:43], v[112:113], v[28:29] op_sel_hi:[1,0]
	ds_read_b128 v[26:29], v59 offset:20224
	v_pk_fma_f32 v[108:109], v[92:93], v[16:17], v[42:43] op_sel_hi:[1,0,1]
	ds_read_b128 v[42:45], v59 offset:20240
	ds_read_b128 v[92:95], v59 offset:28416
	ds_read_b128 v[100:103], v59 offset:28432
	ds_read_b32 v16, v60 offset:35264
	ds_read_b32 v115, v60 offset:36288
	s_waitcnt lgkmcnt(14)
; DI float row16_sum(float v) { v += dppf(v, 0); v += dppf(v, 1); v += dppf(v, 2); v += dppf(v, 3); return v; }
; DI void mamba_scan(CP p, const Ptrs& w, int l, int item, float* sm) {
;     ...
; #pragma unroll
;     for (int j = 0; j < 16; ++j) {
;       MStep nxt = cur;
;       if (j + 1 < 16) nxt = lds_step(bf, j + 1);
;       f2v ya = M0 * cur.C0.xy + M1 * cur.C0.zw, yb = M2 * cur.C1.xy + M3 * cur.C1.zw;
;       ya += yb;
;       float yp = row16_sum(ya.x + ya.y);
;       float y = cur.sc.x * yp + cur.xq * cur.sc.y + cur.ds;
;       const float dA = cur.sc.x, xq = cur.xq;
;       M0 = M0 * dA + xq * cur.B0.xy; M1 = M1 * dA + xq * cur.B0.zw;
;       M2 = M2 * dA + xq * cur.B1.xy; M3 = M3 * dA + xq * cur.B1.zw;
;       sy[(ng == 0 ? j * 16 : 0) + ysel] = y;
;       cur = nxt;
;     }
	ds_read_b64 v[112:113], v157 offset:37168
	s_waitcnt lgkmcnt(7)
	v_pk_mul_f32 v[90:91], v[106:107], v[90:91]
	v_pk_fma_f32 v[88:89], v[104:105], v[88:89], v[90:91]
	v_pk_mul_f32 v[90:91], v[110:111], v[98:99]
	v_pk_fma_f32 v[90:91], v[108:109], v[96:97], v[90:91]
	v_pk_add_f32 v[88:89], v[88:89], v[90:91]
	v_add_f32_e32 v88, v88, v89
	s_nop 1
	v_add_f32_dpp v88, v88, v88 quad_perm:[1,0,3,2] row_mask:0xf bank_mask:0xf bound_ctrl:1
	s_nop 1
	v_add_f32_dpp v88, v88, v88 quad_perm:[2,3,0,1] row_mask:0xf bank_mask:0xf bound_ctrl:1
	s_nop 1
	v_add_f32_dpp v88, v88, v88 row_half_mirror row_mask:0xf bank_mask:0xf bound_ctrl:1
	s_nop 1
	v_add_f32_dpp v88, v88, v88 row_mirror row_mask:0xf bank_mask:0xf bound_ctrl:1
	v_mul_f32_e32 v88, v46, v88
	v_fmac_f32_e32 v88, v8, v47
	v_add_f32_e32 v90, v114, v88
	v_pk_mul_f32 v[88:89], v[104:105], v[46:47] op_sel_hi:[1,0]
	ds_write_b32 v63, v90 offset:38400
	v_pk_fma_f32 v[104:105], v[22:23], v[8:9], v[88:89] op_sel_hi:[1,0,1]
	v_pk_mul_f32 v[22:23], v[106:107], v[46:47] op_sel_hi:[1,0]
	v_pk_fma_f32 v[106:107], v[24:25], v[8:9], v[22:23] op_sel_hi:[1,0,1]
	v_pk_mul_f32 v[22:23], v[108:109], v[46:47] op_sel_hi:[1,0]
	v_pk_fma_f32 v[108:109], v[38:39], v[8:9], v[22:23] op_sel_hi:[1,0,1]
	v_pk_mul_f32 v[22:23], v[110:111], v[46:47] op_sel_hi:[1,0]
	s_waitcnt lgkmcnt(1)
	v_pk_mul_f32 v[94:95], v[106:107], v[94:95]
	v_pk_fma_f32 v[46:47], v[40:41], v[8:9], v[22:23] op_sel_hi:[1,0,1]
	ds_read_b128 v[22:25], v59 offset:20736
	v_pk_fma_f32 v[92:93], v[104:105], v[92:93], v[94:95]
	v_pk_mul_f32 v[94:95], v[46:47], v[102:103]
	ds_read_b128 v[38:41], v59 offset:20752
	v_pk_fma_f32 v[94:95], v[108:109], v[100:101], v[94:95]
	ds_read_b128 v[88:91], v59 offset:28928
	v_pk_add_f32 v[92:93], v[92:93], v[94:95]
	ds_read_b128 v[96:99], v59 offset:28944
	v_add_f32_e32 v92, v92, v93
	ds_read_b32 v8, v60 offset:35328
	ds_read_b32 v114, v60 offset:36352
	v_add_f32_dpp v92, v92, v92 quad_perm:[1,0,3,2] row_mask:0xf bank_mask:0xf bound_ctrl:1
	ds_read_b64 v[110:111], v157 offset:37184
	s_nop 0
	v_add_f32_dpp v92, v92, v92 quad_perm:[2,3,0,1] row_mask:0xf bank_mask:0xf bound_ctrl:1
	s_nop 1
	v_add_f32_dpp v92, v92, v92 row_half_mirror row_mask:0xf bank_mask:0xf bound_ctrl:1
	s_nop 1
	v_add_f32_dpp v92, v92, v92 row_mirror row_mask:0xf bank_mask:0xf bound_ctrl:1
	v_mul_f32_e32 v92, v112, v92
	v_fmac_f32_e32 v92, v16, v113
	v_add_f32_e32 v94, v115, v92
	v_pk_mul_f32 v[92:93], v[104:105], v[112:113] op_sel_hi:[1,0]
	ds_write_b32 v65, v94 offset:38400
	v_pk_fma_f32 v[104:105], v[26:27], v[16:17], v[92:93] op_sel_hi:[1,0,1]
	v_pk_mul_f32 v[26:27], v[106:107], v[112:113] op_sel_hi:[1,0]
	v_pk_fma_f32 v[106:107], v[28:29], v[16:17], v[26:27] op_sel_hi:[1,0,1]
	v_pk_mul_f32 v[26:27], v[108:109], v[112:113] op_sel_hi:[1,0]
	v_pk_fma_f32 v[108:109], v[42:43], v[16:17], v[26:27] op_sel_hi:[1,0,1]
	v_pk_mul_f32 v[26:27], v[46:47], v[112:113] op_sel_hi:[1,0]
	v_pk_fma_f32 v[46:47], v[44:45], v[16:17], v[26:27] op_sel_hi:[1,0,1]
	ds_read_b128 v[26:29], v59 offset:21248
	ds_read_b128 v[42:45], v59 offset:21264
	ds_read_b128 v[92:95], v59 offset:29440
	ds_read_b128 v[100:103], v59 offset:29456
	ds_read_b32 v16, v60 offset:35392
	ds_read_b32 v115, v60 offset:36416
	s_waitcnt lgkmcnt(14)
	ds_read_b64 v[112:113], v157 offset:37200
	s_waitcnt lgkmcnt(7)
	v_pk_mul_f32 v[90:91], v[106:107], v[90:91]
	v_pk_fma_f32 v[88:89], v[104:105], v[88:89], v[90:91]
	v_pk_mul_f32 v[90:91], v[46:47], v[98:99]
	v_pk_fma_f32 v[90:91], v[108:109], v[96:97], v[90:91]
	v_pk_add_f32 v[88:89], v[88:89], v[90:91]
	v_add_f32_e32 v88, v88, v89
	s_nop 1
	v_add_f32_dpp v88, v88, v88 quad_perm:[1,0,3,2] row_mask:0xf bank_mask:0xf bound_ctrl:1
	s_nop 1
	v_add_f32_dpp v88, v88, v88 quad_perm:[2,3,0,1] row_mask:0xf bank_mask:0xf bound_ctrl:1
	s_nop 1
	v_add_f32_dpp v88, v88, v88 row_half_mirror row_mask:0xf bank_mask:0xf bound_ctrl:1
	s_nop 1
	v_add_f32_dpp v88, v88, v88 row_mirror row_mask:0xf bank_mask:0xf bound_ctrl:1
	v_mul_f32_e32 v88, v110, v88
	v_fmac_f32_e32 v88, v8, v111
	v_add_f32_e32 v90, v114, v88
	v_pk_mul_f32 v[88:89], v[104:105], v[110:111] op_sel_hi:[1,0]
	ds_write_b32 v66, v90 offset:38400
	v_pk_fma_f32 v[104:105], v[22:23], v[8:9], v[88:89] op_sel_hi:[1,0,1]
	v_pk_mul_f32 v[22:23], v[106:107], v[110:111] op_sel_hi:[1,0]
	v_pk_fma_f32 v[106:107], v[24:25], v[8:9], v[22:23] op_sel_hi:[1,0,1]
	v_pk_mul_f32 v[22:23], v[108:109], v[110:111] op_sel_hi:[1,0]
	v_pk_fma_f32 v[108:109], v[38:39], v[8:9], v[22:23] op_sel_hi:[1,0,1]
	v_pk_mul_f32 v[22:23], v[46:47], v[110:111] op_sel_hi:[1,0]
	v_pk_fma_f32 v[46:47], v[40:41], v[8:9], v[22:23] op_sel_hi:[1,0,1]
	ds_read_b128 v[22:25], v59 offset:21760
	s_waitcnt lgkmcnt(2)
	v_pk_mul_f32 v[94:95], v[106:107], v[94:95]
	ds_read_b128 v[38:41], v59 offset:21776
	v_pk_fma_f32 v[92:93], v[104:105], v[92:93], v[94:95]
	v_pk_mul_f32 v[94:95], v[46:47], v[102:103]
	ds_read_b128 v[88:91], v59 offset:29952
	v_pk_fma_f32 v[94:95], v[108:109], v[100:101], v[94:95]
	ds_read_b128 v[96:99], v59 offset:29968
	v_pk_add_f32 v[92:93], v[92:93], v[94:95]
	ds_read_b32 v8, v60 offset:35456
	v_add_f32_e32 v92, v92, v93
	ds_read_b32 v114, v60 offset:36480
	ds_read_b64 v[110:111], v157 offset:37216
	v_add_f32_dpp v92, v92, v92 quad_perm:[1,0,3,2] row_mask:0xf bank_mask:0xf bound_ctrl:1
	s_nop 1
	v_add_f32_dpp v92, v92, v92 quad_perm:[2,3,0,1] row_mask:0xf bank_mask:0xf bound_ctrl:1
	s_nop 1
	v_add_f32_dpp v92, v92, v92 row_half_mirror row_mask:0xf bank_mask:0xf bound_ctrl:1
	s_nop 1
	v_add_f32_dpp v92, v92, v92 row_mirror row_mask:0xf bank_mask:0xf bound_ctrl:1
	v_mul_f32_e32 v92, v112, v92
	v_fmac_f32_e32 v92, v16, v113
	v_add_f32_e32 v94, v115, v92
	v_pk_mul_f32 v[92:93], v[104:105], v[112:113] op_sel_hi:[1,0]
	ds_write_b32 v67, v94 offset:38400
	v_pk_fma_f32 v[104:105], v[26:27], v[16:17], v[92:93] op_sel_hi:[1,0,1]
	v_pk_mul_f32 v[26:27], v[106:107], v[112:113] op_sel_hi:[1,0]
	v_pk_fma_f32 v[106:107], v[28:29], v[16:17], v[26:27] op_sel_hi:[1,0,1]
	v_pk_mul_f32 v[26:27], v[108:109], v[112:113] op_sel_hi:[1,0]
	v_pk_fma_f32 v[108:109], v[42:43], v[16:17], v[26:27] op_sel_hi:[1,0,1]
	v_pk_mul_f32 v[26:27], v[46:47], v[112:113] op_sel_hi:[1,0]
	v_pk_fma_f32 v[46:47], v[44:45], v[16:17], v[26:27] op_sel_hi:[1,0,1]
	ds_read_b128 v[26:29], v59 offset:22272
	ds_read_b128 v[42:45], v59 offset:22288
	ds_read_b128 v[92:95], v59 offset:30464
	ds_read_b128 v[100:103], v59 offset:30480
	ds_read_b32 v16, v60 offset:35520
	ds_read_b32 v115, v60 offset:36544
	s_waitcnt lgkmcnt(14)
; DI float row16_sum(float v) { v += dppf(v, 0); v += dppf(v, 1); v += dppf(v, 2); v += dppf(v, 3); return v; }
; DI void mamba_scan(CP p, const Ptrs& w, int l, int item, float* sm) {
;     ...
; #pragma unroll
;     for (int j = 0; j < 16; ++j) {
;       MStep nxt = cur;
;       if (j + 1 < 16) nxt = lds_step(bf, j + 1);
;       f2v ya = M0 * cur.C0.xy + M1 * cur.C0.zw, yb = M2 * cur.C1.xy + M3 * cur.C1.zw;
;       ya += yb;
;       float yp = row16_sum(ya.x + ya.y);
;       float y = cur.sc.x * yp + cur.xq * cur.sc.y + cur.ds;
;       const float dA = cur.sc.x, xq = cur.xq;
;       M0 = M0 * dA + xq * cur.B0.xy; M1 = M1 * dA + xq * cur.B0.zw;
;       M2 = M2 * dA + xq * cur.B1.xy; M3 = M3 * dA + xq * cur.B1.zw;
;       sy[(ng == 0 ? j * 16 : 0) + ysel] = y;
;       cur = nxt;
;     }
	ds_read_b64 v[112:113], v157 offset:37232
	s_waitcnt lgkmcnt(7)
	v_pk_mul_f32 v[90:91], v[106:107], v[90:91]
	v_pk_fma_f32 v[88:89], v[104:105], v[88:89], v[90:91]
	v_pk_mul_f32 v[90:91], v[46:47], v[98:99]
	v_pk_fma_f32 v[90:91], v[108:109], v[96:97], v[90:91]
	v_pk_add_f32 v[88:89], v[88:89], v[90:91]
	v_add_f32_e32 v88, v88, v89
	s_nop 1
	v_add_f32_dpp v88, v88, v88 quad_perm:[1,0,3,2] row_mask:0xf bank_mask:0xf bound_ctrl:1
	s_nop 1
	v_add_f32_dpp v88, v88, v88 quad_perm:[2,3,0,1] row_mask:0xf bank_mask:0xf bound_ctrl:1
	s_nop 1
	v_add_f32_dpp v88, v88, v88 row_half_mirror row_mask:0xf bank_mask:0xf bound_ctrl:1
	s_nop 1
	v_add_f32_dpp v88, v88, v88 row_mirror row_mask:0xf bank_mask:0xf bound_ctrl:1
	v_mul_f32_e32 v88, v110, v88
	v_fmac_f32_e32 v88, v8, v111
	v_add_f32_e32 v90, v114, v88
	v_pk_mul_f32 v[88:89], v[104:105], v[110:111] op_sel_hi:[1,0]
	ds_write_b32 v68, v90 offset:38400
	v_pk_fma_f32 v[104:105], v[22:23], v[8:9], v[88:89] op_sel_hi:[1,0,1]
	v_pk_mul_f32 v[22:23], v[106:107], v[110:111] op_sel_hi:[1,0]
	v_pk_fma_f32 v[106:107], v[24:25], v[8:9], v[22:23] op_sel_hi:[1,0,1]
	v_pk_mul_f32 v[22:23], v[108:109], v[110:111] op_sel_hi:[1,0]
	v_pk_fma_f32 v[108:109], v[38:39], v[8:9], v[22:23] op_sel_hi:[1,0,1]
	v_pk_mul_f32 v[22:23], v[46:47], v[110:111] op_sel_hi:[1,0]
	v_pk_fma_f32 v[46:47], v[40:41], v[8:9], v[22:23] op_sel_hi:[1,0,1]
	ds_read_b128 v[22:25], v59 offset:22784
	ds_read_b128 v[38:41], v59 offset:22800
	s_waitcnt lgkmcnt(3)
	v_pk_mul_f32 v[94:95], v[106:107], v[94:95]
	ds_read_b128 v[88:91], v59 offset:30976
	v_pk_fma_f32 v[92:93], v[104:105], v[92:93], v[94:95]
	v_pk_mul_f32 v[94:95], v[46:47], v[102:103]
	ds_read_b128 v[96:99], v59 offset:30992
	v_pk_fma_f32 v[94:95], v[108:109], v[100:101], v[94:95]
	ds_read_b32 v8, v60 offset:35584
	v_pk_add_f32 v[92:93], v[92:93], v[94:95]
	ds_read_b32 v114, v60 offset:36608
	v_add_f32_e32 v92, v92, v93
	ds_read_b64 v[110:111], v157 offset:37248
	s_nop 0
	v_add_f32_dpp v92, v92, v92 quad_perm:[1,0,3,2] row_mask:0xf bank_mask:0xf bound_ctrl:1
	s_nop 1
	v_add_f32_dpp v92, v92, v92 quad_perm:[2,3,0,1] row_mask:0xf bank_mask:0xf bound_ctrl:1
	s_nop 1
	v_add_f32_dpp v92, v92, v92 row_half_mirror row_mask:0xf bank_mask:0xf bound_ctrl:1
	s_nop 1
	v_add_f32_dpp v92, v92, v92 row_mirror row_mask:0xf bank_mask:0xf bound_ctrl:1
	v_mul_f32_e32 v92, v112, v92
	v_fmac_f32_e32 v92, v16, v113
	v_add_f32_e32 v94, v115, v92
	v_pk_mul_f32 v[92:93], v[104:105], v[112:113] op_sel_hi:[1,0]
	ds_write_b32 v70, v94 offset:38400
	v_pk_fma_f32 v[104:105], v[26:27], v[16:17], v[92:93] op_sel_hi:[1,0,1]
	v_pk_mul_f32 v[26:27], v[106:107], v[112:113] op_sel_hi:[1,0]
	v_pk_fma_f32 v[106:107], v[28:29], v[16:17], v[26:27] op_sel_hi:[1,0,1]
	v_pk_mul_f32 v[26:27], v[108:109], v[112:113] op_sel_hi:[1,0]
	v_pk_fma_f32 v[108:109], v[42:43], v[16:17], v[26:27] op_sel_hi:[1,0,1]
	v_pk_mul_f32 v[26:27], v[46:47], v[112:113] op_sel_hi:[1,0]
	v_pk_fma_f32 v[46:47], v[44:45], v[16:17], v[26:27] op_sel_hi:[1,0,1]
	ds_read_b128 v[26:29], v59 offset:23296
	ds_read_b128 v[42:45], v59 offset:23312
	ds_read_b128 v[92:95], v59 offset:31488
	ds_read_b128 v[100:103], v59 offset:31504
	ds_read_b32 v16, v60 offset:35648
	ds_read_b32 v115, v60 offset:36672
	s_waitcnt lgkmcnt(14)
	ds_read_b64 v[112:113], v157 offset:37264
	s_waitcnt lgkmcnt(7)
	v_pk_mul_f32 v[90:91], v[106:107], v[90:91]
	v_pk_fma_f32 v[88:89], v[104:105], v[88:89], v[90:91]
	v_pk_mul_f32 v[90:91], v[46:47], v[98:99]
	v_pk_fma_f32 v[90:91], v[108:109], v[96:97], v[90:91]
	v_pk_add_f32 v[88:89], v[88:89], v[90:91]
	v_add_f32_e32 v88, v88, v89
	s_nop 1
	v_add_f32_dpp v88, v88, v88 quad_perm:[1,0,3,2] row_mask:0xf bank_mask:0xf bound_ctrl:1
	s_nop 1
	v_add_f32_dpp v88, v88, v88 quad_perm:[2,3,0,1] row_mask:0xf bank_mask:0xf bound_ctrl:1
	s_nop 1
	v_add_f32_dpp v88, v88, v88 row_half_mirror row_mask:0xf bank_mask:0xf bound_ctrl:1
	s_nop 1
	v_add_f32_dpp v88, v88, v88 row_mirror row_mask:0xf bank_mask:0xf bound_ctrl:1
	v_mul_f32_e32 v88, v110, v88
	v_fmac_f32_e32 v88, v8, v111
	v_add_f32_e32 v90, v114, v88
	v_pk_mul_f32 v[88:89], v[104:105], v[110:111] op_sel_hi:[1,0]
	ds_write_b32 v71, v90 offset:38400
	v_pk_fma_f32 v[104:105], v[22:23], v[8:9], v[88:89] op_sel_hi:[1,0,1]
	v_pk_mul_f32 v[22:23], v[106:107], v[110:111] op_sel_hi:[1,0]
	v_pk_fma_f32 v[106:107], v[24:25], v[8:9], v[22:23] op_sel_hi:[1,0,1]
	v_pk_mul_f32 v[22:23], v[108:109], v[110:111] op_sel_hi:[1,0]
	v_pk_fma_f32 v[108:109], v[38:39], v[8:9], v[22:23] op_sel_hi:[1,0,1]
	v_pk_mul_f32 v[22:23], v[46:47], v[110:111] op_sel_hi:[1,0]
	v_pk_fma_f32 v[46:47], v[40:41], v[8:9], v[22:23] op_sel_hi:[1,0,1]
	ds_read_b128 v[22:25], v59 offset:23808
	ds_read_b128 v[38:41], v59 offset:23824
	ds_read_b128 v[88:91], v59 offset:32000
	s_waitcnt lgkmcnt(4)
	v_pk_mul_f32 v[94:95], v[106:107], v[94:95]
	ds_read_b128 v[96:99], v59 offset:32016
	v_pk_fma_f32 v[92:93], v[104:105], v[92:93], v[94:95]
	v_pk_mul_f32 v[94:95], v[46:47], v[102:103]
	ds_read_b32 v8, v60 offset:35712
	v_pk_fma_f32 v[94:95], v[108:109], v[100:101], v[94:95]
	ds_read_b32 v114, v60 offset:36736
	v_pk_add_f32 v[92:93], v[92:93], v[94:95]
	ds_read_b64 v[110:111], v157 offset:37280
	v_add_f32_e32 v92, v92, v93
	s_nop 1
	v_add_f32_dpp v92, v92, v92 quad_perm:[1,0,3,2] row_mask:0xf bank_mask:0xf bound_ctrl:1
	s_nop 1
	v_add_f32_dpp v92, v92, v92 quad_perm:[2,3,0,1] row_mask:0xf bank_mask:0xf bound_ctrl:1
	s_nop 1
	v_add_f32_dpp v92, v92, v92 row_half_mirror row_mask:0xf bank_mask:0xf bound_ctrl:1
	s_nop 1
	v_add_f32_dpp v92, v92, v92 row_mirror row_mask:0xf bank_mask:0xf bound_ctrl:1
	v_mul_f32_e32 v92, v112, v92
	v_fmac_f32_e32 v92, v16, v113
	v_add_f32_e32 v94, v115, v92
	v_pk_mul_f32 v[92:93], v[104:105], v[112:113] op_sel_hi:[1,0]
	ds_write_b32 v73, v94 offset:38400
	v_pk_fma_f32 v[104:105], v[26:27], v[16:17], v[92:93] op_sel_hi:[1,0,1]
	v_pk_mul_f32 v[26:27], v[106:107], v[112:113] op_sel_hi:[1,0]
	v_pk_fma_f32 v[106:107], v[28:29], v[16:17], v[26:27] op_sel_hi:[1,0,1]
	v_pk_mul_f32 v[26:27], v[108:109], v[112:113] op_sel_hi:[1,0]
	v_pk_fma_f32 v[108:109], v[42:43], v[16:17], v[26:27] op_sel_hi:[1,0,1]
	v_pk_mul_f32 v[26:27], v[46:47], v[112:113] op_sel_hi:[1,0]
	v_pk_fma_f32 v[46:47], v[44:45], v[16:17], v[26:27] op_sel_hi:[1,0,1]
	ds_read_b128 v[26:29], v59 offset:24320
	ds_read_b128 v[42:45], v59 offset:24336
	ds_read_b128 v[92:95], v59 offset:32512
	ds_read_b128 v[100:103], v59 offset:32528
	ds_read_b32 v16, v60 offset:35776
	ds_read_b32 v115, v60 offset:36800
	s_waitcnt lgkmcnt(6)
; DI float row16_sum(float v) { v += dppf(v, 0); v += dppf(v, 1); v += dppf(v, 2); v += dppf(v, 3); return v; }
; DI void mamba_scan(CP p, const Ptrs& w, int l, int item, float* sm) {
;     ...
; #pragma unroll
;     for (int j = 0; j < 16; ++j) {
;       MStep nxt = cur;
;       if (j + 1 < 16) nxt = lds_step(bf, j + 1);
;       f2v ya = M0 * cur.C0.xy + M1 * cur.C0.zw, yb = M2 * cur.C1.xy + M3 * cur.C1.zw;
;       ya += yb;
;       float yp = row16_sum(ya.x + ya.y);
;       float y = cur.sc.x * yp + cur.xq * cur.sc.y + cur.ds;
;       const float dA = cur.sc.x, xq = cur.xq;
;       M0 = M0 * dA + xq * cur.B0.xy; M1 = M1 * dA + xq * cur.B0.zw;
;       M2 = M2 * dA + xq * cur.B1.xy; M3 = M3 * dA + xq * cur.B1.zw;
;       sy[(ng == 0 ? j * 16 : 0) + ysel] = y;
;       cur = nxt;
;     }
	v_pk_mul_f32 v[90:91], v[106:107], v[90:91]
	ds_read_b64 v[112:113], v157 offset:37296
	v_pk_fma_f32 v[88:89], v[104:105], v[88:89], v[90:91]
	v_pk_mul_f32 v[90:91], v[46:47], v[98:99]
	v_pk_fma_f32 v[90:91], v[108:109], v[96:97], v[90:91]
	v_pk_add_f32 v[88:89], v[88:89], v[90:91]
	v_add_f32_e32 v88, v88, v89
	s_nop 1
	v_add_f32_dpp v88, v88, v88 quad_perm:[1,0,3,2] row_mask:0xf bank_mask:0xf bound_ctrl:1
	s_nop 1
	v_add_f32_dpp v88, v88, v88 quad_perm:[2,3,0,1] row_mask:0xf bank_mask:0xf bound_ctrl:1
	s_nop 1
	v_add_f32_dpp v88, v88, v88 row_half_mirror row_mask:0xf bank_mask:0xf bound_ctrl:1
	s_nop 1
	v_add_f32_dpp v88, v88, v88 row_mirror row_mask:0xf bank_mask:0xf bound_ctrl:1
	v_mul_f32_e32 v88, v110, v88
	v_fmac_f32_e32 v88, v8, v111
	v_add_f32_e32 v90, v114, v88
	v_pk_mul_f32 v[88:89], v[104:105], v[110:111] op_sel_hi:[1,0]
	ds_write_b32 v74, v90 offset:38400
	v_pk_fma_f32 v[104:105], v[22:23], v[8:9], v[88:89] op_sel_hi:[1,0,1]
	v_pk_mul_f32 v[22:23], v[106:107], v[110:111] op_sel_hi:[1,0]
	v_pk_fma_f32 v[106:107], v[24:25], v[8:9], v[22:23] op_sel_hi:[1,0,1]
	v_pk_mul_f32 v[22:23], v[108:109], v[110:111] op_sel_hi:[1,0]
	v_pk_fma_f32 v[108:109], v[38:39], v[8:9], v[22:23] op_sel_hi:[1,0,1]
	v_pk_mul_f32 v[22:23], v[46:47], v[110:111] op_sel_hi:[1,0]
	v_pk_fma_f32 v[46:47], v[40:41], v[8:9], v[22:23] op_sel_hi:[1,0,1]
	ds_read_b128 v[22:25], v59 offset:24832
	ds_read_b128 v[38:41], v59 offset:24848
	ds_read_b128 v[88:91], v59 offset:33024
	ds_read_b128 v[96:99], v59 offset:33040
	s_waitcnt lgkmcnt(4)
	v_pk_mul_f32 v[94:95], v[106:107], v[94:95]
	ds_read_b32 v8, v60 offset:35840
	v_pk_fma_f32 v[92:93], v[104:105], v[92:93], v[94:95]
	v_pk_mul_f32 v[94:95], v[46:47], v[102:103]
	ds_read_b32 v114, v60 offset:36864
	v_pk_fma_f32 v[94:95], v[108:109], v[100:101], v[94:95]
	ds_read_b64 v[110:111], v157 offset:37312
	v_pk_add_f32 v[92:93], v[92:93], v[94:95]
	v_add_f32_e32 v92, v92, v93
	s_nop 1
	v_add_f32_dpp v92, v92, v92 quad_perm:[1,0,3,2] row_mask:0xf bank_mask:0xf bound_ctrl:1
	s_nop 1
	v_add_f32_dpp v92, v92, v92 quad_perm:[2,3,0,1] row_mask:0xf bank_mask:0xf bound_ctrl:1
	s_nop 1
	v_add_f32_dpp v92, v92, v92 row_half_mirror row_mask:0xf bank_mask:0xf bound_ctrl:1
	s_nop 1
	v_add_f32_dpp v92, v92, v92 row_mirror row_mask:0xf bank_mask:0xf bound_ctrl:1
	v_mul_f32_e32 v92, v112, v92
	v_fmac_f32_e32 v92, v16, v113
	v_add_f32_e32 v94, v115, v92
	v_pk_mul_f32 v[92:93], v[104:105], v[112:113] op_sel_hi:[1,0]
	ds_write_b32 v75, v94 offset:38400
	v_pk_fma_f32 v[104:105], v[26:27], v[16:17], v[92:93] op_sel_hi:[1,0,1]
	v_pk_mul_f32 v[26:27], v[106:107], v[112:113] op_sel_hi:[1,0]
	v_pk_fma_f32 v[106:107], v[28:29], v[16:17], v[26:27] op_sel_hi:[1,0,1]
	v_pk_mul_f32 v[26:27], v[108:109], v[112:113] op_sel_hi:[1,0]
	v_pk_fma_f32 v[108:109], v[42:43], v[16:17], v[26:27] op_sel_hi:[1,0,1]
	v_pk_mul_f32 v[26:27], v[46:47], v[112:113] op_sel_hi:[1,0]
	v_pk_fma_f32 v[46:47], v[44:45], v[16:17], v[26:27] op_sel_hi:[1,0,1]
	ds_read_b128 v[26:29], v59 offset:25344
	ds_read_b128 v[42:45], v59 offset:25360
	ds_read_b128 v[92:95], v59 offset:33536
	ds_read_b128 v[100:103], v59 offset:33552
	ds_read_b32 v16, v60 offset:35904
	ds_read_b32 v116, v60 offset:36928
	s_waitcnt lgkmcnt(6)
	v_pk_mul_f32 v[90:91], v[106:107], v[90:91]
	ds_read_b64 v[112:113], v157 offset:37328
	v_pk_fma_f32 v[88:89], v[104:105], v[88:89], v[90:91]
	v_pk_mul_f32 v[90:91], v[46:47], v[98:99]
	v_pk_fma_f32 v[90:91], v[108:109], v[96:97], v[90:91]
	v_pk_add_f32 v[88:89], v[88:89], v[90:91]
	v_pk_mul_f32 v[46:47], v[46:47], v[110:111] op_sel_hi:[1,0]
	v_add_f32_e32 v88, v88, v89
	v_pk_fma_f32 v[40:41], v[40:41], v[8:9], v[46:47] op_sel_hi:[1,0,1]
	s_nop 0
	v_add_f32_dpp v88, v88, v88 quad_perm:[1,0,3,2] row_mask:0xf bank_mask:0xf bound_ctrl:1
	s_nop 1
	v_add_f32_dpp v88, v88, v88 quad_perm:[2,3,0,1] row_mask:0xf bank_mask:0xf bound_ctrl:1
	s_nop 1
	v_add_f32_dpp v88, v88, v88 row_half_mirror row_mask:0xf bank_mask:0xf bound_ctrl:1
	s_nop 1
	v_add_f32_dpp v88, v88, v88 row_mirror row_mask:0xf bank_mask:0xf bound_ctrl:1
	v_mul_f32_e32 v88, v110, v88
	v_fmac_f32_e32 v88, v8, v111
	v_add_f32_e32 v90, v114, v88
	v_pk_mul_f32 v[88:89], v[104:105], v[110:111] op_sel_hi:[1,0]
	ds_write_b32 v76, v90 offset:38400
	v_pk_fma_f32 v[22:23], v[22:23], v[8:9], v[88:89] op_sel_hi:[1,0,1]
	v_pk_mul_f32 v[88:89], v[106:107], v[110:111] op_sel_hi:[1,0]
	v_pk_fma_f32 v[24:25], v[24:25], v[8:9], v[88:89] op_sel_hi:[1,0,1]
	v_pk_mul_f32 v[88:89], v[108:109], v[110:111] op_sel_hi:[1,0]
	v_pk_fma_f32 v[38:39], v[38:39], v[8:9], v[88:89] op_sel_hi:[1,0,1]
	ds_read_b128 v[88:91], v59 offset:25856
	ds_read_b128 v[96:99], v59 offset:25872
	ds_read_b128 v[104:107], v59 offset:34048
	ds_read_b128 v[108:111], v59 offset:34064
	ds_read_b32 v46, v60 offset:35968
	ds_read_b32 v47, v60 offset:36992
	s_waitcnt lgkmcnt(6)
; DI float bf2f(bf16_t h) { return __uint_as_float(((unsigned)h) << 16); }
; DI float siluf(float x) { return x * sigmf(x); }
; DI float row16_sum(float v) { v += dppf(v, 0); v += dppf(v, 1); v += dppf(v, 2); v += dppf(v, 3); return v; }
; DI void mamba_scan(CP p, const Ptrs& w, int l, int item, float* sm) {
;     ...
;   auto stage = [&](const MPre& P, float* bufp) {
; #pragma unroll
;     for (int i = 0; i < 2; ++i) {
;       int idx = tid + 256 * i, j = idx >> 5, q = idx & 31;
;       float f[8];
;       unpack8(P.pbq[i], f);
;       float* d = bufp + (q < 16 ? 0 : 2048) + j * 128 + (q & 15) * 8;
;       *(float4*)d = make_float4(f[0], f[1], f[2], f[3]);
;       *(float4*)(d + 4) = make_float4(f[4], f[5], f[6], f[7]);
;     }
;     {
;       float xs = siluf(wX0 * P.pxm[0] * bf2f(P.px[0]) + wX1 * bf2f(P.px[1]) + wX2 * P.pxm[1] * bf2f(P.px[2]) + bX);
;       bufp[4096 + xj * 16 + xp] = xs * P.pdt[0];
;       bufp[4096 + 256 + xj * 16 + xp] = Dsk * xs;
;       if (xp == 0) *(float4*)(bufp + 4096 + 512 + xj * 4) = make_float4(P.pdt[1], P.pdt[2], 0.f, 0.f);
;     }
;     ...
;   auto run_chunk = [&](int c, const float* bf, float* sy) {
;     flush(max(c - 1, 0));
;     MStep cur = lds_step(bf, 0);
; #pragma unroll
;     for (int j = 0; j < 16; ++j) {
;       MStep nxt = cur;
;       if (j + 1 < 16) nxt = lds_step(bf, j + 1);
;       f2v ya = M0 * cur.C0.xy + M1 * cur.C0.zw, yb = M2 * cur.C1.xy + M3 * cur.C1.zw;
;       ya += yb;
;       float yp = row16_sum(ya.x + ya.y);
;       float y = cur.sc.x * yp + cur.xq * cur.sc.y + cur.ds;
;       const float dA = cur.sc.x, xq = cur.xq;
;       M0 = M0 * dA + xq * cur.B0.xy; M1 = M1 * dA + xq * cur.B0.zw;
;       M2 = M2 * dA + xq * cur.B1.xy; M3 = M3 * dA + xq * cur.B1.zw;
;       sy[(ng == 0 ? j * 16 : 0) + ysel] = y;
;       cur = nxt;
	v_pk_mul_f32 v[94:95], v[24:25], v[94:95]
	ds_read_b64 v[114:115], v157 offset:37344
	v_pk_fma_f32 v[92:93], v[22:23], v[92:93], v[94:95]
	v_pk_mul_f32 v[94:95], v[40:41], v[102:103]
	v_pk_fma_f32 v[94:95], v[38:39], v[100:101], v[94:95]
	v_pk_mul_f32 v[22:23], v[22:23], v[112:113] op_sel_hi:[1,0]
	v_pk_add_f32 v[92:93], v[92:93], v[94:95]
	v_add_f32_e32 v8, v92, v93
	s_nop 1
	v_add_f32_dpp v8, v8, v8 quad_perm:[1,0,3,2] row_mask:0xf bank_mask:0xf bound_ctrl:1
	s_nop 1
	v_add_f32_dpp v8, v8, v8 quad_perm:[2,3,0,1] row_mask:0xf bank_mask:0xf bound_ctrl:1
	s_nop 1
	v_add_f32_dpp v8, v8, v8 row_half_mirror row_mask:0xf bank_mask:0xf bound_ctrl:1
	s_nop 1
	v_add_f32_dpp v8, v8, v8 row_mirror row_mask:0xf bank_mask:0xf bound_ctrl:1
	v_mul_f32_e32 v8, v112, v8
	v_fmac_f32_e32 v8, v16, v113
	v_add_f32_e32 v8, v116, v8
	v_pk_fma_f32 v[116:117], v[26:27], v[16:17], v[22:23] op_sel_hi:[1,0,1]
	v_pk_mul_f32 v[22:23], v[24:25], v[112:113] op_sel_hi:[1,0]
	ds_write_b32 v77, v8 offset:38400
	v_pk_fma_f32 v[118:119], v[28:29], v[16:17], v[22:23] op_sel_hi:[1,0,1]
	v_pk_mul_f32 v[22:23], v[38:39], v[112:113] op_sel_hi:[1,0]
	ds_read_b128 v[26:29], v59 offset:26368
	v_pk_fma_f32 v[120:121], v[42:43], v[16:17], v[22:23] op_sel_hi:[1,0,1]
	v_pk_mul_f32 v[22:23], v[40:41], v[112:113] op_sel_hi:[1,0]
	v_pk_fma_f32 v[112:113], v[44:45], v[16:17], v[22:23] op_sel_hi:[1,0,1]
	ds_read_b128 v[22:25], v59 offset:26384
	ds_read_b128 v[92:95], v59 offset:34560
	ds_read_b128 v[100:103], v59 offset:34576
	ds_read_b32 v8, v60 offset:36032
	ds_read_b32 v16, v60 offset:37056
	s_waitcnt lgkmcnt(6)
	v_pk_mul_f32 v[40:41], v[118:119], v[106:107]
	ds_read_b64 v[38:39], v157 offset:37360
	v_pk_mul_f32 v[42:43], v[112:113], v[110:111]
	v_pk_fma_f32 v[40:41], v[116:117], v[104:105], v[40:41]
	v_pk_fma_f32 v[42:43], v[120:121], v[108:109], v[42:43]
	v_pk_add_f32 v[40:41], v[40:41], v[42:43]
	v_add_f32_e32 v40, v40, v41
	s_nop 1
	v_add_f32_dpp v40, v40, v40 quad_perm:[1,0,3,2] row_mask:0xf bank_mask:0xf bound_ctrl:1
	s_nop 1
	v_add_f32_dpp v40, v40, v40 quad_perm:[2,3,0,1] row_mask:0xf bank_mask:0xf bound_ctrl:1
	s_nop 1
	v_add_f32_dpp v40, v40, v40 row_half_mirror row_mask:0xf bank_mask:0xf bound_ctrl:1
	s_nop 1
	v_add_f32_dpp v40, v40, v40 row_mirror row_mask:0xf bank_mask:0xf bound_ctrl:1
	v_mul_f32_e32 v40, v114, v40
	v_fmac_f32_e32 v40, v46, v115
	v_add_f32_e32 v104, v47, v40
	v_pk_mul_f32 v[40:41], v[116:117], v[114:115] op_sel_hi:[1,0]
	ds_write_b32 v78, v104 offset:38400
	v_pk_fma_f32 v[42:43], v[88:89], v[46:47], v[40:41] op_sel_hi:[1,0,1]
	v_pk_mul_f32 v[40:41], v[118:119], v[114:115] op_sel_hi:[1,0]
	v_pk_mul_f32 v[88:89], v[112:113], v[114:115] op_sel_hi:[1,0]
	v_pk_fma_f32 v[44:45], v[90:91], v[46:47], v[40:41] op_sel_hi:[1,0,1]
	v_pk_mul_f32 v[40:41], v[120:121], v[114:115] op_sel_hi:[1,0]
	v_pk_fma_f32 v[40:41], v[96:97], v[46:47], v[40:41] op_sel_hi:[1,0,1]
	v_pk_fma_f32 v[46:47], v[98:99], v[46:47], v[88:89] op_sel_hi:[1,0,1]
	s_waitcnt lgkmcnt(1)
	v_pk_mul_f32 v[88:89], v[44:45], v[94:95]
	v_pk_mul_f32 v[90:91], v[46:47], v[102:103]
	v_pk_fma_f32 v[88:89], v[42:43], v[92:93], v[88:89]
	v_pk_fma_f32 v[90:91], v[40:41], v[100:101], v[90:91]
	s_waitcnt vmcnt(8)
	v_lshlrev_b32_e32 v94, 16, v21
	v_pk_add_f32 v[88:89], v[88:89], v[90:91]
	v_and_b32_e32 v95, 0xffff0000, v21
	v_add_f32_e32 v88, v88, v89
	v_lshlrev_b32_e32 v21, 16, v85
	v_lshlrev_b32_e32 v90, 16, v19
	v_add_f32_dpp v88, v88, v88 quad_perm:[1,0,3,2] row_mask:0xf bank_mask:0xf bound_ctrl:1
	v_and_b32_e32 v91, 0xffff0000, v19
	v_lshlrev_b32_e32 v19, 16, v84
	v_add_f32_dpp v88, v88, v88 quad_perm:[2,3,0,1] row_mask:0xf bank_mask:0xf bound_ctrl:1
	v_mul_f32_e32 v21, v50, v21
	v_and_b32_e32 v89, 0xffff0000, v18
	v_add_f32_dpp v88, v88, v88 row_half_mirror row_mask:0xf bank_mask:0xf bound_ctrl:1
	v_lshlrev_b32_e32 v92, 16, v20
	v_and_b32_e32 v93, 0xffff0000, v20
	v_add_f32_dpp v88, v88, v88 row_mirror row_mask:0xf bank_mask:0xf bound_ctrl:1
	s_waitcnt lgkmcnt(1)
	v_mul_f32_e32 v88, v38, v88
	v_fmac_f32_e32 v88, v8, v39
	v_add_f32_e32 v16, v16, v88
	ds_write_b32 v80, v16 offset:38400
	v_mul_f32_e32 v16, v49, v87
	v_fmac_f32_e32 v21, v16, v19
	v_mul_f32_e32 v16, v51, v86
	v_lshlrev_b32_e32 v19, 16, v83
	v_fmac_f32_e32 v21, v16, v19
	v_add_f32_e32 v16, v52, v21
	v_mul_f32_e32 v19, 0xbfb8aa3b, v16
	v_exp_f32_e32 v39, v19
	v_lshlrev_b32_e32 v88, 16, v18
	v_lshlrev_b32_e32 v18, 16, v12
	v_and_b32_e32 v19, 0xffff0000, v12
	v_add_f32_e32 v12, 1.0, v39
	v_rcp_f32_e32 v12, v12
	ds_write_b128 v58, v[92:95] offset:16
	ds_write_b128 v58, v[88:91]
	v_lshlrev_b32_e32 v20, 16, v13
	v_lshlrev_b32_e32 v90, 16, v15
	v_mul_f32_e32 v12, v16, v12
	v_lshlrev_b32_e32 v88, 16, v14
	v_and_b32_e32 v21, 0xffff0000, v13
	v_and_b32_e32 v91, 0xffff0000, v15
	v_and_b32_e32 v89, 0xffff0000, v14
	v_mul_f32_e32 v13, v36, v12
	v_mul_f32_e32 v12, v53, v12
	ds_write_b128 v58, v[88:91] offset:4112
	ds_write_b128 v58, v[18:21] offset:4096
	ds_write2st64_b32 v57, v13, v12 offset0:64 offset1:68
	s_and_saveexec_b64 s[4:5], vcc
	s_cbranch_execz .LBB0_543
	v_mov_b32_e32 v16, v37
	v_mov_b32_e32 v18, v157
	v_mov_b32_e32 v19, v157
	ds_write_b128 v72, v[16:19] offset:18432
	s_branch .LBB0_543

; DI float row16_sum(float v) { v += dppf(v, 0); v += dppf(v, 1); v += dppf(v, 2); v += dppf(v, 3); return v; }
; DI void rwkv_scan(CP p, const Ptrs& w, int l, int item, float* sm) {
;     ...
;   auto load = [&](int c, RPre& P) {
;     int ii = pos2i(c * 16 + sj, dir);
;     size_t tok = (size_t)b * TPB + ii;
;     const bf16_t* prow = w.pB + tok * SPB + sc_;
;     bool hp = (ii != 0) && (ii != CTXL), hn = (ii != CTXL - 1) && (ii != TPB - 1);
;     const int op = hp ? -SPB : 0, on = hn ? SPB : 0;
;     P.pmk[0] = hp ? 0.5f : 0.f; P.pmk[1] = hn ? 0.5f : 0.f;
; #pragma unroll
;     for (int q = 0; q < 3; ++q) {
;       P.pq[q][0] = *(const uint2*)(prow + q * 512);
;       P.pq[q][1] = *(const uint2*)(prow + q * 512 + op);
;       P.pq[q][2] = *(const uint2*)(prow + q * 512 + on);
;     }
;     P.pwd = *(const uint2*)(Wd + tok * 512 + sc_);
;     P.pad_ = *(const uint2*)(Ad + tok * 512 + sc_);
;     const float* sc = w.bonus + (tok * 8 + hd) * 8;
;     P.psc[0] = sc[0]; P.psc[1] = sc[1 + 3 * dir]; P.psc[2] = sc[2 + 3 * dir];
;   };
;     ...
;   auto flush = [&](int c) {
;     {
;       int j = tid >> 4, rr = tid & 15;
;       int ii = pos2i(c * 16 + j, dir);
;       yout[((size_t)b * TPB + ii) * 512 + hd * 64 + rq * 16 + rr] = f2bf(sY[(c & 1) * 256 + j * 16 + rr]);
;     }
;   };
;   __syncthreads();
;   load(0, PA);
;   stage(PA, sm);
;   load(1, PB);
;   __syncthreads();
;   const int NCH = TPB / 16;
;   auto run_chunk = [&](int c, const float* bf, float* sy) {
;     flush(max(c - 1, 0));
;     RStep cur = lds_step(bf, 0);
; #pragma unroll
;     for (int j = 0; j < 16; ++j) {
;       RStep nxt = cur;
;       if (j + 1 < 16) nxt = lds_step(bf, j + 1);
;       f2v sa2 = SA * cur.a4.xy + SB * cur.a4.zw;
;       f2v yp2 = SA * cur.wr4.xy + SB * cur.wr4.zw;
;       float sa = sa2.x + sa2.y, yp = yp2.x + yp2.y;
;       sa = row16_sum(sa); yp = row16_sum(yp);
;       float y = yp + sa * cur.sc.x + cur.vv * cur.sc.y;
;       SA = SA * cur.w4.xy + (sa * cur.b4.xy + cur.vv * cur.k4.xy);
;       SB = SB * cur.w4.zw + (sa * cur.b4.zw + cur.vv * cur.k4.zw);
;       sy[(kg == 0 ? j * 16 : 0) + ysel - (c & 1) * 0] = y;
.LBB0_554:
	s_min_u32 s4, s38, 1
	s_lshl_b32 s5, s4, 8
	s_lshl_b32 s46, s4, 4
	s_add_i32 s4, s17, 4
	s_min_u32 s4, s4, 0x20f
	v_lshl_add_u32 v24, s4, 4, v97
	s_sub_i32 s39, s16, s5
	v_cmp_lt_i32_e64 s[4:5], s37, v24
	s_nop 1
	v_cndmask_b32_e64 v25, v231, v232, s[4:5]
	v_sub_u32_e32 v25, v25, v24
	v_cndmask_b32_e32 v24, v25, v24, vcc
	v_ashrrev_i32_e32 v25, 31, v24
	v_lshl_add_u64 v[26:27], s[12:13], 0, v[24:25]
	v_mad_u64_u32 v[28:29], s[4:5], v26, s20, v[42:43]
	v_mov_b32_e32 v30, v29
	v_mad_u64_u32 v[30:31], s[4:5], v27, s20, v[30:31]
	v_and_b32_e32 v25, 0xfffffeff, v24
	v_mov_b32_e32 v29, v30
	v_and_b32_e32 v30, 0xffffdfff, v24
	v_cmp_eq_u32_e64 s[42:43], 0, v25
	v_cmp_eq_u32_e64 s[44:45], s37, v30
	s_and_b32 s4, s39, 0x100
	v_cndmask_b32_e64 v25, -1, 0, s[42:43]
	v_cndmask_b32_e64 v24, v236, 0, s[42:43]
	v_cndmask_b32_e64 v156, v237, 0, s[44:45]
	v_lshl_add_u64 v[24:25], v[28:29], 0, v[24:25]
	v_lshl_add_u64 v[30:31], v[28:29], 0, v[156:157]
	global_load_dwordx2 v[88:89], v[28:29], off
	global_load_dwordx2 v[86:87], v[28:29], off offset:1024
	global_load_dwordx2 v[84:85], v[28:29], off offset:2048
	global_load_dwordx2 v[74:75], v[24:25], off
	global_load_dwordx2 v[76:77], v[30:31], off
	global_load_dwordx2 v[78:79], v[24:25], off offset:1024
	global_load_dwordx2 v[70:71], v[24:25], off offset:2048
	v_lshlrev_b64 v[24:25], 10, v[26:27]
	v_lshl_add_u64 v[28:29], v[34:35], 0, v[24:25]
	v_lshl_add_u64 v[24:25], v[36:37], 0, v[24:25]
	global_load_dwordx2 v[80:81], v[30:31], off offset:1024
	global_load_dwordx2 v[72:73], v[30:31], off offset:2048
	global_load_dwordx2 v[92:93], v[28:29], off
	global_load_dwordx2 v[90:91], v[24:25], off
	v_lshlrev_b64 v[24:25], 8, v[26:27]
	v_lshl_add_u64 v[24:25], s[6:7], 0, v[24:25]
	v_lshl_add_u64 v[26:27], v[24:25], 0, s[90:91]
	global_load_dword v82, v[24:25], off
	global_load_dwordx2 v[68:69], v[26:27], off offset:4
	v_lshl_add_u32 v25, s4, 2, v83
	v_subrev_u32_e32 v24, s46, v125
	ds_read_b32 v25, v25 offset:49408
	v_cmp_lt_i32_e64 s[4:5], s37, v24
	ds_read2st64_b32 v[154:155], v106 offset0:80 offset1:81
	s_nop 0
	v_cndmask_b32_e64 v26, v231, v232, s[4:5]
	v_add3_u32 v26, v26, v124, s46
	v_cndmask_b32_e32 v24, v26, v24, vcc
	s_waitcnt lgkmcnt(1)
	v_cvt_pk_bf16_f32 v26, v25, s0
	v_ashrrev_i32_e32 v25, 31, v24
	v_lshl_add_u64 v[24:25], s[12:13], 0, v[24:25]
	v_lshlrev_b64 v[24:25], 10, v[24:25]
	v_lshl_add_u64 v[24:25], v[38:39], 0, v[24:25]
	global_store_short v[24:25], v26, off
	s_waitcnt lgkmcnt(0)
	v_add_u32_e64 v24, s21, 0
	ds_read2_b64 v[24:27], v24 offset1:1
	ds_read_b128 v[28:31], v105
	ds_read_b128 v[98:101], v105 offset:256
	ds_read_b128 v[126:129], v105 offset:4096
	ds_read_b128 v[130:133], v105 offset:4352
	ds_read_b128 v[134:137], v105 offset:8192
	ds_read_b128 v[138:141], v105 offset:8448
	ds_read_b128 v[142:145], v105 offset:12288
	ds_read_b128 v[146:149], v105 offset:12544
	ds_read_b128 v[150:153], v105 offset:16384
	ds_read_b128 v[168:171], v105 offset:16640
	s_waitcnt lgkmcnt(9)
	v_pk_mul_f32 v[30:31], v[22:23], v[30:31]
	v_pk_fma_f32 v[28:29], v[20:21], v[28:29], v[30:31]
	v_add_f32_e32 v28, v28, v29
	s_waitcnt lgkmcnt(7)
	v_pk_mul_f32 v[30:31], v[22:23], v[128:129]
	v_pk_fma_f32 v[30:31], v[20:21], v[126:127], v[30:31]
	v_add_f32_dpp v28, v28, v28 quad_perm:[1,0,3,2] row_mask:0xf bank_mask:0xf bound_ctrl:1
	v_add_f32_e32 v29, v30, v31
	s_nop 0
	v_add_f32_dpp v28, v28, v28 quad_perm:[2,3,0,1] row_mask:0xf bank_mask:0xf bound_ctrl:1
	v_add_f32_dpp v29, v29, v29 quad_perm:[1,0,3,2] row_mask:0xf bank_mask:0xf bound_ctrl:1
	s_nop 0
	v_add_f32_dpp v28, v28, v28 row_half_mirror row_mask:0xf bank_mask:0xf bound_ctrl:1
	v_add_f32_dpp v29, v29, v29 quad_perm:[2,3,0,1] row_mask:0xf bank_mask:0xf bound_ctrl:1
	s_nop 0
	v_add_f32_dpp v28, v28, v28 row_mirror row_mask:0xf bank_mask:0xf bound_ctrl:1
	v_add_f32_dpp v29, v29, v29 row_half_mirror row_mask:0xf bank_mask:0xf bound_ctrl:1
	s_nop 1
	v_add_f32_dpp v29, v29, v29 row_mirror row_mask:0xf bank_mask:0xf bound_ctrl:1
	v_fmac_f32_e32 v29, v24, v28
	v_fmac_f32_e32 v29, v154, v25
	s_waitcnt lgkmcnt(0)
	v_pk_mul_f32 v[24:25], v[142:143], v[28:29] op_sel_hi:[1,0]
	ds_write_b32 v107, v29 offset:49408
	v_pk_fma_f32 v[24:25], v[150:151], v[154:155], v[24:25] op_sel_hi:[1,0,1]
	v_pk_fma_f32 v[24:25], v[20:21], v[134:135], v[24:25]
	v_pk_mul_f32 v[20:21], v[144:145], v[28:29] op_sel_hi:[1,0]
	v_pk_fma_f32 v[20:21], v[152:153], v[154:155], v[20:21] op_sel_hi:[1,0,1]
	v_pk_fma_f32 v[150:151], v[22:23], v[136:137], v[20:21]
	ds_read_b128 v[20:23], v105 offset:512
	v_pk_mul_f32 v[100:101], v[100:101], v[150:151]
	ds_read_b128 v[28:31], v105 offset:4608
	v_pk_fma_f32 v[98:99], v[98:99], v[24:25], v[100:101]
	v_pk_mul_f32 v[100:101], v[132:133], v[150:151]
	ds_read_b128 v[126:129], v105 offset:8704
	v_pk_fma_f32 v[100:101], v[130:131], v[24:25], v[100:101]
	v_add_f32_e32 v98, v98, v99
	ds_read_b128 v[134:137], v105 offset:12800
	v_add_f32_e32 v99, v100, v101
	v_add_f32_dpp v98, v98, v98 quad_perm:[1,0,3,2] row_mask:0xf bank_mask:0xf bound_ctrl:1
	ds_read_b128 v[142:145], v105 offset:16896
	v_add_f32_dpp v99, v99, v99 quad_perm:[1,0,3,2] row_mask:0xf bank_mask:0xf bound_ctrl:1
	v_add_f32_dpp v98, v98, v98 quad_perm:[2,3,0,1] row_mask:0xf bank_mask:0xf bound_ctrl:1
	v_mov_b32_e32 v100, v155
	v_add_f32_dpp v99, v99, v99 quad_perm:[2,3,0,1] row_mask:0xf bank_mask:0xf bound_ctrl:1
	v_add_f32_dpp v98, v98, v98 row_half_mirror row_mask:0xf bank_mask:0xf bound_ctrl:1
	ds_read_b32 v96, v106 offset:20992
	v_add_f32_dpp v99, v99, v99 row_half_mirror row_mask:0xf bank_mask:0xf bound_ctrl:1
	v_add_f32_dpp v98, v98, v98 row_mirror row_mask:0xf bank_mask:0xf bound_ctrl:1
	ds_read_b64 v[152:153], v157 offset:24592
	v_add_f32_dpp v99, v99, v99 row_mirror row_mask:0xf bank_mask:0xf bound_ctrl:1
	v_fmac_f32_e32 v99, v98, v26
	v_fmac_f32_e32 v99, v155, v27
	v_pk_mul_f32 v[26:27], v[146:147], v[98:99] op_sel_hi:[1,0]
	ds_write_b32 v108, v99 offset:49408
	v_pk_fma_f32 v[26:27], v[168:169], v[100:101], v[26:27] op_sel_hi:[1,0,1]
	v_pk_fma_f32 v[154:155], v[138:139], v[24:25], v[26:27]
	v_pk_mul_f32 v[24:25], v[148:149], v[98:99] op_sel_hi:[1,0]
	v_pk_fma_f32 v[24:25], v[170:171], v[100:101], v[24:25] op_sel_hi:[1,0,1]
	v_pk_fma_f32 v[150:151], v[140:141], v[150:151], v[24:25]
	ds_read_b128 v[24:27], v105 offset:768
	ds_read_b128 v[98:101], v105 offset:4864
	ds_read_b128 v[130:133], v105 offset:8960
	ds_read_b128 v[138:141], v105 offset:13056
	ds_read_b128 v[146:149], v105 offset:17152
	ds_read_b32 v102, v106 offset:21248
	s_waitcnt lgkmcnt(14)
; DI float row16_sum(float v) { v += dppf(v, 0); v += dppf(v, 1); v += dppf(v, 2); v += dppf(v, 3); return v; }
; DI void rwkv_scan(CP p, const Ptrs& w, int l, int item, float* sm) {
;     ...
;     RStep cur = lds_step(bf, 0);
; #pragma unroll
;     for (int j = 0; j < 16; ++j) {
;       RStep nxt = cur;
;       if (j + 1 < 16) nxt = lds_step(bf, j + 1);
;       f2v sa2 = SA * cur.a4.xy + SB * cur.a4.zw;
;       f2v yp2 = SA * cur.wr4.xy + SB * cur.wr4.zw;
;       float sa = sa2.x + sa2.y, yp = yp2.x + yp2.y;
;       sa = row16_sum(sa); yp = row16_sum(yp);
;       float y = yp + sa * cur.sc.x + cur.vv * cur.sc.y;
;       SA = SA * cur.w4.xy + (sa * cur.b4.xy + cur.vv * cur.k4.xy);
;       SB = SB * cur.w4.zw + (sa * cur.b4.zw + cur.vv * cur.k4.zw);
;       sy[(kg == 0 ? j * 16 : 0) + ysel - (c & 1) * 0] = y;
;       cur = nxt;
	ds_read_b64 v[168:169], v157 offset:24600
	s_waitcnt lgkmcnt(7)
	v_pk_mul_f32 v[22:23], v[22:23], v[150:151]
	v_pk_fma_f32 v[20:21], v[20:21], v[154:155], v[22:23]
	v_pk_mul_f32 v[22:23], v[30:31], v[150:151]
	v_add_f32_e32 v20, v20, v21
	v_pk_fma_f32 v[22:23], v[28:29], v[154:155], v[22:23]
	v_add_f32_e32 v21, v22, v23
	v_add_f32_dpp v20, v20, v20 quad_perm:[1,0,3,2] row_mask:0xf bank_mask:0xf bound_ctrl:1
	s_nop 0
	v_add_f32_dpp v21, v21, v21 quad_perm:[1,0,3,2] row_mask:0xf bank_mask:0xf bound_ctrl:1
	v_add_f32_dpp v20, v20, v20 quad_perm:[2,3,0,1] row_mask:0xf bank_mask:0xf bound_ctrl:1
	s_nop 0
	v_add_f32_dpp v21, v21, v21 quad_perm:[2,3,0,1] row_mask:0xf bank_mask:0xf bound_ctrl:1
	v_add_f32_dpp v20, v20, v20 row_half_mirror row_mask:0xf bank_mask:0xf bound_ctrl:1
	s_nop 0
	v_add_f32_dpp v21, v21, v21 row_half_mirror row_mask:0xf bank_mask:0xf bound_ctrl:1
	v_add_f32_dpp v20, v20, v20 row_mirror row_mask:0xf bank_mask:0xf bound_ctrl:1
	v_pk_mul_f32 v[22:23], v[134:135], v[20:21] op_sel_hi:[1,0]
	v_add_f32_dpp v28, v21, v21 row_mirror row_mask:0xf bank_mask:0xf bound_ctrl:1
	v_pk_fma_f32 v[22:23], v[142:143], v[96:97], v[22:23] op_sel_hi:[1,0,1]
	v_fmac_f32_e32 v28, v20, v152
	v_pk_mul_f32 v[20:21], v[136:137], v[20:21] op_sel_hi:[1,0]
	v_fmac_f32_e32 v28, v96, v153
	v_pk_fma_f32 v[20:21], v[144:145], v[96:97], v[20:21] op_sel_hi:[1,0,1]
	v_pk_fma_f32 v[152:153], v[126:127], v[154:155], v[22:23]
	ds_write_b32 v109, v28 offset:49408
	v_pk_fma_f32 v[150:151], v[128:129], v[150:151], v[20:21]
	ds_read_b128 v[20:23], v105 offset:1024
	ds_read_b128 v[28:31], v105 offset:5120
	ds_read_b128 v[126:129], v105 offset:9216
	ds_read_b128 v[134:137], v105 offset:13312
	ds_read_b128 v[142:145], v105 offset:17408
	ds_read_b32 v96, v106 offset:21504
	ds_read_b64 v[154:155], v157 offset:24608
	s_waitcnt lgkmcnt(8)
	v_pk_mul_f32 v[26:27], v[26:27], v[150:151]
	v_pk_fma_f32 v[24:25], v[24:25], v[152:153], v[26:27]
	v_pk_mul_f32 v[26:27], v[100:101], v[150:151]
	v_add_f32_e32 v24, v24, v25
	v_pk_fma_f32 v[26:27], v[98:99], v[152:153], v[26:27]
	v_add_f32_e32 v25, v26, v27
	v_add_f32_dpp v24, v24, v24 quad_perm:[1,0,3,2] row_mask:0xf bank_mask:0xf bound_ctrl:1
	s_nop 0
	v_add_f32_dpp v25, v25, v25 quad_perm:[1,0,3,2] row_mask:0xf bank_mask:0xf bound_ctrl:1
	v_add_f32_dpp v24, v24, v24 quad_perm:[2,3,0,1] row_mask:0xf bank_mask:0xf bound_ctrl:1
	s_nop 0
	v_add_f32_dpp v25, v25, v25 quad_perm:[2,3,0,1] row_mask:0xf bank_mask:0xf bound_ctrl:1
	v_add_f32_dpp v24, v24, v24 row_half_mirror row_mask:0xf bank_mask:0xf bound_ctrl:1
	s_nop 0
	v_add_f32_dpp v25, v25, v25 row_half_mirror row_mask:0xf bank_mask:0xf bound_ctrl:1
	v_add_f32_dpp v24, v24, v24 row_mirror row_mask:0xf bank_mask:0xf bound_ctrl:1
	v_pk_mul_f32 v[26:27], v[138:139], v[24:25] op_sel_hi:[1,0]
	v_add_f32_dpp v98, v25, v25 row_mirror row_mask:0xf bank_mask:0xf bound_ctrl:1
	v_pk_fma_f32 v[26:27], v[146:147], v[102:103], v[26:27] op_sel_hi:[1,0,1]
	v_fmac_f32_e32 v98, v24, v168
	v_pk_mul_f32 v[24:25], v[140:141], v[24:25] op_sel_hi:[1,0]
	v_pk_fma_f32 v[152:153], v[130:131], v[152:153], v[26:27]
	v_fmac_f32_e32 v98, v102, v169
	v_pk_fma_f32 v[24:25], v[148:149], v[102:103], v[24:25] op_sel_hi:[1,0,1]
	ds_write_b32 v110, v98 offset:49408
	v_pk_fma_f32 v[150:151], v[132:133], v[150:151], v[24:25]
	ds_read_b128 v[24:27], v105 offset:1280
	ds_read_b128 v[98:101], v105 offset:5376
	ds_read_b128 v[130:133], v105 offset:9472
	ds_read_b128 v[138:141], v105 offset:13568
	ds_read_b128 v[146:149], v105 offset:17664
	ds_read_b32 v102, v106 offset:21760
	s_waitcnt lgkmcnt(14)
	ds_read_b64 v[168:169], v157 offset:24616
	s_waitcnt lgkmcnt(8)
	v_pk_mul_f32 v[22:23], v[22:23], v[150:151]
	v_pk_fma_f32 v[20:21], v[20:21], v[152:153], v[22:23]
	v_pk_mul_f32 v[22:23], v[30:31], v[150:151]
	v_add_f32_e32 v20, v20, v21
	v_pk_fma_f32 v[22:23], v[28:29], v[152:153], v[22:23]
	v_add_f32_e32 v21, v22, v23
	v_add_f32_dpp v20, v20, v20 quad_perm:[1,0,3,2] row_mask:0xf bank_mask:0xf bound_ctrl:1
	s_nop 0
	v_add_f32_dpp v21, v21, v21 quad_perm:[1,0,3,2] row_mask:0xf bank_mask:0xf bound_ctrl:1
	v_add_f32_dpp v20, v20, v20 quad_perm:[2,3,0,1] row_mask:0xf bank_mask:0xf bound_ctrl:1
	s_nop 0
	v_add_f32_dpp v21, v21, v21 quad_perm:[2,3,0,1] row_mask:0xf bank_mask:0xf bound_ctrl:1
	v_add_f32_dpp v20, v20, v20 row_half_mirror row_mask:0xf bank_mask:0xf bound_ctrl:1
	s_nop 0
	v_add_f32_dpp v21, v21, v21 row_half_mirror row_mask:0xf bank_mask:0xf bound_ctrl:1
	v_add_f32_dpp v20, v20, v20 row_mirror row_mask:0xf bank_mask:0xf bound_ctrl:1
	v_pk_mul_f32 v[22:23], v[134:135], v[20:21] op_sel_hi:[1,0]
	v_add_f32_dpp v28, v21, v21 row_mirror row_mask:0xf bank_mask:0xf bound_ctrl:1
	v_pk_fma_f32 v[22:23], v[142:143], v[96:97], v[22:23] op_sel_hi:[1,0,1]
	v_fmac_f32_e32 v28, v20, v154
	v_pk_mul_f32 v[20:21], v[136:137], v[20:21] op_sel_hi:[1,0]
	v_pk_fma_f32 v[152:153], v[126:127], v[152:153], v[22:23]
	v_fmac_f32_e32 v28, v96, v155
	v_pk_fma_f32 v[20:21], v[144:145], v[96:97], v[20:21] op_sel_hi:[1,0,1]
	ds_write_b32 v111, v28 offset:49408
	v_pk_fma_f32 v[150:151], v[128:129], v[150:151], v[20:21]
	ds_read_b128 v[20:23], v105 offset:1536
	ds_read_b128 v[28:31], v105 offset:5632
	ds_read_b128 v[126:129], v105 offset:9728
	ds_read_b128 v[134:137], v105 offset:13824
	ds_read_b128 v[142:145], v105 offset:17920
	ds_read_b32 v96, v106 offset:22016
	s_waitcnt lgkmcnt(14)
	ds_read_b64 v[154:155], v157 offset:24624
	s_waitcnt lgkmcnt(8)
; DI float row16_sum(float v) { v += dppf(v, 0); v += dppf(v, 1); v += dppf(v, 2); v += dppf(v, 3); return v; }
; DI void rwkv_scan(CP p, const Ptrs& w, int l, int item, float* sm) {
;     ...
;     RStep cur = lds_step(bf, 0);
; #pragma unroll
;     for (int j = 0; j < 16; ++j) {
;       RStep nxt = cur;
;       if (j + 1 < 16) nxt = lds_step(bf, j + 1);
;       f2v sa2 = SA * cur.a4.xy + SB * cur.a4.zw;
;       f2v yp2 = SA * cur.wr4.xy + SB * cur.wr4.zw;
;       float sa = sa2.x + sa2.y, yp = yp2.x + yp2.y;
;       sa = row16_sum(sa); yp = row16_sum(yp);
;       float y = yp + sa * cur.sc.x + cur.vv * cur.sc.y;
;       SA = SA * cur.w4.xy + (sa * cur.b4.xy + cur.vv * cur.k4.xy);
;       SB = SB * cur.w4.zw + (sa * cur.b4.zw + cur.vv * cur.k4.zw);
;       sy[(kg == 0 ? j * 16 : 0) + ysel - (c & 1) * 0] = y;
;       cur = nxt;
	v_pk_mul_f32 v[26:27], v[26:27], v[150:151]
	v_pk_fma_f32 v[24:25], v[24:25], v[152:153], v[26:27]
	v_pk_mul_f32 v[26:27], v[100:101], v[150:151]
	v_add_f32_e32 v24, v24, v25
	v_pk_fma_f32 v[26:27], v[98:99], v[152:153], v[26:27]
	v_add_f32_e32 v25, v26, v27
	v_add_f32_dpp v24, v24, v24 quad_perm:[1,0,3,2] row_mask:0xf bank_mask:0xf bound_ctrl:1
	s_nop 0
	v_add_f32_dpp v25, v25, v25 quad_perm:[1,0,3,2] row_mask:0xf bank_mask:0xf bound_ctrl:1
	v_add_f32_dpp v24, v24, v24 quad_perm:[2,3,0,1] row_mask:0xf bank_mask:0xf bound_ctrl:1
	s_nop 0
	v_add_f32_dpp v25, v25, v25 quad_perm:[2,3,0,1] row_mask:0xf bank_mask:0xf bound_ctrl:1
	v_add_f32_dpp v24, v24, v24 row_half_mirror row_mask:0xf bank_mask:0xf bound_ctrl:1
	s_nop 0
	v_add_f32_dpp v25, v25, v25 row_half_mirror row_mask:0xf bank_mask:0xf bound_ctrl:1
	v_add_f32_dpp v24, v24, v24 row_mirror row_mask:0xf bank_mask:0xf bound_ctrl:1
	v_pk_mul_f32 v[26:27], v[138:139], v[24:25] op_sel_hi:[1,0]
	v_add_f32_dpp v98, v25, v25 row_mirror row_mask:0xf bank_mask:0xf bound_ctrl:1
	v_pk_fma_f32 v[26:27], v[146:147], v[102:103], v[26:27] op_sel_hi:[1,0,1]
	v_fmac_f32_e32 v98, v24, v168
	v_pk_mul_f32 v[24:25], v[140:141], v[24:25] op_sel_hi:[1,0]
	v_pk_fma_f32 v[152:153], v[130:131], v[152:153], v[26:27]
	v_fmac_f32_e32 v98, v102, v169
	v_pk_fma_f32 v[24:25], v[148:149], v[102:103], v[24:25] op_sel_hi:[1,0,1]
	ds_write_b32 v112, v98 offset:49408
	v_pk_fma_f32 v[150:151], v[132:133], v[150:151], v[24:25]
	ds_read_b128 v[24:27], v105 offset:1792
	ds_read_b128 v[98:101], v105 offset:5888
	ds_read_b128 v[130:133], v105 offset:9984
	ds_read_b128 v[138:141], v105 offset:14080
	ds_read_b128 v[146:149], v105 offset:18176
	ds_read_b32 v102, v106 offset:22272
	s_waitcnt lgkmcnt(14)
	ds_read_b64 v[168:169], v157 offset:24632
	s_waitcnt lgkmcnt(8)
	v_pk_mul_f32 v[22:23], v[22:23], v[150:151]
	v_pk_fma_f32 v[20:21], v[20:21], v[152:153], v[22:23]
	v_pk_mul_f32 v[22:23], v[30:31], v[150:151]
	v_add_f32_e32 v20, v20, v21
	v_pk_fma_f32 v[22:23], v[28:29], v[152:153], v[22:23]
	v_add_f32_e32 v21, v22, v23
	v_add_f32_dpp v20, v20, v20 quad_perm:[1,0,3,2] row_mask:0xf bank_mask:0xf bound_ctrl:1
	s_nop 0
	v_add_f32_dpp v21, v21, v21 quad_perm:[1,0,3,2] row_mask:0xf bank_mask:0xf bound_ctrl:1
	v_add_f32_dpp v20, v20, v20 quad_perm:[2,3,0,1] row_mask:0xf bank_mask:0xf bound_ctrl:1
	s_nop 0
	v_add_f32_dpp v21, v21, v21 quad_perm:[2,3,0,1] row_mask:0xf bank_mask:0xf bound_ctrl:1
	v_add_f32_dpp v20, v20, v20 row_half_mirror row_mask:0xf bank_mask:0xf bound_ctrl:1
	s_nop 0
	v_add_f32_dpp v21, v21, v21 row_half_mirror row_mask:0xf bank_mask:0xf bound_ctrl:1
	v_add_f32_dpp v20, v20, v20 row_mirror row_mask:0xf bank_mask:0xf bound_ctrl:1
	v_pk_mul_f32 v[22:23], v[134:135], v[20:21] op_sel_hi:[1,0]
	v_add_f32_dpp v28, v21, v21 row_mirror row_mask:0xf bank_mask:0xf bound_ctrl:1
	v_pk_fma_f32 v[22:23], v[142:143], v[96:97], v[22:23] op_sel_hi:[1,0,1]
	v_fmac_f32_e32 v28, v20, v154
	v_pk_mul_f32 v[20:21], v[136:137], v[20:21] op_sel_hi:[1,0]
	v_pk_fma_f32 v[152:153], v[126:127], v[152:153], v[22:23]
	v_fmac_f32_e32 v28, v96, v155
	v_pk_fma_f32 v[20:21], v[144:145], v[96:97], v[20:21] op_sel_hi:[1,0,1]
	ds_write_b32 v113, v28 offset:49408
	v_pk_fma_f32 v[150:151], v[128:129], v[150:151], v[20:21]
	ds_read_b128 v[20:23], v105 offset:2048
	ds_read_b128 v[28:31], v105 offset:6144
	ds_read_b128 v[126:129], v105 offset:10240
	ds_read_b128 v[134:137], v105 offset:14336
	ds_read_b128 v[142:145], v105 offset:18432
	ds_read_b32 v96, v106 offset:22528
	s_waitcnt lgkmcnt(14)
	ds_read_b64 v[154:155], v157 offset:24640
	s_waitcnt lgkmcnt(8)
	v_pk_mul_f32 v[26:27], v[26:27], v[150:151]
	v_pk_fma_f32 v[24:25], v[24:25], v[152:153], v[26:27]
	v_pk_mul_f32 v[26:27], v[100:101], v[150:151]
	v_add_f32_e32 v24, v24, v25
	v_pk_fma_f32 v[26:27], v[98:99], v[152:153], v[26:27]
	v_add_f32_e32 v25, v26, v27
	v_add_f32_dpp v24, v24, v24 quad_perm:[1,0,3,2] row_mask:0xf bank_mask:0xf bound_ctrl:1
	s_nop 0
	v_add_f32_dpp v25, v25, v25 quad_perm:[1,0,3,2] row_mask:0xf bank_mask:0xf bound_ctrl:1
	v_add_f32_dpp v24, v24, v24 quad_perm:[2,3,0,1] row_mask:0xf bank_mask:0xf bound_ctrl:1
	s_nop 0
	v_add_f32_dpp v25, v25, v25 quad_perm:[2,3,0,1] row_mask:0xf bank_mask:0xf bound_ctrl:1
	v_add_f32_dpp v24, v24, v24 row_half_mirror row_mask:0xf bank_mask:0xf bound_ctrl:1
	s_nop 0
	v_add_f32_dpp v25, v25, v25 row_half_mirror row_mask:0xf bank_mask:0xf bound_ctrl:1
	v_add_f32_dpp v24, v24, v24 row_mirror row_mask:0xf bank_mask:0xf bound_ctrl:1
	v_pk_mul_f32 v[26:27], v[138:139], v[24:25] op_sel_hi:[1,0]
	v_add_f32_dpp v98, v25, v25 row_mirror row_mask:0xf bank_mask:0xf bound_ctrl:1
	v_pk_fma_f32 v[26:27], v[146:147], v[102:103], v[26:27] op_sel_hi:[1,0,1]
	v_fmac_f32_e32 v98, v24, v168
	v_pk_mul_f32 v[24:25], v[140:141], v[24:25] op_sel_hi:[1,0]
	v_pk_fma_f32 v[152:153], v[130:131], v[152:153], v[26:27]
	v_fmac_f32_e32 v98, v102, v169
	v_pk_fma_f32 v[24:25], v[148:149], v[102:103], v[24:25] op_sel_hi:[1,0,1]
	ds_write_b32 v114, v98 offset:49408
	v_pk_fma_f32 v[150:151], v[132:133], v[150:151], v[24:25]
	ds_read_b128 v[24:27], v105 offset:2304
	ds_read_b128 v[98:101], v105 offset:6400
	ds_read_b128 v[130:133], v105 offset:10496
	ds_read_b128 v[138:141], v105 offset:14592
	ds_read_b128 v[146:149], v105 offset:18688
	ds_read_b32 v102, v106 offset:22784
	s_waitcnt lgkmcnt(14)
	ds_read_b64 v[168:169], v157 offset:24648
	s_waitcnt lgkmcnt(8)
; DI float row16_sum(float v) { v += dppf(v, 0); v += dppf(v, 1); v += dppf(v, 2); v += dppf(v, 3); return v; }
; DI void rwkv_scan(CP p, const Ptrs& w, int l, int item, float* sm) {
;     ...
;     RStep cur = lds_step(bf, 0);
; #pragma unroll
;     for (int j = 0; j < 16; ++j) {
;       RStep nxt = cur;
;       if (j + 1 < 16) nxt = lds_step(bf, j + 1);
;       f2v sa2 = SA * cur.a4.xy + SB * cur.a4.zw;
;       f2v yp2 = SA * cur.wr4.xy + SB * cur.wr4.zw;
;       float sa = sa2.x + sa2.y, yp = yp2.x + yp2.y;
;       sa = row16_sum(sa); yp = row16_sum(yp);
;       float y = yp + sa * cur.sc.x + cur.vv * cur.sc.y;
;       SA = SA * cur.w4.xy + (sa * cur.b4.xy + cur.vv * cur.k4.xy);
;       SB = SB * cur.w4.zw + (sa * cur.b4.zw + cur.vv * cur.k4.zw);
;       sy[(kg == 0 ? j * 16 : 0) + ysel - (c & 1) * 0] = y;
;       cur = nxt;
	v_pk_mul_f32 v[22:23], v[22:23], v[150:151]
	v_pk_fma_f32 v[20:21], v[20:21], v[152:153], v[22:23]
	v_pk_mul_f32 v[22:23], v[30:31], v[150:151]
	v_add_f32_e32 v20, v20, v21
	v_pk_fma_f32 v[22:23], v[28:29], v[152:153], v[22:23]
	v_add_f32_e32 v21, v22, v23
	v_add_f32_dpp v20, v20, v20 quad_perm:[1,0,3,2] row_mask:0xf bank_mask:0xf bound_ctrl:1
	s_nop 0
	v_add_f32_dpp v21, v21, v21 quad_perm:[1,0,3,2] row_mask:0xf bank_mask:0xf bound_ctrl:1
	v_add_f32_dpp v20, v20, v20 quad_perm:[2,3,0,1] row_mask:0xf bank_mask:0xf bound_ctrl:1
	s_nop 0
	v_add_f32_dpp v21, v21, v21 quad_perm:[2,3,0,1] row_mask:0xf bank_mask:0xf bound_ctrl:1
	v_add_f32_dpp v20, v20, v20 row_half_mirror row_mask:0xf bank_mask:0xf bound_ctrl:1
	s_nop 0
	v_add_f32_dpp v21, v21, v21 row_half_mirror row_mask:0xf bank_mask:0xf bound_ctrl:1
	v_add_f32_dpp v20, v20, v20 row_mirror row_mask:0xf bank_mask:0xf bound_ctrl:1
	v_pk_mul_f32 v[22:23], v[134:135], v[20:21] op_sel_hi:[1,0]
	v_add_f32_dpp v28, v21, v21 row_mirror row_mask:0xf bank_mask:0xf bound_ctrl:1
	v_pk_fma_f32 v[22:23], v[142:143], v[96:97], v[22:23] op_sel_hi:[1,0,1]
	v_fmac_f32_e32 v28, v20, v154
	v_pk_mul_f32 v[20:21], v[136:137], v[20:21] op_sel_hi:[1,0]
	v_pk_fma_f32 v[152:153], v[126:127], v[152:153], v[22:23]
	v_fmac_f32_e32 v28, v96, v155
	v_pk_fma_f32 v[20:21], v[144:145], v[96:97], v[20:21] op_sel_hi:[1,0,1]
	ds_write_b32 v115, v28 offset:49408
	v_pk_fma_f32 v[150:151], v[128:129], v[150:151], v[20:21]
	ds_read_b128 v[20:23], v105 offset:2560
	ds_read_b128 v[28:31], v105 offset:6656
	ds_read_b128 v[126:129], v105 offset:10752
	ds_read_b128 v[134:137], v105 offset:14848
	ds_read_b128 v[142:145], v105 offset:18944
	ds_read_b32 v96, v106 offset:23040
	s_waitcnt lgkmcnt(14)
	ds_read_b64 v[154:155], v157 offset:24656
	s_waitcnt lgkmcnt(8)
	v_pk_mul_f32 v[26:27], v[26:27], v[150:151]
	v_pk_fma_f32 v[24:25], v[24:25], v[152:153], v[26:27]
	v_pk_mul_f32 v[26:27], v[100:101], v[150:151]
	v_add_f32_e32 v24, v24, v25
	v_pk_fma_f32 v[26:27], v[98:99], v[152:153], v[26:27]
	v_add_f32_e32 v25, v26, v27
	v_add_f32_dpp v24, v24, v24 quad_perm:[1,0,3,2] row_mask:0xf bank_mask:0xf bound_ctrl:1
	s_nop 0
	v_add_f32_dpp v25, v25, v25 quad_perm:[1,0,3,2] row_mask:0xf bank_mask:0xf bound_ctrl:1
	v_add_f32_dpp v24, v24, v24 quad_perm:[2,3,0,1] row_mask:0xf bank_mask:0xf bound_ctrl:1
	s_nop 0
	v_add_f32_dpp v25, v25, v25 quad_perm:[2,3,0,1] row_mask:0xf bank_mask:0xf bound_ctrl:1
	v_add_f32_dpp v24, v24, v24 row_half_mirror row_mask:0xf bank_mask:0xf bound_ctrl:1
	s_nop 0
	v_add_f32_dpp v25, v25, v25 row_half_mirror row_mask:0xf bank_mask:0xf bound_ctrl:1
	v_add_f32_dpp v24, v24, v24 row_mirror row_mask:0xf bank_mask:0xf bound_ctrl:1
	v_pk_mul_f32 v[26:27], v[138:139], v[24:25] op_sel_hi:[1,0]
	v_add_f32_dpp v98, v25, v25 row_mirror row_mask:0xf bank_mask:0xf bound_ctrl:1
	v_pk_fma_f32 v[26:27], v[146:147], v[102:103], v[26:27] op_sel_hi:[1,0,1]
	v_fmac_f32_e32 v98, v24, v168
	v_pk_mul_f32 v[24:25], v[140:141], v[24:25] op_sel_hi:[1,0]
	v_pk_fma_f32 v[152:153], v[130:131], v[152:153], v[26:27]
	v_fmac_f32_e32 v98, v102, v169
	v_pk_fma_f32 v[24:25], v[148:149], v[102:103], v[24:25] op_sel_hi:[1,0,1]
	ds_write_b32 v116, v98 offset:49408
	v_pk_fma_f32 v[150:151], v[132:133], v[150:151], v[24:25]
	ds_read_b128 v[24:27], v105 offset:2816
	ds_read_b128 v[98:101], v105 offset:6912
	ds_read_b128 v[130:133], v105 offset:11008
	ds_read_b128 v[138:141], v105 offset:15104
	ds_read_b128 v[146:149], v105 offset:19200
	ds_read_b32 v102, v106 offset:23296
	s_waitcnt lgkmcnt(14)
	ds_read_b64 v[168:169], v157 offset:24664
	s_waitcnt lgkmcnt(8)
	v_pk_mul_f32 v[22:23], v[22:23], v[150:151]
	v_pk_fma_f32 v[20:21], v[20:21], v[152:153], v[22:23]
	v_pk_mul_f32 v[22:23], v[30:31], v[150:151]
	v_add_f32_e32 v20, v20, v21
	v_pk_fma_f32 v[22:23], v[28:29], v[152:153], v[22:23]
	v_add_f32_e32 v21, v22, v23
	v_add_f32_dpp v20, v20, v20 quad_perm:[1,0,3,2] row_mask:0xf bank_mask:0xf bound_ctrl:1
	s_nop 0
	v_add_f32_dpp v21, v21, v21 quad_perm:[1,0,3,2] row_mask:0xf bank_mask:0xf bound_ctrl:1
	v_add_f32_dpp v20, v20, v20 quad_perm:[2,3,0,1] row_mask:0xf bank_mask:0xf bound_ctrl:1
	s_nop 0
	v_add_f32_dpp v21, v21, v21 quad_perm:[2,3,0,1] row_mask:0xf bank_mask:0xf bound_ctrl:1
	v_add_f32_dpp v20, v20, v20 row_half_mirror row_mask:0xf bank_mask:0xf bound_ctrl:1
	s_nop 0
	v_add_f32_dpp v21, v21, v21 row_half_mirror row_mask:0xf bank_mask:0xf bound_ctrl:1
	v_add_f32_dpp v20, v20, v20 row_mirror row_mask:0xf bank_mask:0xf bound_ctrl:1
	v_pk_mul_f32 v[22:23], v[134:135], v[20:21] op_sel_hi:[1,0]
	v_add_f32_dpp v28, v21, v21 row_mirror row_mask:0xf bank_mask:0xf bound_ctrl:1
	v_pk_fma_f32 v[22:23], v[142:143], v[96:97], v[22:23] op_sel_hi:[1,0,1]
	v_fmac_f32_e32 v28, v20, v154
	v_pk_mul_f32 v[20:21], v[136:137], v[20:21] op_sel_hi:[1,0]
	v_pk_fma_f32 v[152:153], v[126:127], v[152:153], v[22:23]
	v_fmac_f32_e32 v28, v96, v155
	v_pk_fma_f32 v[20:21], v[144:145], v[96:97], v[20:21] op_sel_hi:[1,0,1]
	ds_write_b32 v117, v28 offset:49408
	v_pk_fma_f32 v[150:151], v[128:129], v[150:151], v[20:21]
	ds_read_b128 v[20:23], v105 offset:3072
	ds_read_b128 v[28:31], v105 offset:7168
	ds_read_b128 v[126:129], v105 offset:11264
	ds_read_b128 v[134:137], v105 offset:15360
	ds_read_b128 v[142:145], v105 offset:19456
	ds_read_b32 v96, v106 offset:23552
	s_waitcnt lgkmcnt(14)
	ds_read_b64 v[154:155], v157 offset:24672
	s_waitcnt lgkmcnt(8)
; DI float row16_sum(float v) { v += dppf(v, 0); v += dppf(v, 1); v += dppf(v, 2); v += dppf(v, 3); return v; }
; DI void rwkv_scan(CP p, const Ptrs& w, int l, int item, float* sm) {
;     ...
;     RStep cur = lds_step(bf, 0);
; #pragma unroll
;     for (int j = 0; j < 16; ++j) {
;       RStep nxt = cur;
;       if (j + 1 < 16) nxt = lds_step(bf, j + 1);
;       f2v sa2 = SA * cur.a4.xy + SB * cur.a4.zw;
;       f2v yp2 = SA * cur.wr4.xy + SB * cur.wr4.zw;
;       float sa = sa2.x + sa2.y, yp = yp2.x + yp2.y;
;       sa = row16_sum(sa); yp = row16_sum(yp);
;       float y = yp + sa * cur.sc.x + cur.vv * cur.sc.y;
;       SA = SA * cur.w4.xy + (sa * cur.b4.xy + cur.vv * cur.k4.xy);
;       SB = SB * cur.w4.zw + (sa * cur.b4.zw + cur.vv * cur.k4.zw);
;       sy[(kg == 0 ? j * 16 : 0) + ysel - (c & 1) * 0] = y;
;       cur = nxt;
	v_pk_mul_f32 v[26:27], v[26:27], v[150:151]
	v_pk_fma_f32 v[24:25], v[24:25], v[152:153], v[26:27]
	v_pk_mul_f32 v[26:27], v[100:101], v[150:151]
	v_add_f32_e32 v24, v24, v25
	v_pk_fma_f32 v[26:27], v[98:99], v[152:153], v[26:27]
	v_add_f32_e32 v25, v26, v27
	v_add_f32_dpp v24, v24, v24 quad_perm:[1,0,3,2] row_mask:0xf bank_mask:0xf bound_ctrl:1
	s_nop 0
	v_add_f32_dpp v25, v25, v25 quad_perm:[1,0,3,2] row_mask:0xf bank_mask:0xf bound_ctrl:1
	v_add_f32_dpp v24, v24, v24 quad_perm:[2,3,0,1] row_mask:0xf bank_mask:0xf bound_ctrl:1
	s_nop 0
	v_add_f32_dpp v25, v25, v25 quad_perm:[2,3,0,1] row_mask:0xf bank_mask:0xf bound_ctrl:1
	v_add_f32_dpp v24, v24, v24 row_half_mirror row_mask:0xf bank_mask:0xf bound_ctrl:1
	s_nop 0
	v_add_f32_dpp v25, v25, v25 row_half_mirror row_mask:0xf bank_mask:0xf bound_ctrl:1
	v_add_f32_dpp v24, v24, v24 row_mirror row_mask:0xf bank_mask:0xf bound_ctrl:1
	v_pk_mul_f32 v[26:27], v[138:139], v[24:25] op_sel_hi:[1,0]
	v_add_f32_dpp v98, v25, v25 row_mirror row_mask:0xf bank_mask:0xf bound_ctrl:1
	v_pk_fma_f32 v[26:27], v[146:147], v[102:103], v[26:27] op_sel_hi:[1,0,1]
	v_fmac_f32_e32 v98, v24, v168
	v_pk_mul_f32 v[24:25], v[140:141], v[24:25] op_sel_hi:[1,0]
	v_pk_fma_f32 v[152:153], v[130:131], v[152:153], v[26:27]
	v_fmac_f32_e32 v98, v102, v169
	v_pk_fma_f32 v[24:25], v[148:149], v[102:103], v[24:25] op_sel_hi:[1,0,1]
	ds_write_b32 v118, v98 offset:49408
	v_pk_fma_f32 v[150:151], v[132:133], v[150:151], v[24:25]
	ds_read_b128 v[24:27], v105 offset:3328
	ds_read_b128 v[98:101], v105 offset:7424
	ds_read_b128 v[130:133], v105 offset:11520
	ds_read_b128 v[138:141], v105 offset:15616
	ds_read_b128 v[146:149], v105 offset:19712
	ds_read_b32 v102, v106 offset:23808
	s_waitcnt lgkmcnt(14)
	ds_read_b64 v[172:173], v157 offset:24680
	s_waitcnt lgkmcnt(8)
	v_pk_mul_f32 v[22:23], v[22:23], v[150:151]
	v_pk_fma_f32 v[20:21], v[20:21], v[152:153], v[22:23]
	v_pk_mul_f32 v[22:23], v[30:31], v[150:151]
	v_add_f32_e32 v20, v20, v21
	v_pk_fma_f32 v[22:23], v[28:29], v[152:153], v[22:23]
	v_add_f32_e32 v21, v22, v23
	v_add_f32_dpp v20, v20, v20 quad_perm:[1,0,3,2] row_mask:0xf bank_mask:0xf bound_ctrl:1
	s_nop 0
	v_add_f32_dpp v21, v21, v21 quad_perm:[1,0,3,2] row_mask:0xf bank_mask:0xf bound_ctrl:1
	v_add_f32_dpp v20, v20, v20 quad_perm:[2,3,0,1] row_mask:0xf bank_mask:0xf bound_ctrl:1
	s_nop 0
	v_add_f32_dpp v21, v21, v21 quad_perm:[2,3,0,1] row_mask:0xf bank_mask:0xf bound_ctrl:1
	v_add_f32_dpp v20, v20, v20 row_half_mirror row_mask:0xf bank_mask:0xf bound_ctrl:1
	s_nop 0
	v_add_f32_dpp v21, v21, v21 row_half_mirror row_mask:0xf bank_mask:0xf bound_ctrl:1
	v_add_f32_dpp v20, v20, v20 row_mirror row_mask:0xf bank_mask:0xf bound_ctrl:1
	v_pk_mul_f32 v[22:23], v[134:135], v[20:21] op_sel_hi:[1,0]
	v_add_f32_dpp v28, v21, v21 row_mirror row_mask:0xf bank_mask:0xf bound_ctrl:1
	v_pk_fma_f32 v[22:23], v[142:143], v[96:97], v[22:23] op_sel_hi:[1,0,1]
	v_fmac_f32_e32 v28, v20, v154
	v_pk_mul_f32 v[20:21], v[136:137], v[20:21] op_sel_hi:[1,0]
	v_pk_fma_f32 v[22:23], v[126:127], v[152:153], v[22:23]
	v_fmac_f32_e32 v28, v96, v155
	v_pk_fma_f32 v[20:21], v[144:145], v[96:97], v[20:21] op_sel_hi:[1,0,1]
	ds_write_b32 v119, v28 offset:49408
	v_pk_fma_f32 v[20:21], v[128:129], v[150:151], v[20:21]
	ds_read_b128 v[126:129], v105 offset:3584
	ds_read_b128 v[134:137], v105 offset:7680
	ds_read_b128 v[142:145], v105 offset:11776
	ds_read_b128 v[150:153], v105 offset:15872
	ds_read_b128 v[168:171], v105 offset:19968
	ds_read_b32 v154, v106 offset:24064
	s_waitcnt lgkmcnt(14)
	ds_read_b64 v[174:175], v157 offset:24688
	s_waitcnt lgkmcnt(8)
	v_pk_mul_f32 v[26:27], v[26:27], v[20:21]
	v_pk_fma_f32 v[24:25], v[24:25], v[22:23], v[26:27]
	v_pk_mul_f32 v[26:27], v[100:101], v[20:21]
	v_add_f32_e32 v24, v24, v25
	v_pk_fma_f32 v[26:27], v[98:99], v[22:23], v[26:27]
	v_add_f32_e32 v25, v26, v27
	v_add_f32_dpp v24, v24, v24 quad_perm:[1,0,3,2] row_mask:0xf bank_mask:0xf bound_ctrl:1
	s_nop 0
	v_add_f32_dpp v25, v25, v25 quad_perm:[1,0,3,2] row_mask:0xf bank_mask:0xf bound_ctrl:1
	v_add_f32_dpp v24, v24, v24 quad_perm:[2,3,0,1] row_mask:0xf bank_mask:0xf bound_ctrl:1
	s_nop 0
	v_add_f32_dpp v25, v25, v25 quad_perm:[2,3,0,1] row_mask:0xf bank_mask:0xf bound_ctrl:1
	v_add_f32_dpp v24, v24, v24 row_half_mirror row_mask:0xf bank_mask:0xf bound_ctrl:1
	s_nop 0
	v_add_f32_dpp v25, v25, v25 row_half_mirror row_mask:0xf bank_mask:0xf bound_ctrl:1
	v_add_f32_dpp v24, v24, v24 row_mirror row_mask:0xf bank_mask:0xf bound_ctrl:1
	s_nop 0
	v_add_f32_dpp v25, v25, v25 row_mirror row_mask:0xf bank_mask:0xf bound_ctrl:1
	v_fmac_f32_e32 v25, v24, v172
	v_fmac_f32_e32 v25, v102, v173
	v_pk_mul_f32 v[26:27], v[138:139], v[24:25] op_sel_hi:[1,0]
	ds_write_b32 v120, v25 offset:49408
	v_pk_fma_f32 v[26:27], v[146:147], v[102:103], v[26:27] op_sel_hi:[1,0,1]
	v_pk_fma_f32 v[98:99], v[130:131], v[22:23], v[26:27]
	v_pk_mul_f32 v[22:23], v[140:141], v[24:25] op_sel_hi:[1,0]
	v_pk_fma_f32 v[22:23], v[148:149], v[102:103], v[22:23] op_sel_hi:[1,0,1]
	v_pk_fma_f32 v[100:101], v[132:133], v[20:21], v[22:23]
	ds_read_b128 v[130:133], v105 offset:3840
	ds_read_b128 v[138:141], v105 offset:7936
	ds_read_b128 v[20:23], v105 offset:12032
	ds_read_b128 v[28:31], v105 offset:16128
	s_waitcnt lgkmcnt(5)
	v_pk_mul_f32 v[128:129], v[128:129], v[100:101]
	ds_read_b128 v[24:27], v105 offset:20224
	v_pk_fma_f32 v[126:127], v[126:127], v[98:99], v[128:129]
	v_pk_mul_f32 v[128:129], v[136:137], v[100:101]
	ds_read_b32 v96, v106 offset:24320
	ds_read_b64 v[146:147], v157 offset:24696
	v_add_f32_e32 v102, v126, v127
	v_pk_fma_f32 v[128:129], v[134:135], v[98:99], v[128:129]
	s_waitcnt vmcnt(21)
; DI float row16_sum(float v) { v += dppf(v, 0); v += dppf(v, 1); v += dppf(v, 2); v += dppf(v, 3); return v; }
; DI void rwkv_scan(CP p, const Ptrs& w, int l, int item, float* sm) {
;     ...
;   auto stage = [&](const RPre& P, float* bufp) {
;     float rc[4], rp[4], rn[4], kc[4], kp[4], kn[4], vc[4], vp[4], vn[4], wd4[4], ad4[4];
;     up4(P.pq[0][0], rc); up4(P.pq[0][1], rp); up4(P.pq[0][2], rn);
;     up4(P.pq[1][0], kc); up4(P.pq[1][1], kp); up4(P.pq[1][2], kn);
;     up4(P.pq[2][0], vc); up4(P.pq[2][1], vp); up4(P.pq[2][2], vn);
;     up4(P.pwd, wd4); up4(P.pad_, ad4);
;     float o0[4], o1[4], o2[4], o3[4], o4[4], o5[4];
; #pragma unroll
;     for (int j = 0; j < 4; ++j) {
;       float r_s = rc[j] + ((P.pmk[0] * rp[j] + P.pmk[1] * rn[j]) - rc[j]) * mu_r[j];
;       float k_s = kc[j] + ((P.pmk[0] * kp[j] + P.pmk[1] * kn[j]) - kc[j]) * mu_k[j];
;       float v_s = vc[j] + ((P.pmk[0] * vp[j] + P.pmk[1] * vn[j]) - vc[j]) * mu_v[j];
;       float kk = k_s * kk_c[j] * P.psc[0];
;       float a = ad4[j], wv = 1.f - wd4[j];
;       o0[j] = -kk; o1[j] = wv * r_s; o2[j] = wv; o3[j] = kk * a; o4[j] = k_s * (1.f + (a - 1.f) * ka_c[j]); o5[j] = v_s;
;     }
;     float* d = bufp + sj * 64 + skq;
;     *(float4*)(d + 0 * 1024) = make_float4(o0[0], o0[1], o0[2], o0[3]);
;     *(float4*)(d + 1 * 1024) = make_float4(o1[0], o1[1], o1[2], o1[3]);
;     *(float4*)(d + 2 * 1024) = make_float4(o2[0], o2[1], o2[2], o2[3]);
;     *(float4*)(d + 3 * 1024) = make_float4(o3[0], o3[1], o3[2], o3[3]);
;     *(float4*)(d + 4 * 1024) = make_float4(o4[0], o4[1], o4[2], o4[3]);
;     *(float4*)(d + 5 * 1024) = make_float4(o5[0], o5[1], o5[2], o5[3]);
;     ...
;       f2v sa2 = SA * cur.a4.xy + SB * cur.a4.zw;
;       f2v yp2 = SA * cur.wr4.xy + SB * cur.wr4.zw;
;       float sa = sa2.x + sa2.y, yp = yp2.x + yp2.y;
;       sa = row16_sum(sa); yp = row16_sum(yp);
;       float y = yp + sa * cur.sc.x + cur.vv * cur.sc.y;
;       SA = SA * cur.w4.xy + (sa * cur.b4.xy + cur.vv * cur.k4.xy);
;       SB = SB * cur.w4.zw + (sa * cur.b4.zw + cur.vv * cur.k4.zw);
;       sy[(kg == 0 ? j * 16 : 0) + ysel - (c & 1) * 0] = y;
	v_and_b32_e32 v137, 0xffff0000, v52
	v_add_f32_e32 v126, v128, v129
	v_add_f32_dpp v102, v102, v102 quad_perm:[1,0,3,2] row_mask:0xf bank_mask:0xf bound_ctrl:1
	s_waitcnt vmcnt(20)
	v_lshlrev_b32_e32 v136, 16, v54
	v_add_f32_dpp v126, v126, v126 quad_perm:[1,0,3,2] row_mask:0xf bank_mask:0xf bound_ctrl:1
	v_add_f32_dpp v102, v102, v102 quad_perm:[2,3,0,1] row_mask:0xf bank_mask:0xf bound_ctrl:1
	s_waitcnt vmcnt(16)
	v_lshlrev_b32_e32 v134, 16, v64
	v_add_f32_dpp v126, v126, v126 quad_perm:[2,3,0,1] row_mask:0xf bank_mask:0xf bound_ctrl:1
	v_add_f32_dpp v102, v102, v102 row_half_mirror row_mask:0xf bank_mask:0xf bound_ctrl:1
	v_and_b32_e32 v135, 0xffff0000, v64
	v_add_f32_dpp v126, v126, v126 row_half_mirror row_mask:0xf bank_mask:0xf bound_ctrl:1
	v_add_f32_dpp v102, v102, v102 row_mirror row_mask:0xf bank_mask:0xf bound_ctrl:1
	v_lshlrev_b32_e32 v64, 16, v65
	v_add_f32_dpp v128, v126, v126 row_mirror row_mask:0xf bank_mask:0xf bound_ctrl:1
	s_waitcnt lgkmcnt(11)
	v_pk_mul_f32 v[126:127], v[150:151], v[102:103] op_sel_hi:[1,0]
	s_waitcnt lgkmcnt(8)
	v_fmac_f32_e32 v128, v102, v174
	v_pk_fma_f32 v[126:127], v[168:169], v[154:155], v[126:127] op_sel_hi:[1,0,1]
	v_fmac_f32_e32 v128, v154, v175
	v_pk_fma_f32 v[98:99], v[142:143], v[98:99], v[126:127]
	v_pk_mul_f32 v[126:127], v[152:153], v[102:103] op_sel_hi:[1,0]
	ds_write_b32 v121, v128 offset:49408
	v_pk_fma_f32 v[126:127], v[170:171], v[154:155], v[126:127] op_sel_hi:[1,0,1]
	v_and_b32_e32 v65, 0xffff0000, v65
	v_pk_fma_f32 v[100:101], v[144:145], v[100:101], v[126:127]
	s_waitcnt lgkmcnt(7)
	v_pk_mul_f32 v[126:127], v[132:133], v[100:101]
	s_waitcnt lgkmcnt(6)
	v_pk_mul_f32 v[128:129], v[140:141], v[100:101]
	v_pk_fma_f32 v[126:127], v[130:131], v[98:99], v[126:127]
	v_pk_fma_f32 v[128:129], v[138:139], v[98:99], v[128:129]
	v_add_f32_e32 v102, v126, v127
	v_add_f32_e32 v126, v128, v129
	v_lshlrev_b32_e32 v138, 16, v52
	v_add_f32_dpp v102, v102, v102 quad_perm:[1,0,3,2] row_mask:0xf bank_mask:0xf bound_ctrl:1
	v_add_f32_dpp v126, v126, v126 quad_perm:[1,0,3,2] row_mask:0xf bank_mask:0xf bound_ctrl:1
	v_and_b32_e32 v139, 0xffff0000, v54
	v_add_f32_dpp v102, v102, v102 quad_perm:[2,3,0,1] row_mask:0xf bank_mask:0xf bound_ctrl:1
	v_add_f32_dpp v126, v126, v126 quad_perm:[2,3,0,1] row_mask:0xf bank_mask:0xf bound_ctrl:1
	v_and_b32_e32 v141, 0xffff0000, v53
	v_add_f32_dpp v102, v102, v102 row_half_mirror row_mask:0xf bank_mask:0xf bound_ctrl:1
	v_add_f32_dpp v126, v126, v126 row_half_mirror row_mask:0xf bank_mask:0xf bound_ctrl:1
	v_lshlrev_b32_e32 v52, 16, v53
	v_add_f32_dpp v102, v102, v102 row_mirror row_mask:0xf bank_mask:0xf bound_ctrl:1
	v_add_f32_dpp v126, v126, v126 row_mirror row_mask:0xf bank_mask:0xf bound_ctrl:1
	s_waitcnt lgkmcnt(1)
	v_fmac_f32_e32 v126, v102, v146
	v_and_b32_e32 v53, 0xffff0000, v55
	v_fmac_f32_e32 v126, v96, v147
	v_pk_mul_f32 v[138:139], v[94:95], v[138:139] op_sel:[1,0] op_sel_hi:[0,1]
	v_lshlrev_b32_e32 v140, 16, v55
	v_pk_mul_f32 v[52:53], v[94:95], v[52:53] op_sel:[1,0] op_sel_hi:[0,1]
	ds_write_b32 v122, v126 offset:49408
	v_lshlrev_b32_e32 v126, 16, v58
	v_and_b32_e32 v127, 0xffff0000, v58
	v_lshlrev_b32_e32 v128, 16, v59
	v_and_b32_e32 v129, 0xffff0000, v59
	v_lshlrev_b32_e32 v58, 16, v60
	v_and_b32_e32 v59, 0xffff0000, v60
	v_lshlrev_b32_e32 v60, 16, v61
	v_and_b32_e32 v61, 0xffff0000, v61
	v_pk_fma_f32 v[136:137], v[94:95], v[136:137], v[138:139]
	v_pk_fma_f32 v[52:53], v[94:95], v[140:141], v[52:53]
	v_pk_add_f32 v[136:137], v[136:137], v[58:59] neg_lo:[0,1] neg_hi:[0,1]
	v_pk_add_f32 v[52:53], v[52:53], v[60:61] neg_lo:[0,1] neg_hi:[0,1]
	v_pk_fma_f32 v[136:137], v[8:9], v[136:137], v[58:59]
	v_pk_fma_f32 v[140:141], v[10:11], v[52:53], v[60:61]
	v_pk_mul_f32 v[58:59], v[12:13], v[136:137]
	v_pk_mul_f32 v[52:53], v[14:15], v[140:141]
	s_waitcnt vmcnt(15)
	v_pk_mul_f32 v[138:139], v[56:57], v[58:59] op_sel_hi:[0,1]
	v_pk_mul_f32 v[142:143], v[56:57], v[52:53] op_sel_hi:[0,1]
	v_xor_b32_e32 v59, 0x80000000, v139
	v_xor_b32_e32 v58, 0x80000000, v138
	v_xor_b32_e32 v61, 0x80000000, v143
	v_xor_b32_e32 v60, 0x80000000, v142
	ds_write_b128 v103, v[58:61] offset:24704
	v_lshlrev_b32_e32 v59, 16, v48
	v_and_b32_e32 v61, s0, v48
	v_and_b32_e32 v60, 0xffff0000, v50
	v_pk_mov_b32 v[58:59], v[58:59], v[60:61] op_sel:[1,0]
	v_lshlrev_b32_e32 v54, 16, v50
	v_and_b32_e32 v55, 0xffff0000, v48
	v_pk_mul_f32 v[58:59], v[94:95], v[58:59] op_sel:[1,0] op_sel_hi:[0,1]
	v_pk_fma_f32 v[54:55], v[94:95], v[54:55], v[58:59]
	v_lshlrev_b32_e32 v132, 16, v66
	v_and_b32_e32 v133, 0xffff0000, v66
	v_pk_add_f32 v[54:55], v[54:55], v[126:127] neg_lo:[0,1] neg_hi:[0,1]
	v_lshlrev_b32_e32 v66, 16, v67
	v_and_b32_e32 v67, 0xffff0000, v67
	v_pk_add_f32 v[52:53], v[132:133], 1.0 op_sel_hi:[1,0] neg_lo:[1,0] neg_hi:[1,0]
	v_pk_fma_f32 v[54:55], v[0:1], v[54:55], v[126:127]
	v_and_b32_e32 v61, 0xffff0000, v49
	v_pk_mul_f32 v[58:59], v[54:55], v[52:53]
	v_pk_add_f32 v[54:55], v[66:67], 1.0 op_sel_hi:[1,0] neg_lo:[1,0] neg_hi:[1,0]
	v_lshlrev_b32_e32 v67, 16, v49
	v_and_b32_e32 v49, s0, v49
	v_and_b32_e32 v48, 0xffff0000, v51
	v_pk_mov_b32 v[48:49], v[66:67], v[48:49] op_sel:[1,0]
	v_lshlrev_b32_e32 v60, 16, v51
	v_pk_mul_f32 v[48:49], v[94:95], v[48:49] op_sel:[1,0] op_sel_hi:[0,1]
	v_pk_fma_f32 v[48:49], v[94:95], v[60:61], v[48:49]
	v_pk_mul_f32 v[50:51], v[142:143], v[64:65]
	v_pk_add_f32 v[48:49], v[48:49], v[128:129] neg_lo:[0,1] neg_hi:[0,1]
	v_lshlrev_b32_e32 v130, 16, v62
	v_pk_fma_f32 v[48:49], v[2:3], v[48:49], v[128:129]
	v_and_b32_e32 v131, 0xffff0000, v62
	v_pk_mul_f32 v[60:61], v[48:49], v[54:55]
	v_pk_mul_f32 v[48:49], v[138:139], v[134:135]
	ds_write_b128 v103, v[58:61] offset:28800
; DI float row16_sum(float v) { v += dppf(v, 0); v += dppf(v, 1); v += dppf(v, 2); v += dppf(v, 3); return v; }
; DI void rwkv_scan(CP p, const Ptrs& w, int l, int item, float* sm) {
;     ...
;     *(float4*)(d + 1 * 1024) = make_float4(o1[0], o1[1], o1[2], o1[3]);
;     *(float4*)(d + 2 * 1024) = make_float4(o2[0], o2[1], o2[2], o2[3]);
;     *(float4*)(d + 3 * 1024) = make_float4(o3[0], o3[1], o3[2], o3[3]);
;     *(float4*)(d + 4 * 1024) = make_float4(o4[0], o4[1], o4[2], o4[3]);
;     *(float4*)(d + 5 * 1024) = make_float4(o5[0], o5[1], o5[2], o5[3]);
;     if (skq == 0) *(float2*)(bufp + 6 * 1024 + sj * 2) = make_float2(P.psc[1], P.psc[2]);
;     ...
;   auto flush = [&](int c) {
;     {
;       int j = tid >> 4, rr = tid & 15;
;       int ii = pos2i(c * 16 + j, dir);
;       yout[((size_t)b * TPB + ii) * 512 + hd * 64 + rq * 16 + rr] = f2bf(sY[(c & 1) * 256 + j * 16 + rr]);
;     }
;   };
;   __syncthreads();
;   load(0, PA);
;   stage(PA, sm);
;   load(1, PB);
;   __syncthreads();
;   const int NCH = TPB / 16;
;   auto run_chunk = [&](int c, const float* bf, float* sy) {
;     flush(max(c - 1, 0));
;     RStep cur = lds_step(bf, 0);
; #pragma unroll
;     for (int j = 0; j < 16; ++j) {
;       RStep nxt = cur;
;       if (j + 1 < 16) nxt = lds_step(bf, j + 1);
;       f2v sa2 = SA * cur.a4.xy + SB * cur.a4.zw;
;       f2v yp2 = SA * cur.wr4.xy + SB * cur.wr4.zw;
;       float sa = sa2.x + sa2.y, yp = yp2.x + yp2.y;
;       sa = row16_sum(sa); yp = row16_sum(yp);
;       float y = yp + sa * cur.sc.x + cur.vv * cur.sc.y;
;       SA = SA * cur.w4.xy + (sa * cur.b4.xy + cur.vv * cur.k4.xy);
;       SB = SB * cur.w4.zw + (sa * cur.b4.zw + cur.vv * cur.k4.zw);
;       sy[(kg == 0 ? j * 16 : 0) + ysel - (c & 1) * 0] = y;
;       cur = nxt;
;     }
;   };
;   for (int c = 0; c < NCH; c += 2) {
;     load(min(c + 2, NCH - 1), PA);
;     run_chunk(c, sm, sY);
;     stage(PB, sm + BUF);
;     __syncthreads();
;     load(min(c + 3, NCH - 1), PB);
	ds_write_b128 v103, v[52:55] offset:32896
	ds_write_b128 v103, v[48:51] offset:36992
	v_pk_add_f32 v[48:49], v[134:135], -1.0 op_sel_hi:[1,0]
	v_pk_add_f32 v[50:51], v[64:65], -1.0 op_sel_hi:[1,0]
	v_pk_fma_f32 v[48:49], v[16:17], v[48:49], 1.0 op_sel_hi:[1,1,0]
	v_pk_fma_f32 v[50:51], v[18:19], v[50:51], 1.0 op_sel_hi:[1,1,0]
	v_pk_mul_f32 v[48:49], v[48:49], v[136:137]
	v_pk_mul_f32 v[50:51], v[50:51], v[140:141]
	ds_write_b128 v103, v[48:51] offset:41088
	v_lshlrev_b32_e32 v51, 16, v40
	v_and_b32_e32 v53, s0, v40
	v_and_b32_e32 v52, 0xffff0000, v46
	v_pk_mov_b32 v[50:51], v[50:51], v[52:53] op_sel:[1,0]
	v_lshlrev_b32_e32 v48, 16, v46
	v_and_b32_e32 v49, 0xffff0000, v40
	v_pk_mul_f32 v[50:51], v[94:95], v[50:51] op_sel:[1,0] op_sel_hi:[0,1]
	v_pk_fma_f32 v[48:49], v[94:95], v[48:49], v[50:51]
	v_and_b32_e32 v51, 0xffff0000, v41
	v_lshlrev_b32_e32 v53, 16, v41
	v_and_b32_e32 v41, s0, v41
	v_and_b32_e32 v40, 0xffff0000, v47
	v_pk_mov_b32 v[40:41], v[52:53], v[40:41] op_sel:[1,0]
	v_lshlrev_b32_e32 v50, 16, v47
	v_pk_mul_f32 v[40:41], v[94:95], v[40:41] op_sel:[1,0] op_sel_hi:[0,1]
	v_lshlrev_b32_e32 v62, 16, v63
	v_and_b32_e32 v63, 0xffff0000, v63
	v_pk_fma_f32 v[40:41], v[94:95], v[50:51], v[40:41]
	v_pk_add_f32 v[48:49], v[48:49], v[130:131] neg_lo:[0,1] neg_hi:[0,1]
	v_pk_add_f32 v[40:41], v[40:41], v[62:63] neg_lo:[0,1] neg_hi:[0,1]
	v_pk_fma_f32 v[48:49], v[4:5], v[48:49], v[130:131]
	v_pk_fma_f32 v[50:51], v[6:7], v[40:41], v[62:63]
	ds_write_b128 v103, v[48:51] offset:45184
	s_and_saveexec_b64 s[4:5], s[40:41]
	s_cbranch_execz .LBB0_556
	s_waitcnt vmcnt(14)
	ds_write_b64 v104, v[44:45] offset:49280
.LBB0_556:
	s_or_b64 exec, exec, s[4:5]
	v_pk_mul_f32 v[28:29], v[28:29], v[102:103] op_sel_hi:[1,0]
	s_add_i32 s17, s17, 2
	v_pk_fma_f32 v[24:25], v[24:25], v[96:97], v[28:29] op_sel_hi:[1,0,1]
	s_min_u32 s4, s17, 0x20c
	v_pk_fma_f32 v[154:155], v[20:21], v[98:99], v[24:25]
	v_pk_mul_f32 v[20:21], v[30:31], v[102:103] op_sel_hi:[1,0]
	v_cndmask_b32_e64 v95, 0.5, 0, s[42:43]
	v_pk_fma_f32 v[20:21], v[26:27], v[96:97], v[20:21] op_sel_hi:[1,0,1]
	v_cndmask_b32_e64 v94, 0.5, 0, s[44:45]
	v_pk_fma_f32 v[168:169], v[22:23], v[100:101], v[20:21]
	v_lshl_add_u32 v20, s4, 4, v123
	v_cmp_lt_i32_e64 s[4:5], s37, v20
	s_waitcnt lgkmcnt(0)
	s_barrier
	v_cndmask_b32_e64 v21, v231, v232, s[4:5]
	v_sub_u32_e32 v21, v21, v20
	v_cndmask_b32_e32 v20, v21, v20, vcc
	v_ashrrev_i32_e32 v21, 31, v20
	v_lshl_add_u64 v[22:23], s[12:13], 0, v[20:21]
	v_mad_u64_u32 v[24:25], s[4:5], v22, s20, v[42:43]
	v_mov_b32_e32 v26, v25
	v_mad_u64_u32 v[26:27], s[4:5], v23, s20, v[26:27]
	v_and_b32_e32 v21, 0xfffffeff, v20
	v_mov_b32_e32 v25, v26
	v_and_b32_e32 v26, 0xffffdfff, v20
	v_cmp_eq_u32_e64 s[42:43], 0, v21
	v_cmp_eq_u32_e64 s[44:45], s37, v26
	s_nop 0
	v_cndmask_b32_e64 v21, -1, 0, s[42:43]
	v_cndmask_b32_e64 v20, v236, 0, s[42:43]
	v_cndmask_b32_e64 v156, v237, 0, s[44:45]
	v_lshl_add_u64 v[20:21], v[24:25], 0, v[20:21]
	v_lshl_add_u64 v[26:27], v[24:25], 0, v[156:157]
	global_load_dwordx2 v[58:59], v[24:25], off
	global_load_dwordx2 v[60:61], v[24:25], off offset:1024
	global_load_dwordx2 v[62:63], v[24:25], off offset:2048
	global_load_dwordx2 v[48:49], v[20:21], off
	global_load_dwordx2 v[50:51], v[26:27], off
	global_load_dwordx2 v[52:53], v[20:21], off offset:1024
	global_load_dwordx2 v[40:41], v[20:21], off offset:2048
	v_lshlrev_b64 v[20:21], 10, v[22:23]
	v_lshl_add_u64 v[24:25], v[34:35], 0, v[20:21]
	v_lshl_add_u64 v[20:21], v[36:37], 0, v[20:21]
	global_load_dwordx2 v[54:55], v[26:27], off offset:1024
	global_load_dwordx2 v[46:47], v[26:27], off offset:2048
	global_load_dwordx2 v[66:67], v[24:25], off
	global_load_dwordx2 v[64:65], v[20:21], off
	v_lshlrev_b64 v[20:21], 8, v[22:23]
	v_lshl_add_u64 v[20:21], s[6:7], 0, v[20:21]
	v_lshl_add_u64 v[22:23], v[20:21], 0, s[90:91]
	global_load_dword v56, v[20:21], off
	global_load_dwordx2 v[44:45], v[22:23], off offset:4
	ds_read_b32 v21, v83 offset:49408
	v_cmp_lt_i32_e64 s[4:5], s37, v125
	s_waitcnt lgkmcnt(0)
	v_cvt_pk_bf16_f32 v22, v21, s0
	v_cndmask_b32_e64 v20, v231, v232, s[4:5]
	v_add_u32_e32 v20, v20, v124
	v_cndmask_b32_e32 v20, v20, v125, vcc
	v_ashrrev_i32_e32 v21, 31, v20
	v_lshl_add_u64 v[20:21], s[12:13], 0, v[20:21]
	v_lshlrev_b64 v[20:21], 10, v[20:21]
	v_lshl_add_u64 v[20:21], v[38:39], 0, v[20:21]
	global_store_short v[20:21], v22, off
	s_waitcnt lgkmcnt(0)
	v_add_u32_e32 v20, 0x80, v106
	ds_read2st64_b32 v[170:171], v20 offset0:176 offset1:177
	v_add_u32_e64 v20, s22, 0
	ds_read2_b64 v[20:23], v20 offset0:16 offset1:17
	ds_read_b128 v[24:27], v105 offset:24704
	ds_read_b128 v[28:31], v105 offset:24960
	ds_read_b128 v[98:101], v105 offset:28800
	ds_read_b128 v[126:129], v105 offset:29056
	ds_read_b128 v[130:133], v105 offset:32896
	ds_read_b128 v[134:137], v105 offset:33152
	ds_read_b128 v[138:141], v105 offset:36992
	ds_read_b128 v[142:145], v105 offset:37248
	ds_read_b128 v[146:149], v105 offset:41088
	ds_read_b128 v[150:153], v105 offset:41344
	s_waitcnt lgkmcnt(9)
	v_pk_mul_f32 v[26:27], v[168:169], v[26:27]
	v_pk_fma_f32 v[24:25], v[154:155], v[24:25], v[26:27]
	v_add_f32_e32 v24, v24, v25
	s_waitcnt lgkmcnt(7)
	v_pk_mul_f32 v[26:27], v[168:169], v[100:101]
	v_pk_fma_f32 v[26:27], v[154:155], v[98:99], v[26:27]
	v_add_f32_dpp v24, v24, v24 quad_perm:[1,0,3,2] row_mask:0xf bank_mask:0xf bound_ctrl:1
	v_add_f32_e32 v25, v26, v27
	s_nop 0
	v_add_f32_dpp v24, v24, v24 quad_perm:[2,3,0,1] row_mask:0xf bank_mask:0xf bound_ctrl:1
	v_add_f32_dpp v25, v25, v25 quad_perm:[1,0,3,2] row_mask:0xf bank_mask:0xf bound_ctrl:1
	s_nop 0
	v_add_f32_dpp v24, v24, v24 row_half_mirror row_mask:0xf bank_mask:0xf bound_ctrl:1
	v_add_f32_dpp v25, v25, v25 quad_perm:[2,3,0,1] row_mask:0xf bank_mask:0xf bound_ctrl:1
	s_nop 0
	v_add_f32_dpp v24, v24, v24 row_mirror row_mask:0xf bank_mask:0xf bound_ctrl:1
	v_add_f32_dpp v25, v25, v25 row_half_mirror row_mask:0xf bank_mask:0xf bound_ctrl:1
	s_nop 1
	v_add_f32_dpp v26, v25, v25 row_mirror row_mask:0xf bank_mask:0xf bound_ctrl:1
	v_fmac_f32_e32 v26, v20, v24
	v_fmac_f32_e32 v26, v170, v21
	s_waitcnt lgkmcnt(0)
; DI float row16_sum(float v) { v += dppf(v, 0); v += dppf(v, 1); v += dppf(v, 2); v += dppf(v, 3); return v; }
; DI void rwkv_scan(CP p, const Ptrs& w, int l, int item, float* sm) {
;     ...
;     RStep cur = lds_step(bf, 0);
; #pragma unroll
;     for (int j = 0; j < 16; ++j) {
;       RStep nxt = cur;
;       if (j + 1 < 16) nxt = lds_step(bf, j + 1);
;       f2v sa2 = SA * cur.a4.xy + SB * cur.a4.zw;
;       f2v yp2 = SA * cur.wr4.xy + SB * cur.wr4.zw;
;       float sa = sa2.x + sa2.y, yp = yp2.x + yp2.y;
;       sa = row16_sum(sa); yp = row16_sum(yp);
;       float y = yp + sa * cur.sc.x + cur.vv * cur.sc.y;
;       SA = SA * cur.w4.xy + (sa * cur.b4.xy + cur.vv * cur.k4.xy);
;       SB = SB * cur.w4.zw + (sa * cur.b4.zw + cur.vv * cur.k4.zw);
;       sy[(kg == 0 ? j * 16 : 0) + ysel - (c & 1) * 0] = y;
;       cur = nxt;
	v_pk_mul_f32 v[20:21], v[138:139], v[24:25] op_sel_hi:[1,0]
	v_pk_mul_f32 v[24:25], v[140:141], v[24:25] op_sel_hi:[1,0]
	ds_write_b32 v107, v26 offset:50432
	v_pk_fma_f32 v[20:21], v[146:147], v[170:171], v[20:21] op_sel_hi:[1,0,1]
	v_pk_fma_f32 v[24:25], v[148:149], v[170:171], v[24:25] op_sel_hi:[1,0,1]
	v_pk_fma_f32 v[20:21], v[154:155], v[130:131], v[20:21]
	v_pk_fma_f32 v[154:155], v[168:169], v[132:133], v[24:25]
	ds_read_b128 v[24:27], v105 offset:33408
	ds_read_b128 v[98:101], v105 offset:37504
	ds_read_b128 v[130:133], v105 offset:25216
	ds_read_b128 v[138:141], v105 offset:41600
	ds_read_b128 v[146:149], v105 offset:29312
	v_pk_mul_f32 v[30:31], v[30:31], v[154:155]
	ds_read_b32 v96, v106 offset:45696
	v_pk_fma_f32 v[28:29], v[28:29], v[20:21], v[30:31]
	v_pk_mul_f32 v[30:31], v[128:129], v[154:155]
	ds_read_b64 v[168:169], v157 offset:49296
	v_pk_fma_f32 v[30:31], v[126:127], v[20:21], v[30:31]
	v_add_f32_e32 v28, v28, v29
	v_add_f32_e32 v29, v30, v31
	v_mov_b32_e32 v30, v171
	v_add_f32_dpp v28, v28, v28 quad_perm:[1,0,3,2] row_mask:0xf bank_mask:0xf bound_ctrl:1
	v_add_f32_dpp v29, v29, v29 quad_perm:[1,0,3,2] row_mask:0xf bank_mask:0xf bound_ctrl:1
	s_nop 0
	v_add_f32_dpp v28, v28, v28 quad_perm:[2,3,0,1] row_mask:0xf bank_mask:0xf bound_ctrl:1
	v_add_f32_dpp v29, v29, v29 quad_perm:[2,3,0,1] row_mask:0xf bank_mask:0xf bound_ctrl:1
	s_nop 0
	v_add_f32_dpp v28, v28, v28 row_half_mirror row_mask:0xf bank_mask:0xf bound_ctrl:1
	v_add_f32_dpp v29, v29, v29 row_half_mirror row_mask:0xf bank_mask:0xf bound_ctrl:1
	s_nop 0
	v_add_f32_dpp v28, v28, v28 row_mirror row_mask:0xf bank_mask:0xf bound_ctrl:1
	v_add_f32_dpp v29, v29, v29 row_mirror row_mask:0xf bank_mask:0xf bound_ctrl:1
	v_fmac_f32_e32 v29, v28, v22
	v_fmac_f32_e32 v29, v171, v23
	v_pk_mul_f32 v[22:23], v[142:143], v[28:29] op_sel_hi:[1,0]
	ds_write_b32 v108, v29 offset:50432
	v_pk_fma_f32 v[22:23], v[150:151], v[30:31], v[22:23] op_sel_hi:[1,0,1]
	v_pk_fma_f32 v[150:151], v[134:135], v[20:21], v[22:23]
	v_pk_mul_f32 v[20:21], v[144:145], v[28:29] op_sel_hi:[1,0]
	v_pk_fma_f32 v[20:21], v[152:153], v[30:31], v[20:21] op_sel_hi:[1,0,1]
	v_pk_fma_f32 v[152:153], v[136:137], v[154:155], v[20:21]
	ds_read_b128 v[20:23], v105 offset:33664
	ds_read_b128 v[28:31], v105 offset:37760
	ds_read_b128 v[126:129], v105 offset:25472
	ds_read_b128 v[134:137], v105 offset:41856
	ds_read_b128 v[142:145], v105 offset:29568
	ds_read_b32 v102, v106 offset:45952
	s_waitcnt lgkmcnt(14)
	ds_read_b64 v[154:155], v157 offset:49304
	s_waitcnt lgkmcnt(7)
	v_pk_mul_f32 v[132:133], v[132:133], v[152:153]
	v_pk_fma_f32 v[130:131], v[130:131], v[150:151], v[132:133]
	v_pk_mul_f32 v[132:133], v[148:149], v[152:153]
	v_add_f32_e32 v130, v130, v131
	v_pk_fma_f32 v[132:133], v[146:147], v[150:151], v[132:133]
	v_add_f32_e32 v131, v132, v133
	v_add_f32_dpp v130, v130, v130 quad_perm:[1,0,3,2] row_mask:0xf bank_mask:0xf bound_ctrl:1
	s_nop 0
	v_add_f32_dpp v131, v131, v131 quad_perm:[1,0,3,2] row_mask:0xf bank_mask:0xf bound_ctrl:1
	v_add_f32_dpp v130, v130, v130 quad_perm:[2,3,0,1] row_mask:0xf bank_mask:0xf bound_ctrl:1
	s_nop 0
	v_add_f32_dpp v131, v131, v131 quad_perm:[2,3,0,1] row_mask:0xf bank_mask:0xf bound_ctrl:1
	v_add_f32_dpp v130, v130, v130 row_half_mirror row_mask:0xf bank_mask:0xf bound_ctrl:1
	s_nop 0
	v_add_f32_dpp v131, v131, v131 row_half_mirror row_mask:0xf bank_mask:0xf bound_ctrl:1
	v_add_f32_dpp v130, v130, v130 row_mirror row_mask:0xf bank_mask:0xf bound_ctrl:1
	s_nop 0
	v_add_f32_dpp v131, v131, v131 row_mirror row_mask:0xf bank_mask:0xf bound_ctrl:1
	v_fmac_f32_e32 v131, v130, v168
	v_fmac_f32_e32 v131, v96, v169
	v_pk_mul_f32 v[98:99], v[98:99], v[130:131] op_sel_hi:[1,0]
	ds_write_b32 v109, v131 offset:50432
	v_pk_fma_f32 v[98:99], v[138:139], v[96:97], v[98:99] op_sel_hi:[1,0,1]
	v_pk_fma_f32 v[150:151], v[24:25], v[150:151], v[98:99]
	v_pk_mul_f32 v[24:25], v[100:101], v[130:131] op_sel_hi:[1,0]
	v_pk_fma_f32 v[24:25], v[140:141], v[96:97], v[24:25] op_sel_hi:[1,0,1]
	v_pk_fma_f32 v[152:153], v[26:27], v[152:153], v[24:25]
	ds_read_b128 v[24:27], v105 offset:33920
	ds_read_b128 v[98:101], v105 offset:38016
	ds_read_b128 v[130:133], v105 offset:25728
	ds_read_b128 v[138:141], v105 offset:42112
	ds_read_b128 v[146:149], v105 offset:29824
	ds_read_b32 v96, v106 offset:46208
	s_waitcnt lgkmcnt(6)
	v_pk_mul_f32 v[128:129], v[128:129], v[152:153]
	ds_read_b64 v[168:169], v157 offset:49312
	v_pk_fma_f32 v[126:127], v[126:127], v[150:151], v[128:129]
	v_pk_mul_f32 v[128:129], v[144:145], v[152:153]
	v_add_f32_e32 v126, v126, v127
	v_pk_fma_f32 v[128:129], v[142:143], v[150:151], v[128:129]
	v_add_f32_e32 v127, v128, v129
	v_add_f32_dpp v126, v126, v126 quad_perm:[1,0,3,2] row_mask:0xf bank_mask:0xf bound_ctrl:1
	s_nop 0
	v_add_f32_dpp v127, v127, v127 quad_perm:[1,0,3,2] row_mask:0xf bank_mask:0xf bound_ctrl:1
	v_add_f32_dpp v126, v126, v126 quad_perm:[2,3,0,1] row_mask:0xf bank_mask:0xf bound_ctrl:1
	s_nop 0
	v_add_f32_dpp v127, v127, v127 quad_perm:[2,3,0,1] row_mask:0xf bank_mask:0xf bound_ctrl:1
	v_add_f32_dpp v126, v126, v126 row_half_mirror row_mask:0xf bank_mask:0xf bound_ctrl:1
	s_nop 0
	v_add_f32_dpp v127, v127, v127 row_half_mirror row_mask:0xf bank_mask:0xf bound_ctrl:1
	v_add_f32_dpp v126, v126, v126 row_mirror row_mask:0xf bank_mask:0xf bound_ctrl:1
	s_nop 0
	v_add_f32_dpp v127, v127, v127 row_mirror row_mask:0xf bank_mask:0xf bound_ctrl:1
	v_fmac_f32_e32 v127, v126, v154
	v_fmac_f32_e32 v127, v102, v155
	v_pk_mul_f32 v[28:29], v[28:29], v[126:127] op_sel_hi:[1,0]
	ds_write_b32 v110, v127 offset:50432
	v_pk_fma_f32 v[28:29], v[134:135], v[102:103], v[28:29] op_sel_hi:[1,0,1]
	v_pk_fma_f32 v[150:151], v[20:21], v[150:151], v[28:29]
	v_pk_mul_f32 v[20:21], v[30:31], v[126:127] op_sel_hi:[1,0]
	v_pk_fma_f32 v[20:21], v[136:137], v[102:103], v[20:21] op_sel_hi:[1,0,1]
	v_pk_fma_f32 v[152:153], v[22:23], v[152:153], v[20:21]
	ds_read_b128 v[20:23], v105 offset:34176
	ds_read_b128 v[28:31], v105 offset:38272
	ds_read_b128 v[126:129], v105 offset:25984
	ds_read_b128 v[134:137], v105 offset:42368
	ds_read_b128 v[142:145], v105 offset:30080
	ds_read_b32 v102, v106 offset:46464
	ds_read_b64 v[154:155], v157 offset:49320
	s_waitcnt lgkmcnt(7)
; DI float row16_sum(float v) { v += dppf(v, 0); v += dppf(v, 1); v += dppf(v, 2); v += dppf(v, 3); return v; }
; DI void rwkv_scan(CP p, const Ptrs& w, int l, int item, float* sm) {
;     ...
;     RStep cur = lds_step(bf, 0);
; #pragma unroll
;     for (int j = 0; j < 16; ++j) {
;       RStep nxt = cur;
;       if (j + 1 < 16) nxt = lds_step(bf, j + 1);
;       f2v sa2 = SA * cur.a4.xy + SB * cur.a4.zw;
;       f2v yp2 = SA * cur.wr4.xy + SB * cur.wr4.zw;
;       float sa = sa2.x + sa2.y, yp = yp2.x + yp2.y;
;       sa = row16_sum(sa); yp = row16_sum(yp);
;       float y = yp + sa * cur.sc.x + cur.vv * cur.sc.y;
;       SA = SA * cur.w4.xy + (sa * cur.b4.xy + cur.vv * cur.k4.xy);
;       SB = SB * cur.w4.zw + (sa * cur.b4.zw + cur.vv * cur.k4.zw);
;       sy[(kg == 0 ? j * 16 : 0) + ysel - (c & 1) * 0] = y;
;       cur = nxt;
	v_pk_mul_f32 v[132:133], v[132:133], v[152:153]
	v_pk_fma_f32 v[130:131], v[130:131], v[150:151], v[132:133]
	v_pk_mul_f32 v[132:133], v[148:149], v[152:153]
	v_add_f32_e32 v130, v130, v131
	v_pk_fma_f32 v[132:133], v[146:147], v[150:151], v[132:133]
	v_add_f32_e32 v131, v132, v133
	v_add_f32_dpp v130, v130, v130 quad_perm:[1,0,3,2] row_mask:0xf bank_mask:0xf bound_ctrl:1
	s_nop 0
	v_add_f32_dpp v131, v131, v131 quad_perm:[1,0,3,2] row_mask:0xf bank_mask:0xf bound_ctrl:1
	v_add_f32_dpp v130, v130, v130 quad_perm:[2,3,0,1] row_mask:0xf bank_mask:0xf bound_ctrl:1
	s_nop 0
	v_add_f32_dpp v131, v131, v131 quad_perm:[2,3,0,1] row_mask:0xf bank_mask:0xf bound_ctrl:1
	v_add_f32_dpp v130, v130, v130 row_half_mirror row_mask:0xf bank_mask:0xf bound_ctrl:1
	s_nop 0
	v_add_f32_dpp v131, v131, v131 row_half_mirror row_mask:0xf bank_mask:0xf bound_ctrl:1
	v_add_f32_dpp v130, v130, v130 row_mirror row_mask:0xf bank_mask:0xf bound_ctrl:1
	s_nop 0
	v_add_f32_dpp v131, v131, v131 row_mirror row_mask:0xf bank_mask:0xf bound_ctrl:1
	v_fmac_f32_e32 v131, v130, v168
	v_fmac_f32_e32 v131, v96, v169
	v_pk_mul_f32 v[98:99], v[98:99], v[130:131] op_sel_hi:[1,0]
	ds_write_b32 v111, v131 offset:50432
	v_pk_fma_f32 v[98:99], v[138:139], v[96:97], v[98:99] op_sel_hi:[1,0,1]
	v_pk_fma_f32 v[150:151], v[24:25], v[150:151], v[98:99]
	v_pk_mul_f32 v[24:25], v[100:101], v[130:131] op_sel_hi:[1,0]
	v_pk_fma_f32 v[24:25], v[140:141], v[96:97], v[24:25] op_sel_hi:[1,0,1]
	v_pk_fma_f32 v[152:153], v[26:27], v[152:153], v[24:25]
	ds_read_b128 v[24:27], v105 offset:34432
	ds_read_b128 v[98:101], v105 offset:38528
	ds_read_b128 v[130:133], v105 offset:26240
	ds_read_b128 v[138:141], v105 offset:42624
	ds_read_b128 v[146:149], v105 offset:30336
	ds_read_b32 v96, v106 offset:46720
	s_waitcnt lgkmcnt(6)
	v_pk_mul_f32 v[128:129], v[128:129], v[152:153]
	ds_read_b64 v[168:169], v157 offset:49328
	v_pk_fma_f32 v[126:127], v[126:127], v[150:151], v[128:129]
	v_pk_mul_f32 v[128:129], v[144:145], v[152:153]
	v_add_f32_e32 v126, v126, v127
	v_pk_fma_f32 v[128:129], v[142:143], v[150:151], v[128:129]
	v_add_f32_e32 v127, v128, v129
	v_add_f32_dpp v126, v126, v126 quad_perm:[1,0,3,2] row_mask:0xf bank_mask:0xf bound_ctrl:1
	s_nop 0
	v_add_f32_dpp v127, v127, v127 quad_perm:[1,0,3,2] row_mask:0xf bank_mask:0xf bound_ctrl:1
	v_add_f32_dpp v126, v126, v126 quad_perm:[2,3,0,1] row_mask:0xf bank_mask:0xf bound_ctrl:1
	s_nop 0
	v_add_f32_dpp v127, v127, v127 quad_perm:[2,3,0,1] row_mask:0xf bank_mask:0xf bound_ctrl:1
	v_add_f32_dpp v126, v126, v126 row_half_mirror row_mask:0xf bank_mask:0xf bound_ctrl:1
	s_nop 0
	v_add_f32_dpp v127, v127, v127 row_half_mirror row_mask:0xf bank_mask:0xf bound_ctrl:1
	v_add_f32_dpp v126, v126, v126 row_mirror row_mask:0xf bank_mask:0xf bound_ctrl:1
	s_nop 0
	v_add_f32_dpp v127, v127, v127 row_mirror row_mask:0xf bank_mask:0xf bound_ctrl:1
	v_fmac_f32_e32 v127, v126, v154
	v_fmac_f32_e32 v127, v102, v155
	v_pk_mul_f32 v[28:29], v[28:29], v[126:127] op_sel_hi:[1,0]
	ds_write_b32 v112, v127 offset:50432
	v_pk_fma_f32 v[28:29], v[134:135], v[102:103], v[28:29] op_sel_hi:[1,0,1]
	v_pk_fma_f32 v[150:151], v[20:21], v[150:151], v[28:29]
	v_pk_mul_f32 v[20:21], v[30:31], v[126:127] op_sel_hi:[1,0]
	v_pk_fma_f32 v[20:21], v[136:137], v[102:103], v[20:21] op_sel_hi:[1,0,1]
	v_pk_fma_f32 v[152:153], v[22:23], v[152:153], v[20:21]
	ds_read_b128 v[20:23], v105 offset:34688
	ds_read_b128 v[28:31], v105 offset:38784
	ds_read_b128 v[126:129], v105 offset:26496
	ds_read_b128 v[134:137], v105 offset:42880
	ds_read_b128 v[142:145], v105 offset:30592
	ds_read_b32 v102, v106 offset:46976
	ds_read_b64 v[154:155], v157 offset:49336
	s_waitcnt lgkmcnt(7)
	v_pk_mul_f32 v[132:133], v[132:133], v[152:153]
	v_pk_fma_f32 v[130:131], v[130:131], v[150:151], v[132:133]
	v_pk_mul_f32 v[132:133], v[148:149], v[152:153]
	v_add_f32_e32 v130, v130, v131
	v_pk_fma_f32 v[132:133], v[146:147], v[150:151], v[132:133]
	v_add_f32_e32 v131, v132, v133
	v_add_f32_dpp v130, v130, v130 quad_perm:[1,0,3,2] row_mask:0xf bank_mask:0xf bound_ctrl:1
	s_nop 0
	v_add_f32_dpp v131, v131, v131 quad_perm:[1,0,3,2] row_mask:0xf bank_mask:0xf bound_ctrl:1
	v_add_f32_dpp v130, v130, v130 quad_perm:[2,3,0,1] row_mask:0xf bank_mask:0xf bound_ctrl:1
	s_nop 0
	v_add_f32_dpp v131, v131, v131 quad_perm:[2,3,0,1] row_mask:0xf bank_mask:0xf bound_ctrl:1
	v_add_f32_dpp v130, v130, v130 row_half_mirror row_mask:0xf bank_mask:0xf bound_ctrl:1
	s_nop 0
	v_add_f32_dpp v131, v131, v131 row_half_mirror row_mask:0xf bank_mask:0xf bound_ctrl:1
	v_add_f32_dpp v130, v130, v130 row_mirror row_mask:0xf bank_mask:0xf bound_ctrl:1
	s_nop 0
	v_add_f32_dpp v131, v131, v131 row_mirror row_mask:0xf bank_mask:0xf bound_ctrl:1
	v_fmac_f32_e32 v131, v130, v168
	v_fmac_f32_e32 v131, v96, v169
	v_pk_mul_f32 v[98:99], v[98:99], v[130:131] op_sel_hi:[1,0]
	ds_write_b32 v113, v131 offset:50432
	v_pk_fma_f32 v[98:99], v[138:139], v[96:97], v[98:99] op_sel_hi:[1,0,1]
	v_pk_fma_f32 v[150:151], v[24:25], v[150:151], v[98:99]
	v_pk_mul_f32 v[24:25], v[100:101], v[130:131] op_sel_hi:[1,0]
	v_pk_fma_f32 v[24:25], v[140:141], v[96:97], v[24:25] op_sel_hi:[1,0,1]
	v_pk_fma_f32 v[152:153], v[26:27], v[152:153], v[24:25]
	ds_read_b128 v[24:27], v105 offset:34944
	ds_read_b128 v[98:101], v105 offset:39040
	ds_read_b128 v[130:133], v105 offset:26752
	ds_read_b128 v[138:141], v105 offset:43136
	ds_read_b128 v[146:149], v105 offset:30848
	ds_read_b32 v96, v106 offset:47232
	s_waitcnt lgkmcnt(6)
; DI float row16_sum(float v) { v += dppf(v, 0); v += dppf(v, 1); v += dppf(v, 2); v += dppf(v, 3); return v; }
; DI void rwkv_scan(CP p, const Ptrs& w, int l, int item, float* sm) {
;     ...
;     RStep cur = lds_step(bf, 0);
; #pragma unroll
;     for (int j = 0; j < 16; ++j) {
;       RStep nxt = cur;
;       if (j + 1 < 16) nxt = lds_step(bf, j + 1);
;       f2v sa2 = SA * cur.a4.xy + SB * cur.a4.zw;
;       f2v yp2 = SA * cur.wr4.xy + SB * cur.wr4.zw;
;       float sa = sa2.x + sa2.y, yp = yp2.x + yp2.y;
;       sa = row16_sum(sa); yp = row16_sum(yp);
;       float y = yp + sa * cur.sc.x + cur.vv * cur.sc.y;
;       SA = SA * cur.w4.xy + (sa * cur.b4.xy + cur.vv * cur.k4.xy);
;       SB = SB * cur.w4.zw + (sa * cur.b4.zw + cur.vv * cur.k4.zw);
;       sy[(kg == 0 ? j * 16 : 0) + ysel - (c & 1) * 0] = y;
;       cur = nxt;
	v_pk_mul_f32 v[128:129], v[128:129], v[152:153]
	ds_read_b64 v[168:169], v157 offset:49344
	v_pk_fma_f32 v[126:127], v[126:127], v[150:151], v[128:129]
	v_pk_mul_f32 v[128:129], v[144:145], v[152:153]
	v_add_f32_e32 v126, v126, v127
	v_pk_fma_f32 v[128:129], v[142:143], v[150:151], v[128:129]
	v_add_f32_e32 v127, v128, v129
	v_add_f32_dpp v126, v126, v126 quad_perm:[1,0,3,2] row_mask:0xf bank_mask:0xf bound_ctrl:1
	s_nop 0
	v_add_f32_dpp v127, v127, v127 quad_perm:[1,0,3,2] row_mask:0xf bank_mask:0xf bound_ctrl:1
	v_add_f32_dpp v126, v126, v126 quad_perm:[2,3,0,1] row_mask:0xf bank_mask:0xf bound_ctrl:1
	s_nop 0
	v_add_f32_dpp v127, v127, v127 quad_perm:[2,3,0,1] row_mask:0xf bank_mask:0xf bound_ctrl:1
	v_add_f32_dpp v126, v126, v126 row_half_mirror row_mask:0xf bank_mask:0xf bound_ctrl:1
	s_nop 0
	v_add_f32_dpp v127, v127, v127 row_half_mirror row_mask:0xf bank_mask:0xf bound_ctrl:1
	v_add_f32_dpp v126, v126, v126 row_mirror row_mask:0xf bank_mask:0xf bound_ctrl:1
	s_nop 0
	v_add_f32_dpp v127, v127, v127 row_mirror row_mask:0xf bank_mask:0xf bound_ctrl:1
	v_fmac_f32_e32 v127, v126, v154
	v_fmac_f32_e32 v127, v102, v155
	v_pk_mul_f32 v[28:29], v[28:29], v[126:127] op_sel_hi:[1,0]
	ds_write_b32 v114, v127 offset:50432
	v_pk_fma_f32 v[28:29], v[134:135], v[102:103], v[28:29] op_sel_hi:[1,0,1]
	v_pk_fma_f32 v[150:151], v[20:21], v[150:151], v[28:29]
	v_pk_mul_f32 v[20:21], v[30:31], v[126:127] op_sel_hi:[1,0]
	v_pk_fma_f32 v[20:21], v[136:137], v[102:103], v[20:21] op_sel_hi:[1,0,1]
	v_pk_fma_f32 v[152:153], v[22:23], v[152:153], v[20:21]
	ds_read_b128 v[20:23], v105 offset:35200
	ds_read_b128 v[28:31], v105 offset:39296
	ds_read_b128 v[126:129], v105 offset:27008
	ds_read_b128 v[134:137], v105 offset:43392
	ds_read_b128 v[142:145], v105 offset:31104
	ds_read_b32 v102, v106 offset:47488
	ds_read_b64 v[154:155], v157 offset:49352
	s_waitcnt lgkmcnt(7)
	v_pk_mul_f32 v[132:133], v[132:133], v[152:153]
	v_pk_fma_f32 v[130:131], v[130:131], v[150:151], v[132:133]
	v_pk_mul_f32 v[132:133], v[148:149], v[152:153]
	v_add_f32_e32 v130, v130, v131
	v_pk_fma_f32 v[132:133], v[146:147], v[150:151], v[132:133]
	v_add_f32_e32 v131, v132, v133
	v_add_f32_dpp v130, v130, v130 quad_perm:[1,0,3,2] row_mask:0xf bank_mask:0xf bound_ctrl:1
	s_nop 0
	v_add_f32_dpp v131, v131, v131 quad_perm:[1,0,3,2] row_mask:0xf bank_mask:0xf bound_ctrl:1
	v_add_f32_dpp v130, v130, v130 quad_perm:[2,3,0,1] row_mask:0xf bank_mask:0xf bound_ctrl:1
	s_nop 0
	v_add_f32_dpp v131, v131, v131 quad_perm:[2,3,0,1] row_mask:0xf bank_mask:0xf bound_ctrl:1
	v_add_f32_dpp v130, v130, v130 row_half_mirror row_mask:0xf bank_mask:0xf bound_ctrl:1
	s_nop 0
	v_add_f32_dpp v131, v131, v131 row_half_mirror row_mask:0xf bank_mask:0xf bound_ctrl:1
	v_add_f32_dpp v130, v130, v130 row_mirror row_mask:0xf bank_mask:0xf bound_ctrl:1
	s_nop 0
	v_add_f32_dpp v131, v131, v131 row_mirror row_mask:0xf bank_mask:0xf bound_ctrl:1
	v_fmac_f32_e32 v131, v130, v168
	v_fmac_f32_e32 v131, v96, v169
	v_pk_mul_f32 v[98:99], v[98:99], v[130:131] op_sel_hi:[1,0]
	ds_write_b32 v115, v131 offset:50432
	v_pk_fma_f32 v[98:99], v[138:139], v[96:97], v[98:99] op_sel_hi:[1,0,1]
	v_pk_fma_f32 v[150:151], v[24:25], v[150:151], v[98:99]
	v_pk_mul_f32 v[24:25], v[100:101], v[130:131] op_sel_hi:[1,0]
	v_pk_fma_f32 v[24:25], v[140:141], v[96:97], v[24:25] op_sel_hi:[1,0,1]
	v_pk_fma_f32 v[152:153], v[26:27], v[152:153], v[24:25]
	ds_read_b128 v[24:27], v105 offset:35456
	ds_read_b128 v[98:101], v105 offset:39552
	ds_read_b128 v[130:133], v105 offset:27264
	ds_read_b128 v[138:141], v105 offset:43648
	ds_read_b128 v[146:149], v105 offset:31360
	ds_read_b32 v96, v106 offset:47744
	s_waitcnt lgkmcnt(6)
	v_pk_mul_f32 v[128:129], v[128:129], v[152:153]
	ds_read_b64 v[168:169], v157 offset:49360
	v_pk_fma_f32 v[126:127], v[126:127], v[150:151], v[128:129]
	v_pk_mul_f32 v[128:129], v[144:145], v[152:153]
	v_add_f32_e32 v126, v126, v127
	v_pk_fma_f32 v[128:129], v[142:143], v[150:151], v[128:129]
	v_add_f32_e32 v127, v128, v129
	v_add_f32_dpp v126, v126, v126 quad_perm:[1,0,3,2] row_mask:0xf bank_mask:0xf bound_ctrl:1
	s_nop 0
	v_add_f32_dpp v127, v127, v127 quad_perm:[1,0,3,2] row_mask:0xf bank_mask:0xf bound_ctrl:1
	v_add_f32_dpp v126, v126, v126 quad_perm:[2,3,0,1] row_mask:0xf bank_mask:0xf bound_ctrl:1
	s_nop 0
	v_add_f32_dpp v127, v127, v127 quad_perm:[2,3,0,1] row_mask:0xf bank_mask:0xf bound_ctrl:1
	v_add_f32_dpp v126, v126, v126 row_half_mirror row_mask:0xf bank_mask:0xf bound_ctrl:1
	s_nop 0
	v_add_f32_dpp v127, v127, v127 row_half_mirror row_mask:0xf bank_mask:0xf bound_ctrl:1
	v_add_f32_dpp v126, v126, v126 row_mirror row_mask:0xf bank_mask:0xf bound_ctrl:1
	s_nop 0
	v_add_f32_dpp v127, v127, v127 row_mirror row_mask:0xf bank_mask:0xf bound_ctrl:1
	v_fmac_f32_e32 v127, v126, v154
	v_fmac_f32_e32 v127, v102, v155
	v_pk_mul_f32 v[28:29], v[28:29], v[126:127] op_sel_hi:[1,0]
	ds_write_b32 v116, v127 offset:50432
	v_pk_fma_f32 v[28:29], v[134:135], v[102:103], v[28:29] op_sel_hi:[1,0,1]
	v_pk_fma_f32 v[150:151], v[20:21], v[150:151], v[28:29]
	v_pk_mul_f32 v[20:21], v[30:31], v[126:127] op_sel_hi:[1,0]
	v_pk_fma_f32 v[20:21], v[136:137], v[102:103], v[20:21] op_sel_hi:[1,0,1]
	v_pk_fma_f32 v[152:153], v[22:23], v[152:153], v[20:21]
	ds_read_b128 v[20:23], v105 offset:35712
	ds_read_b128 v[28:31], v105 offset:39808
	ds_read_b128 v[126:129], v105 offset:27520
	ds_read_b128 v[134:137], v105 offset:43904
	ds_read_b128 v[142:145], v105 offset:31616
	ds_read_b32 v102, v106 offset:48000
	ds_read_b64 v[154:155], v157 offset:49368
	s_waitcnt lgkmcnt(7)
; DI float row16_sum(float v) { v += dppf(v, 0); v += dppf(v, 1); v += dppf(v, 2); v += dppf(v, 3); return v; }
; DI void rwkv_scan(CP p, const Ptrs& w, int l, int item, float* sm) {
;     ...
;     RStep cur = lds_step(bf, 0);
; #pragma unroll
;     for (int j = 0; j < 16; ++j) {
;       RStep nxt = cur;
;       if (j + 1 < 16) nxt = lds_step(bf, j + 1);
;       f2v sa2 = SA * cur.a4.xy + SB * cur.a4.zw;
;       f2v yp2 = SA * cur.wr4.xy + SB * cur.wr4.zw;
;       float sa = sa2.x + sa2.y, yp = yp2.x + yp2.y;
;       sa = row16_sum(sa); yp = row16_sum(yp);
;       float y = yp + sa * cur.sc.x + cur.vv * cur.sc.y;
;       SA = SA * cur.w4.xy + (sa * cur.b4.xy + cur.vv * cur.k4.xy);
;       SB = SB * cur.w4.zw + (sa * cur.b4.zw + cur.vv * cur.k4.zw);
;       sy[(kg == 0 ? j * 16 : 0) + ysel - (c & 1) * 0] = y;
;       cur = nxt;
	v_pk_mul_f32 v[132:133], v[132:133], v[152:153]
	v_pk_fma_f32 v[130:131], v[130:131], v[150:151], v[132:133]
	v_pk_mul_f32 v[132:133], v[148:149], v[152:153]
	v_add_f32_e32 v130, v130, v131
	v_pk_fma_f32 v[132:133], v[146:147], v[150:151], v[132:133]
	v_add_f32_e32 v131, v132, v133
	v_add_f32_dpp v130, v130, v130 quad_perm:[1,0,3,2] row_mask:0xf bank_mask:0xf bound_ctrl:1
	s_nop 0
	v_add_f32_dpp v131, v131, v131 quad_perm:[1,0,3,2] row_mask:0xf bank_mask:0xf bound_ctrl:1
	v_add_f32_dpp v130, v130, v130 quad_perm:[2,3,0,1] row_mask:0xf bank_mask:0xf bound_ctrl:1
	s_nop 0
	v_add_f32_dpp v131, v131, v131 quad_perm:[2,3,0,1] row_mask:0xf bank_mask:0xf bound_ctrl:1
	v_add_f32_dpp v130, v130, v130 row_half_mirror row_mask:0xf bank_mask:0xf bound_ctrl:1
	s_nop 0
	v_add_f32_dpp v131, v131, v131 row_half_mirror row_mask:0xf bank_mask:0xf bound_ctrl:1
	v_add_f32_dpp v130, v130, v130 row_mirror row_mask:0xf bank_mask:0xf bound_ctrl:1
	s_nop 0
	v_add_f32_dpp v131, v131, v131 row_mirror row_mask:0xf bank_mask:0xf bound_ctrl:1
	v_fmac_f32_e32 v131, v130, v168
	v_fmac_f32_e32 v131, v96, v169
	v_pk_mul_f32 v[98:99], v[98:99], v[130:131] op_sel_hi:[1,0]
	ds_write_b32 v117, v131 offset:50432
	v_pk_fma_f32 v[98:99], v[138:139], v[96:97], v[98:99] op_sel_hi:[1,0,1]
	v_pk_fma_f32 v[150:151], v[24:25], v[150:151], v[98:99]
	v_pk_mul_f32 v[24:25], v[100:101], v[130:131] op_sel_hi:[1,0]
	v_pk_fma_f32 v[24:25], v[140:141], v[96:97], v[24:25] op_sel_hi:[1,0,1]
	v_pk_fma_f32 v[152:153], v[26:27], v[152:153], v[24:25]
	ds_read_b128 v[24:27], v105 offset:35968
	ds_read_b128 v[98:101], v105 offset:40064
	ds_read_b128 v[130:133], v105 offset:27776
	ds_read_b128 v[138:141], v105 offset:44160
	ds_read_b128 v[146:149], v105 offset:31872
	ds_read_b32 v96, v106 offset:48256
	s_waitcnt lgkmcnt(6)
	v_pk_mul_f32 v[128:129], v[128:129], v[152:153]
	ds_read_b64 v[168:169], v157 offset:49376
	v_pk_fma_f32 v[126:127], v[126:127], v[150:151], v[128:129]
	v_pk_mul_f32 v[128:129], v[144:145], v[152:153]
	v_add_f32_e32 v126, v126, v127
	v_pk_fma_f32 v[128:129], v[142:143], v[150:151], v[128:129]
	v_add_f32_e32 v127, v128, v129
	v_add_f32_dpp v126, v126, v126 quad_perm:[1,0,3,2] row_mask:0xf bank_mask:0xf bound_ctrl:1
	s_nop 0
	v_add_f32_dpp v127, v127, v127 quad_perm:[1,0,3,2] row_mask:0xf bank_mask:0xf bound_ctrl:1
	v_add_f32_dpp v126, v126, v126 quad_perm:[2,3,0,1] row_mask:0xf bank_mask:0xf bound_ctrl:1
	s_nop 0
	v_add_f32_dpp v127, v127, v127 quad_perm:[2,3,0,1] row_mask:0xf bank_mask:0xf bound_ctrl:1
	v_add_f32_dpp v126, v126, v126 row_half_mirror row_mask:0xf bank_mask:0xf bound_ctrl:1
	s_nop 0
	v_add_f32_dpp v127, v127, v127 row_half_mirror row_mask:0xf bank_mask:0xf bound_ctrl:1
	v_add_f32_dpp v126, v126, v126 row_mirror row_mask:0xf bank_mask:0xf bound_ctrl:1
	s_nop 0
	v_add_f32_dpp v127, v127, v127 row_mirror row_mask:0xf bank_mask:0xf bound_ctrl:1
	v_fmac_f32_e32 v127, v126, v154
	v_fmac_f32_e32 v127, v102, v155
	v_pk_mul_f32 v[28:29], v[28:29], v[126:127] op_sel_hi:[1,0]
	ds_write_b32 v118, v127 offset:50432
	v_pk_fma_f32 v[28:29], v[134:135], v[102:103], v[28:29] op_sel_hi:[1,0,1]
	v_pk_fma_f32 v[150:151], v[20:21], v[150:151], v[28:29]
	v_pk_mul_f32 v[20:21], v[30:31], v[126:127] op_sel_hi:[1,0]
	v_pk_fma_f32 v[20:21], v[136:137], v[102:103], v[20:21] op_sel_hi:[1,0,1]
	v_pk_fma_f32 v[152:153], v[22:23], v[152:153], v[20:21]
	ds_read_b128 v[20:23], v105 offset:36224
	ds_read_b128 v[28:31], v105 offset:40320
	ds_read_b128 v[126:129], v105 offset:28032
	ds_read_b128 v[134:137], v105 offset:44416
	ds_read_b128 v[142:145], v105 offset:32128
	ds_read_b32 v102, v106 offset:48512
	ds_read_b64 v[154:155], v157 offset:49384
	s_waitcnt lgkmcnt(7)
	v_pk_mul_f32 v[132:133], v[132:133], v[152:153]
	v_pk_fma_f32 v[130:131], v[130:131], v[150:151], v[132:133]
	v_pk_mul_f32 v[132:133], v[148:149], v[152:153]
	v_add_f32_e32 v130, v130, v131
	v_pk_fma_f32 v[132:133], v[146:147], v[150:151], v[132:133]
	v_add_f32_e32 v131, v132, v133
	v_add_f32_dpp v130, v130, v130 quad_perm:[1,0,3,2] row_mask:0xf bank_mask:0xf bound_ctrl:1
	s_nop 0
	v_add_f32_dpp v131, v131, v131 quad_perm:[1,0,3,2] row_mask:0xf bank_mask:0xf bound_ctrl:1
	v_add_f32_dpp v130, v130, v130 quad_perm:[2,3,0,1] row_mask:0xf bank_mask:0xf bound_ctrl:1
	s_nop 0
	v_add_f32_dpp v131, v131, v131 quad_perm:[2,3,0,1] row_mask:0xf bank_mask:0xf bound_ctrl:1
	v_add_f32_dpp v130, v130, v130 row_half_mirror row_mask:0xf bank_mask:0xf bound_ctrl:1
	s_nop 0
	v_add_f32_dpp v131, v131, v131 row_half_mirror row_mask:0xf bank_mask:0xf bound_ctrl:1
	v_add_f32_dpp v130, v130, v130 row_mirror row_mask:0xf bank_mask:0xf bound_ctrl:1
	s_nop 0
	v_add_f32_dpp v131, v131, v131 row_mirror row_mask:0xf bank_mask:0xf bound_ctrl:1
	v_fmac_f32_e32 v131, v130, v168
	v_fmac_f32_e32 v131, v96, v169
	v_pk_mul_f32 v[98:99], v[98:99], v[130:131] op_sel_hi:[1,0]
	ds_write_b32 v119, v131 offset:50432
	v_pk_fma_f32 v[98:99], v[138:139], v[96:97], v[98:99] op_sel_hi:[1,0,1]
	v_pk_fma_f32 v[24:25], v[24:25], v[150:151], v[98:99]
	v_pk_mul_f32 v[98:99], v[100:101], v[130:131] op_sel_hi:[1,0]
	v_pk_fma_f32 v[98:99], v[140:141], v[96:97], v[98:99] op_sel_hi:[1,0,1]
	v_pk_fma_f32 v[26:27], v[26:27], v[152:153], v[98:99]
	ds_read_b128 v[98:101], v105 offset:36480
	ds_read_b128 v[130:133], v105 offset:40576
	ds_read_b128 v[138:141], v105 offset:28288
	ds_read_b128 v[146:149], v105 offset:44672
	ds_read_b128 v[150:153], v105 offset:32384
	ds_read_b32 v156, v106 offset:48768
	s_waitcnt lgkmcnt(6)
; DI float row16_sum(float v) { v += dppf(v, 0); v += dppf(v, 1); v += dppf(v, 2); v += dppf(v, 3); return v; }
; DI void rwkv_scan(CP p, const Ptrs& w, int l, int item, float* sm) {
;     ...
;     RStep cur = lds_step(bf, 0);
; #pragma unroll
;     for (int j = 0; j < 16; ++j) {
;       RStep nxt = cur;
;       if (j + 1 < 16) nxt = lds_step(bf, j + 1);
;       f2v sa2 = SA * cur.a4.xy + SB * cur.a4.zw;
;       f2v yp2 = SA * cur.wr4.xy + SB * cur.wr4.zw;
;       float sa = sa2.x + sa2.y, yp = yp2.x + yp2.y;
;       sa = row16_sum(sa); yp = row16_sum(yp);
;       float y = yp + sa * cur.sc.x + cur.vv * cur.sc.y;
;       SA = SA * cur.w4.xy + (sa * cur.b4.xy + cur.vv * cur.k4.xy);
;       SB = SB * cur.w4.zw + (sa * cur.b4.zw + cur.vv * cur.k4.zw);
;       sy[(kg == 0 ? j * 16 : 0) + ysel - (c & 1) * 0] = y;
;       cur = nxt;
	v_pk_mul_f32 v[128:129], v[128:129], v[26:27]
	ds_read_b64 v[168:169], v157 offset:49392
	v_pk_fma_f32 v[126:127], v[126:127], v[24:25], v[128:129]
	v_pk_mul_f32 v[128:129], v[144:145], v[26:27]
	v_add_f32_e32 v96, v126, v127
	v_pk_fma_f32 v[128:129], v[142:143], v[24:25], v[128:129]
	v_add_f32_e32 v126, v128, v129
	v_add_f32_dpp v96, v96, v96 quad_perm:[1,0,3,2] row_mask:0xf bank_mask:0xf bound_ctrl:1
	s_nop 0
	v_add_f32_dpp v126, v126, v126 quad_perm:[1,0,3,2] row_mask:0xf bank_mask:0xf bound_ctrl:1
	v_add_f32_dpp v96, v96, v96 quad_perm:[2,3,0,1] row_mask:0xf bank_mask:0xf bound_ctrl:1
	s_nop 0
	v_add_f32_dpp v126, v126, v126 quad_perm:[2,3,0,1] row_mask:0xf bank_mask:0xf bound_ctrl:1
	v_add_f32_dpp v96, v96, v96 row_half_mirror row_mask:0xf bank_mask:0xf bound_ctrl:1
	s_nop 0
	v_add_f32_dpp v126, v126, v126 row_half_mirror row_mask:0xf bank_mask:0xf bound_ctrl:1
	v_add_f32_dpp v96, v96, v96 row_mirror row_mask:0xf bank_mask:0xf bound_ctrl:1
	v_pk_mul_f32 v[28:29], v[28:29], v[96:97] op_sel_hi:[1,0]
	v_add_f32_dpp v126, v126, v126 row_mirror row_mask:0xf bank_mask:0xf bound_ctrl:1
	v_pk_fma_f32 v[28:29], v[134:135], v[102:103], v[28:29] op_sel_hi:[1,0,1]
	v_fmac_f32_e32 v126, v96, v154
	v_pk_fma_f32 v[142:143], v[20:21], v[24:25], v[28:29]
	v_pk_mul_f32 v[20:21], v[30:31], v[96:97] op_sel_hi:[1,0]
	v_fmac_f32_e32 v126, v102, v155
	v_pk_fma_f32 v[20:21], v[136:137], v[102:103], v[20:21] op_sel_hi:[1,0,1]
	ds_write_b32 v120, v126 offset:50432
	v_pk_fma_f32 v[144:145], v[22:23], v[26:27], v[20:21]
	ds_read_b128 v[20:23], v105 offset:36736
	ds_read_b128 v[28:31], v105 offset:40832
	ds_read_b128 v[126:129], v105 offset:28544
	ds_read_b128 v[24:27], v105 offset:44928
	ds_read_b128 v[134:137], v105 offset:32640
	ds_read_b32 v96, v106 offset:49024
	ds_read_b64 v[154:155], v157 offset:49400
	s_waitcnt lgkmcnt(8)
	v_pk_mul_f32 v[140:141], v[140:141], v[144:145]
	v_pk_fma_f32 v[138:139], v[138:139], v[142:143], v[140:141]
	v_pk_mul_f32 v[140:141], v[152:153], v[144:145]
	v_add_f32_e32 v102, v138, v139
	v_pk_fma_f32 v[140:141], v[150:151], v[142:143], v[140:141]
	v_add_f32_e32 v138, v140, v141
	v_add_f32_dpp v102, v102, v102 quad_perm:[1,0,3,2] row_mask:0xf bank_mask:0xf bound_ctrl:1
	s_waitcnt vmcnt(20)
	v_and_b32_e32 v139, 0xffff0000, v80
	v_add_f32_dpp v102, v102, v102 quad_perm:[2,3,0,1] row_mask:0xf bank_mask:0xf bound_ctrl:1
	v_add_f32_dpp v138, v138, v138 quad_perm:[1,0,3,2] row_mask:0xf bank_mask:0xf bound_ctrl:1
	v_and_b32_e32 v141, 0xffff0000, v79
	v_add_f32_dpp v102, v102, v102 row_half_mirror row_mask:0xf bank_mask:0xf bound_ctrl:1
	v_add_f32_dpp v138, v138, v138 quad_perm:[2,3,0,1] row_mask:0xf bank_mask:0xf bound_ctrl:1
	v_lshlrev_b32_e32 v140, 16, v81
	v_add_f32_dpp v102, v102, v102 row_mirror row_mask:0xf bank_mask:0xf bound_ctrl:1
	v_pk_mul_f32 v[130:131], v[130:131], v[102:103] op_sel_hi:[1,0]
	v_add_f32_dpp v138, v138, v138 row_half_mirror row_mask:0xf bank_mask:0xf bound_ctrl:1
	s_waitcnt lgkmcnt(9)
	v_pk_fma_f32 v[130:131], v[146:147], v[156:157], v[130:131] op_sel_hi:[1,0,1]
	s_nop 0
	v_pk_fma_f32 v[98:99], v[98:99], v[142:143], v[130:131]
	v_pk_mul_f32 v[130:131], v[132:133], v[102:103] op_sel_hi:[1,0]
	v_add_f32_dpp v138, v138, v138 row_mirror row_mask:0xf bank_mask:0xf bound_ctrl:1
	v_pk_fma_f32 v[130:131], v[148:149], v[156:157], v[130:131] op_sel_hi:[1,0,1]
	s_waitcnt lgkmcnt(8)
	v_fmac_f32_e32 v138, v102, v168
	v_pk_fma_f32 v[100:101], v[100:101], v[144:145], v[130:131]
	v_fmac_f32_e32 v138, v156, v169
	s_waitcnt lgkmcnt(4)
	v_pk_mul_f32 v[128:129], v[128:129], v[100:101]
	ds_write_b32 v121, v138 offset:50432
	v_pk_fma_f32 v[126:127], v[126:127], v[98:99], v[128:129]
	s_waitcnt lgkmcnt(3)
; DI float row16_sum(float v) { v += dppf(v, 0); v += dppf(v, 1); v += dppf(v, 2); v += dppf(v, 3); return v; }
; DI void rwkv_scan(CP p, const Ptrs& w, int l, int item, float* sm) {
;     ...
;   auto stage = [&](const RPre& P, float* bufp) {
;     float rc[4], rp[4], rn[4], kc[4], kp[4], kn[4], vc[4], vp[4], vn[4], wd4[4], ad4[4];
;     up4(P.pq[0][0], rc); up4(P.pq[0][1], rp); up4(P.pq[0][2], rn);
;     up4(P.pq[1][0], kc); up4(P.pq[1][1], kp); up4(P.pq[1][2], kn);
;     up4(P.pq[2][0], vc); up4(P.pq[2][1], vp); up4(P.pq[2][2], vn);
;     up4(P.pwd, wd4); up4(P.pad_, ad4);
;     float o0[4], o1[4], o2[4], o3[4], o4[4], o5[4];
; #pragma unroll
;     for (int j = 0; j < 4; ++j) {
;       float r_s = rc[j] + ((P.pmk[0] * rp[j] + P.pmk[1] * rn[j]) - rc[j]) * mu_r[j];
;       float k_s = kc[j] + ((P.pmk[0] * kp[j] + P.pmk[1] * kn[j]) - kc[j]) * mu_k[j];
;       float v_s = vc[j] + ((P.pmk[0] * vp[j] + P.pmk[1] * vn[j]) - vc[j]) * mu_v[j];
;       float kk = k_s * kk_c[j] * P.psc[0];
;       float a = ad4[j], wv = 1.f - wd4[j];
;       o0[j] = -kk; o1[j] = wv * r_s; o2[j] = wv; o3[j] = kk * a; o4[j] = k_s * (1.f + (a - 1.f) * ka_c[j]); o5[j] = v_s;
;     }
;     float* d = bufp + sj * 64 + skq;
;     *(float4*)(d + 0 * 1024) = make_float4(o0[0], o0[1], o0[2], o0[3]);
;     *(float4*)(d + 1 * 1024) = make_float4(o1[0], o1[1], o1[2], o1[3]);
;     *(float4*)(d + 2 * 1024) = make_float4(o2[0], o2[1], o2[2], o2[3]);
;     *(float4*)(d + 3 * 1024) = make_float4(o3[0], o3[1], o3[2], o3[3]);
;     *(float4*)(d + 4 * 1024) = make_float4(o4[0], o4[1], o4[2], o4[3]);
;     *(float4*)(d + 5 * 1024) = make_float4(o5[0], o5[1], o5[2], o5[3]);
;     if (skq == 0) *(float2*)(bufp + 6 * 1024 + sj * 2) = make_float2(P.psc[1], P.psc[2]);
;     ...
;       f2v sa2 = SA * cur.a4.xy + SB * cur.a4.zw;
;       f2v yp2 = SA * cur.wr4.xy + SB * cur.wr4.zw;
;       float sa = sa2.x + sa2.y, yp = yp2.x + yp2.y;
;       sa = row16_sum(sa); yp = row16_sum(yp);
;       float y = yp + sa * cur.sc.x + cur.vv * cur.sc.y;
;       SA = SA * cur.w4.xy + (sa * cur.b4.xy + cur.vv * cur.k4.xy);
;       SB = SB * cur.w4.zw + (sa * cur.b4.zw + cur.vv * cur.k4.zw);
;       sy[(kg == 0 ? j * 16 : 0) + ysel - (c & 1) * 0] = y;
	v_pk_mul_f32 v[128:129], v[136:137], v[100:101]
	v_lshlrev_b32_e32 v132, 16, v85
	v_pk_fma_f32 v[128:129], v[134:135], v[98:99], v[128:129]
	v_and_b32_e32 v133, 0xffff0000, v85
	v_and_b32_e32 v85, 0xffff0000, v78
	v_lshlrev_b32_e32 v138, 16, v78
	v_lshlrev_b32_e32 v78, 16, v79
	v_and_b32_e32 v79, 0xffff0000, v81
	v_add_f32_e32 v102, v126, v127
	v_add_f32_e32 v126, v128, v129
	v_lshlrev_b32_e32 v130, 16, v84
	v_and_b32_e32 v131, 0xffff0000, v84
	v_lshlrev_b32_e32 v84, 16, v80
	v_pk_mul_f32 v[138:139], v[94:95], v[138:139] op_sel:[1,0] op_sel_hi:[0,1]
	v_pk_mul_f32 v[78:79], v[94:95], v[78:79] op_sel:[1,0] op_sel_hi:[0,1]
	v_add_f32_dpp v102, v102, v102 quad_perm:[1,0,3,2] row_mask:0xf bank_mask:0xf bound_ctrl:1
	v_add_f32_dpp v126, v126, v126 quad_perm:[1,0,3,2] row_mask:0xf bank_mask:0xf bound_ctrl:1
	v_lshlrev_b32_e32 v128, 16, v86
	v_and_b32_e32 v129, 0xffff0000, v86
	v_lshlrev_b32_e32 v86, 16, v87
	v_and_b32_e32 v87, 0xffff0000, v87
	v_pk_fma_f32 v[84:85], v[94:95], v[84:85], v[138:139]
	v_pk_fma_f32 v[78:79], v[94:95], v[140:141], v[78:79]
	v_add_f32_dpp v102, v102, v102 quad_perm:[2,3,0,1] row_mask:0xf bank_mask:0xf bound_ctrl:1
	v_add_f32_dpp v126, v126, v126 quad_perm:[2,3,0,1] row_mask:0xf bank_mask:0xf bound_ctrl:1
	v_pk_add_f32 v[84:85], v[84:85], v[128:129] neg_lo:[0,1] neg_hi:[0,1]
	v_pk_add_f32 v[78:79], v[78:79], v[86:87] neg_lo:[0,1] neg_hi:[0,1]
	v_add_f32_dpp v102, v102, v102 row_half_mirror row_mask:0xf bank_mask:0xf bound_ctrl:1
	v_add_f32_dpp v126, v126, v126 row_half_mirror row_mask:0xf bank_mask:0xf bound_ctrl:1
	v_pk_fma_f32 v[128:129], v[8:9], v[84:85], v[128:129]
	v_pk_fma_f32 v[140:141], v[10:11], v[78:79], v[86:87]
	v_add_f32_dpp v102, v102, v102 row_mirror row_mask:0xf bank_mask:0xf bound_ctrl:1
	v_add_f32_dpp v126, v126, v126 row_mirror row_mask:0xf bank_mask:0xf bound_ctrl:1
	v_pk_mul_f32 v[84:85], v[12:13], v[128:129]
	v_pk_mul_f32 v[78:79], v[14:15], v[140:141]
	s_waitcnt lgkmcnt(1)
	v_fmac_f32_e32 v126, v102, v154
	s_waitcnt vmcnt(16)
	v_pk_mul_f32 v[138:139], v[82:83], v[84:85] op_sel_hi:[0,1]
	v_pk_mul_f32 v[142:143], v[82:83], v[78:79] op_sel_hi:[0,1]
	v_fmac_f32_e32 v126, v96, v155
	v_xor_b32_e32 v85, 0x80000000, v139
	v_xor_b32_e32 v84, 0x80000000, v138
	v_xor_b32_e32 v87, 0x80000000, v143
	v_xor_b32_e32 v86, 0x80000000, v142
	ds_write_b32 v122, v126 offset:50432
	ds_write_b128 v103, v[84:87]
	v_lshlrev_b32_e32 v84, 16, v74
	v_and_b32_e32 v85, 0xffff0000, v76
	v_lshlrev_b32_e32 v80, 16, v76
	v_and_b32_e32 v81, 0xffff0000, v74
	v_pk_mul_f32 v[84:85], v[94:95], v[84:85] op_sel:[1,0] op_sel_hi:[0,1]
	v_lshlrev_b32_e32 v126, 16, v88
	v_and_b32_e32 v127, 0xffff0000, v88
	v_pk_fma_f32 v[80:81], v[94:95], v[80:81], v[84:85]
	v_lshlrev_b32_e32 v134, 16, v92
	v_and_b32_e32 v135, 0xffff0000, v92
	v_pk_add_f32 v[80:81], v[80:81], v[126:127] neg_lo:[0,1] neg_hi:[0,1]
	v_lshlrev_b32_e32 v92, 16, v93
	v_and_b32_e32 v93, 0xffff0000, v93
	v_pk_add_f32 v[78:79], v[134:135], 1.0 op_sel_hi:[1,0] neg_lo:[1,0] neg_hi:[1,0]
	v_pk_fma_f32 v[80:81], v[0:1], v[80:81], v[126:127]
	v_and_b32_e32 v87, 0xffff0000, v75
	v_pk_mul_f32 v[84:85], v[80:81], v[78:79]
	v_pk_add_f32 v[80:81], v[92:93], 1.0 op_sel_hi:[1,0] neg_lo:[1,0] neg_hi:[1,0]
	v_lshlrev_b32_e32 v93, 16, v75
	v_and_b32_e32 v75, s0, v75
	v_and_b32_e32 v74, 0xffff0000, v77
	v_pk_mov_b32 v[74:75], v[92:93], v[74:75] op_sel:[1,0]
	v_lshlrev_b32_e32 v86, 16, v77
	v_pk_mul_f32 v[74:75], v[94:95], v[74:75] op_sel:[1,0] op_sel_hi:[0,1]
	v_lshlrev_b32_e32 v88, 16, v89
	v_and_b32_e32 v89, 0xffff0000, v89
	v_pk_fma_f32 v[74:75], v[94:95], v[86:87], v[74:75]
	v_lshlrev_b32_e32 v136, 16, v90
	v_pk_add_f32 v[74:75], v[74:75], v[88:89] neg_lo:[0,1] neg_hi:[0,1]
	v_and_b32_e32 v137, 0xffff0000, v90
	v_lshlrev_b32_e32 v90, 16, v91
	v_and_b32_e32 v91, 0xffff0000, v91
	v_pk_fma_f32 v[74:75], v[2:3], v[74:75], v[88:89]
	v_pk_mul_f32 v[76:77], v[142:143], v[90:91]
	v_pk_mul_f32 v[86:87], v[74:75], v[80:81]
	v_pk_mul_f32 v[74:75], v[138:139], v[136:137]
	ds_write_b128 v103, v[84:87] offset:4096
	ds_write_b128 v103, v[78:81] offset:8192
	ds_write_b128 v103, v[74:77] offset:12288
	v_pk_add_f32 v[74:75], v[136:137], -1.0 op_sel_hi:[1,0]
	v_pk_add_f32 v[76:77], v[90:91], -1.0 op_sel_hi:[1,0]
	v_pk_fma_f32 v[74:75], v[16:17], v[74:75], 1.0 op_sel_hi:[1,1,0]
	v_pk_fma_f32 v[76:77], v[18:19], v[76:77], 1.0 op_sel_hi:[1,1,0]
	v_pk_mul_f32 v[74:75], v[128:129], v[74:75]
	v_pk_mul_f32 v[76:77], v[140:141], v[76:77]
	ds_write_b128 v103, v[74:77] offset:16384
	v_lshlrev_b32_e32 v76, 16, v70
	v_and_b32_e32 v77, 0xffff0000, v72
	v_lshlrev_b32_e32 v74, 16, v72
	v_and_b32_e32 v75, 0xffff0000, v70
	v_pk_mul_f32 v[76:77], v[94:95], v[76:77] op_sel:[1,0] op_sel_hi:[0,1]
	v_pk_fma_f32 v[74:75], v[94:95], v[74:75], v[76:77]
	v_and_b32_e32 v77, 0xffff0000, v71
	v_lshlrev_b32_e32 v79, 16, v71
	v_and_b32_e32 v71, s0, v71
	v_and_b32_e32 v70, 0xffff0000, v73
	v_pk_mov_b32 v[70:71], v[78:79], v[70:71] op_sel:[1,0]
	v_lshlrev_b32_e32 v76, 16, v73
	v_pk_mul_f32 v[70:71], v[94:95], v[70:71] op_sel:[1,0] op_sel_hi:[0,1]
	v_pk_fma_f32 v[70:71], v[94:95], v[76:77], v[70:71]
	v_pk_add_f32 v[74:75], v[74:75], v[130:131] neg_lo:[0,1] neg_hi:[0,1]
	v_pk_add_f32 v[70:71], v[70:71], v[132:133] neg_lo:[0,1] neg_hi:[0,1]
	v_pk_fma_f32 v[74:75], v[4:5], v[74:75], v[130:131]
	v_pk_fma_f32 v[76:77], v[6:7], v[70:71], v[132:133]
	ds_write_b128 v103, v[74:77] offset:20480
	s_and_saveexec_b64 s[4:5], s[40:41]
	s_cbranch_execz .LBB0_553
	s_waitcnt vmcnt(15)
	ds_write_b64 v104, v[68:69] offset:24576
	s_branch .LBB0_553
